# U pass: e/a lists handed to the V pass through LDS (no EG/AG round trip); su/sv gathers issued in place of the sweep's last redundant row prefetch
# speedup vs baseline: 1.0084x; 1.0031x over previous
; template <bool STORE>
; DI void peer_item(const Params& p, int item, char* smem) {
;     ...
; #pragma unroll 2
;     for (int k = 0; k < 128; k += 8) {
;       u32x4 uq[8];
;       const int emine = e_s[tl * 128 + k + (lane >> 3)];
;       const float gmine = g_s[tl * 128 + k + (lane >> 3)];
;       const float su = SU[emine], sv = SV[emine];
; #pragma unroll
;       for (int u = 0; u < 8; ++u) {
;         int e = e_s[tl * 128 + k + u];
;         uq[u] = *(const u32x4*)(U8 + (size_t)e * 1024 + lane * 16);
;       }
;       float part[8];
; #pragma unroll
;       for (int u = 0; u < 8; ++u) {
;         float d = 0.f;
; #pragma unroll
;         for (int i = 0; i < 4; ++i) {
;           f32x2_t lo = __builtin_amdgcn_cvt_pk_f32_fp8((int)uq[u][i], false);
;           f32x2_t hi = __builtin_amdgcn_cvt_pk_f32_fp8((int)uq[u][i], true);
;           d += xf[4 * i] * lo.x + xf[4 * i + 1] * lo.y + xf[4 * i + 2] * hi.x + xf[4 * i + 3] * hi.y;
;         }
;         part[u] = d;
;       }
;       float q4[4], r2[2], h;
.Lup_k:
	v_readlane_b32 s48, v130, s72
	v_readlane_b32 s49, v130, s73
	v_readlane_b32 s50, v130, s74
	v_readlane_b32 s51, v130, s75
	v_readlane_b32 s52, v130, s76
	v_readlane_b32 s53, v130, s77
	v_readlane_b32 s54, v130, s78
	v_readlane_b32 s55, v130, s79
	s_add_u32 s32, s0, s48
	s_addc_u32 s33, s1, 0
	s_add_u32 s34, s0, s49
	s_addc_u32 s35, s1, 0
	s_add_u32 s36, s0, s50
	s_addc_u32 s37, s1, 0
	s_add_u32 s38, s0, s51
	s_addc_u32 s39, s1, 0
	s_add_u32 s40, s0, s52
	s_addc_u32 s41, s1, 0
	s_add_u32 s42, s0, s53
	s_addc_u32 s43, s1, 0
	s_add_u32 s44, s0, s54
	s_addc_u32 s45, s1, 0
	s_add_u32 s46, s0, s55
	s_addc_u32 s47, s1, 0
	global_load_dwordx4 v[176:179], v234, s[32:33]
	global_load_dwordx4 v[180:183], v234, s[34:35]
	global_load_dwordx4 v[184:187], v234, s[36:37]
	global_load_dwordx4 v[188:191], v234, s[38:39]
	global_load_dwordx4 v[192:195], v234, s[40:41]
	global_load_dwordx4 v[196:199], v234, s[42:43]
	global_load_dwordx4 v[200:203], v234, s[44:45]
	global_load_dwordx4 v[204:207], v234, s[46:47]
	s_waitcnt vmcnt(8)
	v_cvt_pk_f32_fp8_e32 v[214:215], v144
	v_cvt_pk_f32_fp8_sdwa v[216:217], v144 src0_sel:WORD_1
	v_cvt_pk_f32_fp8_e32 v[218:219], v145
	v_cvt_pk_f32_fp8_sdwa v[220:221], v145 src0_sel:WORD_1
	v_pk_mul_f32 v[222:223], v[0:1], v[214:215]
	v_pk_mul_f32 v[224:225], v[2:3], v[216:217]
	v_cvt_pk_f32_fp8_e32 v[214:215], v146
	v_cvt_pk_f32_fp8_sdwa v[216:217], v146 src0_sel:WORD_1
	v_pk_fma_f32 v[222:223], v[4:5], v[218:219], v[222:223]
	v_pk_fma_f32 v[224:225], v[6:7], v[220:221], v[224:225]
	v_cvt_pk_f32_fp8_e32 v[218:219], v147
	v_cvt_pk_f32_fp8_sdwa v[220:221], v147 src0_sel:WORD_1
	v_pk_fma_f32 v[222:223], v[8:9], v[214:215], v[222:223]
	v_pk_fma_f32 v[224:225], v[10:11], v[216:217], v[224:225]
	v_pk_fma_f32 v[222:223], v[12:13], v[218:219], v[222:223]
	v_pk_fma_f32 v[224:225], v[14:15], v[220:221], v[224:225]
	v_pk_add_f32 v[222:223], v[222:223], v[224:225]
	s_nop 0
	v_add_f32_e32 v226, v222, v223
	v_cvt_pk_f32_fp8_e32 v[214:215], v148
	v_cvt_pk_f32_fp8_sdwa v[216:217], v148 src0_sel:WORD_1
	v_cvt_pk_f32_fp8_e32 v[218:219], v149
	v_cvt_pk_f32_fp8_sdwa v[220:221], v149 src0_sel:WORD_1
	v_pk_mul_f32 v[222:223], v[0:1], v[214:215]
	v_pk_mul_f32 v[224:225], v[2:3], v[216:217]
	v_cvt_pk_f32_fp8_e32 v[214:215], v150
	v_cvt_pk_f32_fp8_sdwa v[216:217], v150 src0_sel:WORD_1
	v_pk_fma_f32 v[222:223], v[4:5], v[218:219], v[222:223]
	v_pk_fma_f32 v[224:225], v[6:7], v[220:221], v[224:225]
	v_cvt_pk_f32_fp8_e32 v[218:219], v151
	v_cvt_pk_f32_fp8_sdwa v[220:221], v151 src0_sel:WORD_1
	v_pk_fma_f32 v[222:223], v[8:9], v[214:215], v[222:223]
	v_pk_fma_f32 v[224:225], v[10:11], v[216:217], v[224:225]
	v_pk_fma_f32 v[222:223], v[12:13], v[218:219], v[222:223]
	v_pk_fma_f32 v[224:225], v[14:15], v[220:221], v[224:225]
	v_pk_add_f32 v[222:223], v[222:223], v[224:225]
	s_nop 0
	v_add_f32_e32 v227, v222, v223
	v_cvt_pk_f32_fp8_e32 v[214:215], v152
	v_cvt_pk_f32_fp8_sdwa v[216:217], v152 src0_sel:WORD_1
	v_cvt_pk_f32_fp8_e32 v[218:219], v153
	v_cvt_pk_f32_fp8_sdwa v[220:221], v153 src0_sel:WORD_1
	v_pk_mul_f32 v[222:223], v[0:1], v[214:215]
	v_pk_mul_f32 v[224:225], v[2:3], v[216:217]
	v_cvt_pk_f32_fp8_e32 v[214:215], v154
	v_cvt_pk_f32_fp8_sdwa v[216:217], v154 src0_sel:WORD_1
	v_pk_fma_f32 v[222:223], v[4:5], v[218:219], v[222:223]
	v_pk_fma_f32 v[224:225], v[6:7], v[220:221], v[224:225]
	v_cvt_pk_f32_fp8_e32 v[218:219], v155
	v_cvt_pk_f32_fp8_sdwa v[220:221], v155 src0_sel:WORD_1
	v_pk_fma_f32 v[222:223], v[8:9], v[214:215], v[222:223]
	v_pk_fma_f32 v[224:225], v[10:11], v[216:217], v[224:225]
	v_pk_fma_f32 v[222:223], v[12:13], v[218:219], v[222:223]
	v_pk_fma_f32 v[224:225], v[14:15], v[220:221], v[224:225]
	v_pk_add_f32 v[222:223], v[222:223], v[224:225]
	s_nop 0
	v_add_f32_e32 v228, v222, v223
	v_cvt_pk_f32_fp8_e32 v[214:215], v156
	v_cvt_pk_f32_fp8_sdwa v[216:217], v156 src0_sel:WORD_1
	v_cvt_pk_f32_fp8_e32 v[218:219], v157
	v_cvt_pk_f32_fp8_sdwa v[220:221], v157 src0_sel:WORD_1
	v_pk_mul_f32 v[222:223], v[0:1], v[214:215]
	v_pk_mul_f32 v[224:225], v[2:3], v[216:217]
	v_cvt_pk_f32_fp8_e32 v[214:215], v158
	v_cvt_pk_f32_fp8_sdwa v[216:217], v158 src0_sel:WORD_1
	v_pk_fma_f32 v[222:223], v[4:5], v[218:219], v[222:223]
	v_pk_fma_f32 v[224:225], v[6:7], v[220:221], v[224:225]
	v_cvt_pk_f32_fp8_e32 v[218:219], v159
	v_cvt_pk_f32_fp8_sdwa v[220:221], v159 src0_sel:WORD_1
	v_pk_fma_f32 v[222:223], v[8:9], v[214:215], v[222:223]
	v_pk_fma_f32 v[224:225], v[10:11], v[216:217], v[224:225]
	v_pk_fma_f32 v[222:223], v[12:13], v[218:219], v[222:223]
	v_pk_fma_f32 v[224:225], v[14:15], v[220:221], v[224:225]
	v_pk_add_f32 v[222:223], v[222:223], v[224:225]
	s_nop 0
	v_add_f32_e32 v229, v222, v223
	v_cvt_pk_f32_fp8_e32 v[214:215], v160
	v_cvt_pk_f32_fp8_sdwa v[216:217], v160 src0_sel:WORD_1
	v_cvt_pk_f32_fp8_e32 v[218:219], v161
	v_cvt_pk_f32_fp8_sdwa v[220:221], v161 src0_sel:WORD_1
	v_pk_mul_f32 v[222:223], v[0:1], v[214:215]
	v_pk_mul_f32 v[224:225], v[2:3], v[216:217]
	v_cvt_pk_f32_fp8_e32 v[214:215], v162
	v_cvt_pk_f32_fp8_sdwa v[216:217], v162 src0_sel:WORD_1
	v_pk_fma_f32 v[222:223], v[4:5], v[218:219], v[222:223]
	v_pk_fma_f32 v[224:225], v[6:7], v[220:221], v[224:225]
	v_cvt_pk_f32_fp8_e32 v[218:219], v163
	v_cvt_pk_f32_fp8_sdwa v[220:221], v163 src0_sel:WORD_1
	v_pk_fma_f32 v[222:223], v[8:9], v[214:215], v[222:223]
	v_pk_fma_f32 v[224:225], v[10:11], v[216:217], v[224:225]
	v_pk_fma_f32 v[222:223], v[12:13], v[218:219], v[222:223]
	v_pk_fma_f32 v[224:225], v[14:15], v[220:221], v[224:225]
	v_pk_add_f32 v[222:223], v[222:223], v[224:225]
	s_nop 0
	v_add_f32_e32 v230, v222, v223
	v_cvt_pk_f32_fp8_e32 v[214:215], v164
; template <bool STORE>
; DI void peer_item(const Params& p, int item, char* smem) {
;     ...
; #pragma unroll
;       for (int u = 0; u < 8; ++u) {
;         int e = e_s[tl * 128 + k + u];
;         uq[u] = *(const u32x4*)(U8 + (size_t)e * 1024 + lane * 16);
;     ...
; #pragma unroll
;       for (int u = 0; u < 8; ++u) {
;         float d = 0.f;
; #pragma unroll
;         for (int i = 0; i < 4; ++i) {
;           f32x2_t lo = __builtin_amdgcn_cvt_pk_f32_fp8((int)uq[u][i], false);
;           f32x2_t hi = __builtin_amdgcn_cvt_pk_f32_fp8((int)uq[u][i], true);
;           d += xf[4 * i] * lo.x + xf[4 * i + 1] * lo.y + xf[4 * i + 2] * hi.x + xf[4 * i + 3] * hi.y;
;         }
;         part[u] = d;
;       }
;       float q4[4], r2[2], h;
; #pragma unroll
;       for (int j = 0; j < 4; ++j) {
;         float mine = b5 ? part[j + 4] : part[j];
;         float other = b5 ? part[j] : part[j + 4];
;         q4[j] = mine + __shfl_xor(other, 32);
;       }
; #pragma unroll
;       for (int j = 0; j < 2; ++j) {
;         float mine = b4 ? q4[j + 2] : q4[j];
;         float other = b4 ? q4[j] : q4[j + 2];
;         r2[j] = mine + __shfl_xor(other, 16);
;       }
;       {
;         float mine = b3 ? r2[1] : r2[0];
;         float other = b3 ? r2[0] : r2[1];
;         h = mine + __shfl_xor(other, 8);
;       }
;       h += __shfl_xor(h, 4);
;       h += __shfl_xor(h, 2);
;       h += __shfl_xor(h, 1);
	v_cvt_pk_f32_fp8_sdwa v[216:217], v164 src0_sel:WORD_1
	v_cvt_pk_f32_fp8_e32 v[218:219], v165
	v_cvt_pk_f32_fp8_sdwa v[220:221], v165 src0_sel:WORD_1
	v_pk_mul_f32 v[222:223], v[0:1], v[214:215]
	v_pk_mul_f32 v[224:225], v[2:3], v[216:217]
	v_cvt_pk_f32_fp8_e32 v[214:215], v166
	v_cvt_pk_f32_fp8_sdwa v[216:217], v166 src0_sel:WORD_1
	v_pk_fma_f32 v[222:223], v[4:5], v[218:219], v[222:223]
	v_pk_fma_f32 v[224:225], v[6:7], v[220:221], v[224:225]
	v_cvt_pk_f32_fp8_e32 v[218:219], v167
	v_cvt_pk_f32_fp8_sdwa v[220:221], v167 src0_sel:WORD_1
	v_pk_fma_f32 v[222:223], v[8:9], v[214:215], v[222:223]
	v_pk_fma_f32 v[224:225], v[10:11], v[216:217], v[224:225]
	v_pk_fma_f32 v[222:223], v[12:13], v[218:219], v[222:223]
	v_pk_fma_f32 v[224:225], v[14:15], v[220:221], v[224:225]
	v_pk_add_f32 v[222:223], v[222:223], v[224:225]
	s_nop 0
	v_add_f32_e32 v231, v222, v223
	v_cvt_pk_f32_fp8_e32 v[214:215], v168
	v_cvt_pk_f32_fp8_sdwa v[216:217], v168 src0_sel:WORD_1
	v_cvt_pk_f32_fp8_e32 v[218:219], v169
	v_cvt_pk_f32_fp8_sdwa v[220:221], v169 src0_sel:WORD_1
	v_pk_mul_f32 v[222:223], v[0:1], v[214:215]
	v_pk_mul_f32 v[224:225], v[2:3], v[216:217]
	v_cvt_pk_f32_fp8_e32 v[214:215], v170
	v_cvt_pk_f32_fp8_sdwa v[216:217], v170 src0_sel:WORD_1
	v_pk_fma_f32 v[222:223], v[4:5], v[218:219], v[222:223]
	v_pk_fma_f32 v[224:225], v[6:7], v[220:221], v[224:225]
	v_cvt_pk_f32_fp8_e32 v[218:219], v171
	v_cvt_pk_f32_fp8_sdwa v[220:221], v171 src0_sel:WORD_1
	v_pk_fma_f32 v[222:223], v[8:9], v[214:215], v[222:223]
	v_pk_fma_f32 v[224:225], v[10:11], v[216:217], v[224:225]
	v_pk_fma_f32 v[222:223], v[12:13], v[218:219], v[222:223]
	v_pk_fma_f32 v[224:225], v[14:15], v[220:221], v[224:225]
	v_pk_add_f32 v[222:223], v[222:223], v[224:225]
	s_nop 0
	v_add_f32_e32 v232, v222, v223
	v_cvt_pk_f32_fp8_e32 v[214:215], v172
	v_cvt_pk_f32_fp8_sdwa v[216:217], v172 src0_sel:WORD_1
	v_cvt_pk_f32_fp8_e32 v[218:219], v173
	v_cvt_pk_f32_fp8_sdwa v[220:221], v173 src0_sel:WORD_1
	v_pk_mul_f32 v[222:223], v[0:1], v[214:215]
	v_pk_mul_f32 v[224:225], v[2:3], v[216:217]
	v_cvt_pk_f32_fp8_e32 v[214:215], v174
	v_cvt_pk_f32_fp8_sdwa v[216:217], v174 src0_sel:WORD_1
	v_pk_fma_f32 v[222:223], v[4:5], v[218:219], v[222:223]
	v_pk_fma_f32 v[224:225], v[6:7], v[220:221], v[224:225]
	v_cvt_pk_f32_fp8_e32 v[218:219], v175
	v_cvt_pk_f32_fp8_sdwa v[220:221], v175 src0_sel:WORD_1
	v_pk_fma_f32 v[222:223], v[8:9], v[214:215], v[222:223]
	v_pk_fma_f32 v[224:225], v[10:11], v[216:217], v[224:225]
	v_pk_fma_f32 v[222:223], v[12:13], v[218:219], v[222:223]
	v_pk_fma_f32 v[224:225], v[14:15], v[220:221], v[224:225]
	v_pk_add_f32 v[222:223], v[222:223], v[224:225]
	s_nop 0
	v_add_f32_e32 v233, v222, v223
	v_permlane32_swap_b32_e32 v226, v230
	v_permlane32_swap_b32_e32 v227, v231
	v_permlane32_swap_b32_e32 v228, v232
	v_permlane32_swap_b32_e32 v229, v233
	v_add_f32_e32 v226, v226, v230
	v_add_f32_e32 v228, v228, v232
	v_add_f32_e32 v227, v227, v231
	v_add_f32_e32 v229, v229, v233
	s_nop 1
	v_permlane16_swap_b32_e32 v226, v228
	v_permlane16_swap_b32_e32 v227, v229
	v_add_f32_e32 v226, v226, v228
	v_add_f32_e32 v227, v227, v229
	s_nop 0
	v_cndmask_b32_e64 v230, v226, v227, s[24:25]
	v_cndmask_b32_e64 v231, v227, v226, s[24:25]
	s_nop 1
	v_add_f32_dpp v232, v231, v230 row_ror:8 row_mask:0xf bank_mask:0xf
	s_nop 1
	v_add_f32_dpp v233, v232, v232 quad_perm:[1,0,3,2] row_mask:0xf bank_mask:0xf
	s_nop 1
	v_add_f32_dpp v232, v233, v233 quad_perm:[2,3,0,1] row_mask:0xf bank_mask:0xf
	s_nop 1
	v_add_f32_dpp v233, v232, v232 row_half_mirror row_mask:0xf bank_mask:0xf
	ds_write_b32 v235, v233 offset:32768
	v_readlane_b32 s48, v132, s72
	v_readlane_b32 s49, v132, s73
	v_readlane_b32 s50, v132, s74
	v_readlane_b32 s51, v132, s75
	v_readlane_b32 s52, v132, s76
	v_readlane_b32 s53, v132, s77
	v_readlane_b32 s54, v132, s78
	v_readlane_b32 s55, v132, s79
	s_add_u32 s32, s0, s48
	s_addc_u32 s33, s1, 0
	s_add_u32 s34, s0, s49
	s_addc_u32 s35, s1, 0
	s_add_u32 s36, s0, s50
	s_addc_u32 s37, s1, 0
	s_add_u32 s38, s0, s51
	s_addc_u32 s39, s1, 0
	s_add_u32 s40, s0, s52
	s_addc_u32 s41, s1, 0
	s_add_u32 s42, s0, s53
	s_addc_u32 s43, s1, 0
	s_add_u32 s44, s0, s54
	s_addc_u32 s45, s1, 0
	s_add_u32 s46, s0, s55
	s_addc_u32 s47, s1, 0
	global_load_dwordx4 v[144:147], v234, s[32:33]
	global_load_dwordx4 v[148:151], v234, s[34:35]
	global_load_dwordx4 v[152:155], v234, s[36:37]
	global_load_dwordx4 v[156:159], v234, s[38:39]
	global_load_dwordx4 v[160:163], v234, s[40:41]
	global_load_dwordx4 v[164:167], v234, s[42:43]
	global_load_dwordx4 v[168:171], v234, s[44:45]
	global_load_dwordx4 v[172:175], v234, s[46:47]
	s_waitcnt vmcnt(8)
; template <bool STORE>
; DI void peer_item(const Params& p, int item, char* smem) {
;     ...
; #pragma unroll
;       for (int u = 0; u < 8; ++u) {
;         float d = 0.f;
; #pragma unroll
;         for (int i = 0; i < 4; ++i) {
;           f32x2_t lo = __builtin_amdgcn_cvt_pk_f32_fp8((int)uq[u][i], false);
;           f32x2_t hi = __builtin_amdgcn_cvt_pk_f32_fp8((int)uq[u][i], true);
;           d += xf[4 * i] * lo.x + xf[4 * i + 1] * lo.y + xf[4 * i + 2] * hi.x + xf[4 * i + 3] * hi.y;
;         }
;         part[u] = d;
;       }
;       float q4[4], r2[2], h;
	v_cvt_pk_f32_fp8_e32 v[214:215], v176
	v_cvt_pk_f32_fp8_sdwa v[216:217], v176 src0_sel:WORD_1
	v_cvt_pk_f32_fp8_e32 v[218:219], v177
	v_cvt_pk_f32_fp8_sdwa v[220:221], v177 src0_sel:WORD_1
	v_pk_mul_f32 v[222:223], v[16:17], v[214:215]
	v_pk_mul_f32 v[224:225], v[18:19], v[216:217]
	v_cvt_pk_f32_fp8_e32 v[214:215], v178
	v_cvt_pk_f32_fp8_sdwa v[216:217], v178 src0_sel:WORD_1
	v_pk_fma_f32 v[222:223], v[20:21], v[218:219], v[222:223]
	v_pk_fma_f32 v[224:225], v[22:23], v[220:221], v[224:225]
	v_cvt_pk_f32_fp8_e32 v[218:219], v179
	v_cvt_pk_f32_fp8_sdwa v[220:221], v179 src0_sel:WORD_1
	v_pk_fma_f32 v[222:223], v[24:25], v[214:215], v[222:223]
	v_pk_fma_f32 v[224:225], v[26:27], v[216:217], v[224:225]
	v_pk_fma_f32 v[222:223], v[28:29], v[218:219], v[222:223]
	v_pk_fma_f32 v[224:225], v[30:31], v[220:221], v[224:225]
	v_pk_add_f32 v[222:223], v[222:223], v[224:225]
	s_nop 0
	v_add_f32_e32 v226, v222, v223
	v_cvt_pk_f32_fp8_e32 v[214:215], v180
	v_cvt_pk_f32_fp8_sdwa v[216:217], v180 src0_sel:WORD_1
	v_cvt_pk_f32_fp8_e32 v[218:219], v181
	v_cvt_pk_f32_fp8_sdwa v[220:221], v181 src0_sel:WORD_1
	v_pk_mul_f32 v[222:223], v[16:17], v[214:215]
	v_pk_mul_f32 v[224:225], v[18:19], v[216:217]
	v_cvt_pk_f32_fp8_e32 v[214:215], v182
	v_cvt_pk_f32_fp8_sdwa v[216:217], v182 src0_sel:WORD_1
	v_pk_fma_f32 v[222:223], v[20:21], v[218:219], v[222:223]
	v_pk_fma_f32 v[224:225], v[22:23], v[220:221], v[224:225]
	v_cvt_pk_f32_fp8_e32 v[218:219], v183
	v_cvt_pk_f32_fp8_sdwa v[220:221], v183 src0_sel:WORD_1
	v_pk_fma_f32 v[222:223], v[24:25], v[214:215], v[222:223]
	v_pk_fma_f32 v[224:225], v[26:27], v[216:217], v[224:225]
	v_pk_fma_f32 v[222:223], v[28:29], v[218:219], v[222:223]
	v_pk_fma_f32 v[224:225], v[30:31], v[220:221], v[224:225]
	v_pk_add_f32 v[222:223], v[222:223], v[224:225]
	s_nop 0
	v_add_f32_e32 v227, v222, v223
	v_cvt_pk_f32_fp8_e32 v[214:215], v184
	v_cvt_pk_f32_fp8_sdwa v[216:217], v184 src0_sel:WORD_1
	v_cvt_pk_f32_fp8_e32 v[218:219], v185
	v_cvt_pk_f32_fp8_sdwa v[220:221], v185 src0_sel:WORD_1
	v_pk_mul_f32 v[222:223], v[16:17], v[214:215]
	v_pk_mul_f32 v[224:225], v[18:19], v[216:217]
	v_cvt_pk_f32_fp8_e32 v[214:215], v186
	v_cvt_pk_f32_fp8_sdwa v[216:217], v186 src0_sel:WORD_1
	v_pk_fma_f32 v[222:223], v[20:21], v[218:219], v[222:223]
	v_pk_fma_f32 v[224:225], v[22:23], v[220:221], v[224:225]
	v_cvt_pk_f32_fp8_e32 v[218:219], v187
	v_cvt_pk_f32_fp8_sdwa v[220:221], v187 src0_sel:WORD_1
	v_pk_fma_f32 v[222:223], v[24:25], v[214:215], v[222:223]
	v_pk_fma_f32 v[224:225], v[26:27], v[216:217], v[224:225]
	v_pk_fma_f32 v[222:223], v[28:29], v[218:219], v[222:223]
	v_pk_fma_f32 v[224:225], v[30:31], v[220:221], v[224:225]
	v_pk_add_f32 v[222:223], v[222:223], v[224:225]
	s_nop 0
	v_add_f32_e32 v228, v222, v223
	v_cvt_pk_f32_fp8_e32 v[214:215], v188
	v_cvt_pk_f32_fp8_sdwa v[216:217], v188 src0_sel:WORD_1
	v_cvt_pk_f32_fp8_e32 v[218:219], v189
	v_cvt_pk_f32_fp8_sdwa v[220:221], v189 src0_sel:WORD_1
	v_pk_mul_f32 v[222:223], v[16:17], v[214:215]
	v_pk_mul_f32 v[224:225], v[18:19], v[216:217]
	v_cvt_pk_f32_fp8_e32 v[214:215], v190
	v_cvt_pk_f32_fp8_sdwa v[216:217], v190 src0_sel:WORD_1
	v_pk_fma_f32 v[222:223], v[20:21], v[218:219], v[222:223]
	v_pk_fma_f32 v[224:225], v[22:23], v[220:221], v[224:225]
	v_cvt_pk_f32_fp8_e32 v[218:219], v191
	v_cvt_pk_f32_fp8_sdwa v[220:221], v191 src0_sel:WORD_1
	v_pk_fma_f32 v[222:223], v[24:25], v[214:215], v[222:223]
	v_pk_fma_f32 v[224:225], v[26:27], v[216:217], v[224:225]
	v_pk_fma_f32 v[222:223], v[28:29], v[218:219], v[222:223]
	v_pk_fma_f32 v[224:225], v[30:31], v[220:221], v[224:225]
	v_pk_add_f32 v[222:223], v[222:223], v[224:225]
	s_nop 0
	v_add_f32_e32 v229, v222, v223
	v_cvt_pk_f32_fp8_e32 v[214:215], v192
	v_cvt_pk_f32_fp8_sdwa v[216:217], v192 src0_sel:WORD_1
	v_cvt_pk_f32_fp8_e32 v[218:219], v193
	v_cvt_pk_f32_fp8_sdwa v[220:221], v193 src0_sel:WORD_1
	v_pk_mul_f32 v[222:223], v[16:17], v[214:215]
	v_pk_mul_f32 v[224:225], v[18:19], v[216:217]
	v_cvt_pk_f32_fp8_e32 v[214:215], v194
	v_cvt_pk_f32_fp8_sdwa v[216:217], v194 src0_sel:WORD_1
	v_pk_fma_f32 v[222:223], v[20:21], v[218:219], v[222:223]
	v_pk_fma_f32 v[224:225], v[22:23], v[220:221], v[224:225]
	v_cvt_pk_f32_fp8_e32 v[218:219], v195
	v_cvt_pk_f32_fp8_sdwa v[220:221], v195 src0_sel:WORD_1
	v_pk_fma_f32 v[222:223], v[24:25], v[214:215], v[222:223]
	v_pk_fma_f32 v[224:225], v[26:27], v[216:217], v[224:225]
	v_pk_fma_f32 v[222:223], v[28:29], v[218:219], v[222:223]
	v_pk_fma_f32 v[224:225], v[30:31], v[220:221], v[224:225]
	v_pk_add_f32 v[222:223], v[222:223], v[224:225]
	s_nop 0
	v_add_f32_e32 v230, v222, v223
	v_cvt_pk_f32_fp8_e32 v[214:215], v196
	v_cvt_pk_f32_fp8_sdwa v[216:217], v196 src0_sel:WORD_1
	v_cvt_pk_f32_fp8_e32 v[218:219], v197
	v_cvt_pk_f32_fp8_sdwa v[220:221], v197 src0_sel:WORD_1
	v_pk_mul_f32 v[222:223], v[16:17], v[214:215]
	v_pk_mul_f32 v[224:225], v[18:19], v[216:217]
	v_cvt_pk_f32_fp8_e32 v[214:215], v198
	v_cvt_pk_f32_fp8_sdwa v[216:217], v198 src0_sel:WORD_1
	v_pk_fma_f32 v[222:223], v[20:21], v[218:219], v[222:223]
	v_pk_fma_f32 v[224:225], v[22:23], v[220:221], v[224:225]
	v_cvt_pk_f32_fp8_e32 v[218:219], v199
	v_cvt_pk_f32_fp8_sdwa v[220:221], v199 src0_sel:WORD_1
	v_pk_fma_f32 v[222:223], v[24:25], v[214:215], v[222:223]
	v_pk_fma_f32 v[224:225], v[26:27], v[216:217], v[224:225]
	v_pk_fma_f32 v[222:223], v[28:29], v[218:219], v[222:223]
	v_pk_fma_f32 v[224:225], v[30:31], v[220:221], v[224:225]
	v_pk_add_f32 v[222:223], v[222:223], v[224:225]
	s_nop 0
	v_add_f32_e32 v231, v222, v223
	v_cvt_pk_f32_fp8_e32 v[214:215], v200
	v_cvt_pk_f32_fp8_sdwa v[216:217], v200 src0_sel:WORD_1
	v_cvt_pk_f32_fp8_e32 v[218:219], v201
; template <bool STORE>
; DI void peer_item(const Params& p, int item, char* smem) {
;     ...
; #pragma unroll
;       for (int u = 0; u < 8; ++u) {
;         int e = e_s[tl * 128 + k + u];
;         uq[u] = *(const u32x4*)(U8 + (size_t)e * 1024 + lane * 16);
;     ...
; #pragma unroll
;       for (int u = 0; u < 8; ++u) {
;         float d = 0.f;
; #pragma unroll
;         for (int i = 0; i < 4; ++i) {
;           f32x2_t lo = __builtin_amdgcn_cvt_pk_f32_fp8((int)uq[u][i], false);
;           f32x2_t hi = __builtin_amdgcn_cvt_pk_f32_fp8((int)uq[u][i], true);
;           d += xf[4 * i] * lo.x + xf[4 * i + 1] * lo.y + xf[4 * i + 2] * hi.x + xf[4 * i + 3] * hi.y;
;         }
;         part[u] = d;
;       }
;       float q4[4], r2[2], h;
; #pragma unroll
;       for (int j = 0; j < 4; ++j) {
;         float mine = b5 ? part[j + 4] : part[j];
;         float other = b5 ? part[j] : part[j + 4];
;         q4[j] = mine + __shfl_xor(other, 32);
;       }
; #pragma unroll
;       for (int j = 0; j < 2; ++j) {
;         float mine = b4 ? q4[j + 2] : q4[j];
;         float other = b4 ? q4[j] : q4[j + 2];
;         r2[j] = mine + __shfl_xor(other, 16);
;       }
;       {
;         float mine = b3 ? r2[1] : r2[0];
;         float other = b3 ? r2[0] : r2[1];
;         h = mine + __shfl_xor(other, 8);
;       }
;       h += __shfl_xor(h, 4);
;       h += __shfl_xor(h, 2);
;       h += __shfl_xor(h, 1);
	v_cvt_pk_f32_fp8_sdwa v[220:221], v201 src0_sel:WORD_1
	v_pk_mul_f32 v[222:223], v[16:17], v[214:215]
	v_pk_mul_f32 v[224:225], v[18:19], v[216:217]
	v_cvt_pk_f32_fp8_e32 v[214:215], v202
	v_cvt_pk_f32_fp8_sdwa v[216:217], v202 src0_sel:WORD_1
	v_pk_fma_f32 v[222:223], v[20:21], v[218:219], v[222:223]
	v_pk_fma_f32 v[224:225], v[22:23], v[220:221], v[224:225]
	v_cvt_pk_f32_fp8_e32 v[218:219], v203
	v_cvt_pk_f32_fp8_sdwa v[220:221], v203 src0_sel:WORD_1
	v_pk_fma_f32 v[222:223], v[24:25], v[214:215], v[222:223]
	v_pk_fma_f32 v[224:225], v[26:27], v[216:217], v[224:225]
	v_pk_fma_f32 v[222:223], v[28:29], v[218:219], v[222:223]
	v_pk_fma_f32 v[224:225], v[30:31], v[220:221], v[224:225]
	v_pk_add_f32 v[222:223], v[222:223], v[224:225]
	s_nop 0
	v_add_f32_e32 v232, v222, v223
	v_cvt_pk_f32_fp8_e32 v[214:215], v204
	v_cvt_pk_f32_fp8_sdwa v[216:217], v204 src0_sel:WORD_1
	v_cvt_pk_f32_fp8_e32 v[218:219], v205
	v_cvt_pk_f32_fp8_sdwa v[220:221], v205 src0_sel:WORD_1
	v_pk_mul_f32 v[222:223], v[16:17], v[214:215]
	v_pk_mul_f32 v[224:225], v[18:19], v[216:217]
	v_cvt_pk_f32_fp8_e32 v[214:215], v206
	v_cvt_pk_f32_fp8_sdwa v[216:217], v206 src0_sel:WORD_1
	v_pk_fma_f32 v[222:223], v[20:21], v[218:219], v[222:223]
	v_pk_fma_f32 v[224:225], v[22:23], v[220:221], v[224:225]
	v_cvt_pk_f32_fp8_e32 v[218:219], v207
	v_cvt_pk_f32_fp8_sdwa v[220:221], v207 src0_sel:WORD_1
	v_pk_fma_f32 v[222:223], v[24:25], v[214:215], v[222:223]
	v_pk_fma_f32 v[224:225], v[26:27], v[216:217], v[224:225]
	v_pk_fma_f32 v[222:223], v[28:29], v[218:219], v[222:223]
	v_pk_fma_f32 v[224:225], v[30:31], v[220:221], v[224:225]
	v_pk_add_f32 v[222:223], v[222:223], v[224:225]
	s_nop 0
	v_add_f32_e32 v233, v222, v223
	v_permlane32_swap_b32_e32 v226, v230
	v_permlane32_swap_b32_e32 v227, v231
	v_permlane32_swap_b32_e32 v228, v232
	v_permlane32_swap_b32_e32 v229, v233
	v_add_f32_e32 v226, v226, v230
	v_add_f32_e32 v228, v228, v232
	v_add_f32_e32 v227, v227, v231
	v_add_f32_e32 v229, v229, v233
	s_nop 1
	v_permlane16_swap_b32_e32 v226, v228
	v_permlane16_swap_b32_e32 v227, v229
	v_add_f32_e32 v226, v226, v228
	v_add_f32_e32 v227, v227, v229
	s_nop 0
	v_cndmask_b32_e64 v230, v226, v227, s[24:25]
	v_cndmask_b32_e64 v231, v227, v226, s[24:25]
	s_nop 1
	v_add_f32_dpp v232, v231, v230 row_ror:8 row_mask:0xf bank_mask:0xf
	s_nop 1
	v_add_f32_dpp v233, v232, v232 quad_perm:[1,0,3,2] row_mask:0xf bank_mask:0xf
	s_nop 1
	v_add_f32_dpp v232, v233, v233 quad_perm:[2,3,0,1] row_mask:0xf bank_mask:0xf
	s_nop 1
	v_add_f32_dpp v233, v232, v232 row_half_mirror row_mask:0xf bank_mask:0xf
	ds_write_b32 v235, v233 offset:33280
	v_readlane_b32 s48, v134, s72
	v_readlane_b32 s49, v134, s73
	v_readlane_b32 s50, v134, s74
	v_readlane_b32 s51, v134, s75
	v_readlane_b32 s52, v134, s76
	v_readlane_b32 s53, v134, s77
	v_readlane_b32 s54, v134, s78
	v_readlane_b32 s55, v134, s79
	s_add_u32 s32, s0, s48
	s_addc_u32 s33, s1, 0
	s_add_u32 s34, s0, s49
	s_addc_u32 s35, s1, 0
	s_add_u32 s36, s0, s50
	s_addc_u32 s37, s1, 0
	s_add_u32 s38, s0, s51
	s_addc_u32 s39, s1, 0
	s_add_u32 s40, s0, s52
	s_addc_u32 s41, s1, 0
	s_add_u32 s42, s0, s53
	s_addc_u32 s43, s1, 0
	s_add_u32 s44, s0, s54
	s_addc_u32 s45, s1, 0
	s_add_u32 s46, s0, s55
	s_addc_u32 s47, s1, 0
	global_load_dwordx4 v[176:179], v234, s[32:33]
	global_load_dwordx4 v[180:183], v234, s[34:35]
	global_load_dwordx4 v[184:187], v234, s[36:37]
	global_load_dwordx4 v[188:191], v234, s[38:39]
	global_load_dwordx4 v[192:195], v234, s[40:41]
	global_load_dwordx4 v[196:199], v234, s[42:43]
	global_load_dwordx4 v[200:203], v234, s[44:45]
	global_load_dwordx4 v[204:207], v234, s[46:47]
	s_waitcnt vmcnt(8)
	v_cvt_pk_f32_fp8_e32 v[214:215], v144
	v_cvt_pk_f32_fp8_sdwa v[216:217], v144 src0_sel:WORD_1
	v_cvt_pk_f32_fp8_e32 v[218:219], v145
	v_cvt_pk_f32_fp8_sdwa v[220:221], v145 src0_sel:WORD_1
	v_pk_mul_f32 v[222:223], v[32:33], v[214:215]
	v_pk_mul_f32 v[224:225], v[34:35], v[216:217]
	v_cvt_pk_f32_fp8_e32 v[214:215], v146
	v_cvt_pk_f32_fp8_sdwa v[216:217], v146 src0_sel:WORD_1
	v_pk_fma_f32 v[222:223], v[36:37], v[218:219], v[222:223]
	v_pk_fma_f32 v[224:225], v[38:39], v[220:221], v[224:225]
	v_cvt_pk_f32_fp8_e32 v[218:219], v147
	v_cvt_pk_f32_fp8_sdwa v[220:221], v147 src0_sel:WORD_1
	v_pk_fma_f32 v[222:223], v[40:41], v[214:215], v[222:223]
	v_pk_fma_f32 v[224:225], v[42:43], v[216:217], v[224:225]
	v_pk_fma_f32 v[222:223], v[44:45], v[218:219], v[222:223]
	v_pk_fma_f32 v[224:225], v[46:47], v[220:221], v[224:225]
	v_pk_add_f32 v[222:223], v[222:223], v[224:225]
	s_nop 0
	v_add_f32_e32 v226, v222, v223
	v_cvt_pk_f32_fp8_e32 v[214:215], v148
	v_cvt_pk_f32_fp8_sdwa v[216:217], v148 src0_sel:WORD_1
	v_cvt_pk_f32_fp8_e32 v[218:219], v149
	v_cvt_pk_f32_fp8_sdwa v[220:221], v149 src0_sel:WORD_1
	v_pk_mul_f32 v[222:223], v[32:33], v[214:215]
	v_pk_mul_f32 v[224:225], v[34:35], v[216:217]
	v_cvt_pk_f32_fp8_e32 v[214:215], v150
	v_cvt_pk_f32_fp8_sdwa v[216:217], v150 src0_sel:WORD_1
	v_pk_fma_f32 v[222:223], v[36:37], v[218:219], v[222:223]
	v_pk_fma_f32 v[224:225], v[38:39], v[220:221], v[224:225]
	v_cvt_pk_f32_fp8_e32 v[218:219], v151
	v_cvt_pk_f32_fp8_sdwa v[220:221], v151 src0_sel:WORD_1
	v_pk_fma_f32 v[222:223], v[40:41], v[214:215], v[222:223]
	v_pk_fma_f32 v[224:225], v[42:43], v[216:217], v[224:225]
	v_pk_fma_f32 v[222:223], v[44:45], v[218:219], v[222:223]
	v_pk_fma_f32 v[224:225], v[46:47], v[220:221], v[224:225]
	v_pk_add_f32 v[222:223], v[222:223], v[224:225]
	s_nop 0
	v_add_f32_e32 v227, v222, v223
	v_cvt_pk_f32_fp8_e32 v[214:215], v152
	v_cvt_pk_f32_fp8_sdwa v[216:217], v152 src0_sel:WORD_1
	v_cvt_pk_f32_fp8_e32 v[218:219], v153
	v_cvt_pk_f32_fp8_sdwa v[220:221], v153 src0_sel:WORD_1
; template <bool STORE>
; DI void peer_item(const Params& p, int item, char* smem) {
;     ...
; #pragma unroll
;       for (int u = 0; u < 8; ++u) {
;         float d = 0.f;
; #pragma unroll
;         for (int i = 0; i < 4; ++i) {
;           f32x2_t lo = __builtin_amdgcn_cvt_pk_f32_fp8((int)uq[u][i], false);
;           f32x2_t hi = __builtin_amdgcn_cvt_pk_f32_fp8((int)uq[u][i], true);
;           d += xf[4 * i] * lo.x + xf[4 * i + 1] * lo.y + xf[4 * i + 2] * hi.x + xf[4 * i + 3] * hi.y;
;         }
;         part[u] = d;
;       }
;       float q4[4], r2[2], h;
; #pragma unroll
;       for (int j = 0; j < 4; ++j) {
;         float mine = b5 ? part[j + 4] : part[j];
;         float other = b5 ? part[j] : part[j + 4];
;         q4[j] = mine + __shfl_xor(other, 32);
;       }
; #pragma unroll
;       for (int j = 0; j < 2; ++j) {
;         float mine = b4 ? q4[j + 2] : q4[j];
	v_pk_mul_f32 v[222:223], v[32:33], v[214:215]
	v_pk_mul_f32 v[224:225], v[34:35], v[216:217]
	v_cvt_pk_f32_fp8_e32 v[214:215], v154
	v_cvt_pk_f32_fp8_sdwa v[216:217], v154 src0_sel:WORD_1
	v_pk_fma_f32 v[222:223], v[36:37], v[218:219], v[222:223]
	v_pk_fma_f32 v[224:225], v[38:39], v[220:221], v[224:225]
	v_cvt_pk_f32_fp8_e32 v[218:219], v155
	v_cvt_pk_f32_fp8_sdwa v[220:221], v155 src0_sel:WORD_1
	v_pk_fma_f32 v[222:223], v[40:41], v[214:215], v[222:223]
	v_pk_fma_f32 v[224:225], v[42:43], v[216:217], v[224:225]
	v_pk_fma_f32 v[222:223], v[44:45], v[218:219], v[222:223]
	v_pk_fma_f32 v[224:225], v[46:47], v[220:221], v[224:225]
	v_pk_add_f32 v[222:223], v[222:223], v[224:225]
	s_nop 0
	v_add_f32_e32 v228, v222, v223
	v_cvt_pk_f32_fp8_e32 v[214:215], v156
	v_cvt_pk_f32_fp8_sdwa v[216:217], v156 src0_sel:WORD_1
	v_cvt_pk_f32_fp8_e32 v[218:219], v157
	v_cvt_pk_f32_fp8_sdwa v[220:221], v157 src0_sel:WORD_1
	v_pk_mul_f32 v[222:223], v[32:33], v[214:215]
	v_pk_mul_f32 v[224:225], v[34:35], v[216:217]
	v_cvt_pk_f32_fp8_e32 v[214:215], v158
	v_cvt_pk_f32_fp8_sdwa v[216:217], v158 src0_sel:WORD_1
	v_pk_fma_f32 v[222:223], v[36:37], v[218:219], v[222:223]
	v_pk_fma_f32 v[224:225], v[38:39], v[220:221], v[224:225]
	v_cvt_pk_f32_fp8_e32 v[218:219], v159
	v_cvt_pk_f32_fp8_sdwa v[220:221], v159 src0_sel:WORD_1
	v_pk_fma_f32 v[222:223], v[40:41], v[214:215], v[222:223]
	v_pk_fma_f32 v[224:225], v[42:43], v[216:217], v[224:225]
	v_pk_fma_f32 v[222:223], v[44:45], v[218:219], v[222:223]
	v_pk_fma_f32 v[224:225], v[46:47], v[220:221], v[224:225]
	v_pk_add_f32 v[222:223], v[222:223], v[224:225]
	s_nop 0
	v_add_f32_e32 v229, v222, v223
	v_cvt_pk_f32_fp8_e32 v[214:215], v160
	v_cvt_pk_f32_fp8_sdwa v[216:217], v160 src0_sel:WORD_1
	v_cvt_pk_f32_fp8_e32 v[218:219], v161
	v_cvt_pk_f32_fp8_sdwa v[220:221], v161 src0_sel:WORD_1
	v_pk_mul_f32 v[222:223], v[32:33], v[214:215]
	v_pk_mul_f32 v[224:225], v[34:35], v[216:217]
	v_cvt_pk_f32_fp8_e32 v[214:215], v162
	v_cvt_pk_f32_fp8_sdwa v[216:217], v162 src0_sel:WORD_1
	v_pk_fma_f32 v[222:223], v[36:37], v[218:219], v[222:223]
	v_pk_fma_f32 v[224:225], v[38:39], v[220:221], v[224:225]
	v_cvt_pk_f32_fp8_e32 v[218:219], v163
	v_cvt_pk_f32_fp8_sdwa v[220:221], v163 src0_sel:WORD_1
	v_pk_fma_f32 v[222:223], v[40:41], v[214:215], v[222:223]
	v_pk_fma_f32 v[224:225], v[42:43], v[216:217], v[224:225]
	v_pk_fma_f32 v[222:223], v[44:45], v[218:219], v[222:223]
	v_pk_fma_f32 v[224:225], v[46:47], v[220:221], v[224:225]
	v_pk_add_f32 v[222:223], v[222:223], v[224:225]
	s_nop 0
	v_add_f32_e32 v230, v222, v223
	v_cvt_pk_f32_fp8_e32 v[214:215], v164
	v_cvt_pk_f32_fp8_sdwa v[216:217], v164 src0_sel:WORD_1
	v_cvt_pk_f32_fp8_e32 v[218:219], v165
	v_cvt_pk_f32_fp8_sdwa v[220:221], v165 src0_sel:WORD_1
	v_pk_mul_f32 v[222:223], v[32:33], v[214:215]
	v_pk_mul_f32 v[224:225], v[34:35], v[216:217]
	v_cvt_pk_f32_fp8_e32 v[214:215], v166
	v_cvt_pk_f32_fp8_sdwa v[216:217], v166 src0_sel:WORD_1
	v_pk_fma_f32 v[222:223], v[36:37], v[218:219], v[222:223]
	v_pk_fma_f32 v[224:225], v[38:39], v[220:221], v[224:225]
	v_cvt_pk_f32_fp8_e32 v[218:219], v167
	v_cvt_pk_f32_fp8_sdwa v[220:221], v167 src0_sel:WORD_1
	v_pk_fma_f32 v[222:223], v[40:41], v[214:215], v[222:223]
	v_pk_fma_f32 v[224:225], v[42:43], v[216:217], v[224:225]
	v_pk_fma_f32 v[222:223], v[44:45], v[218:219], v[222:223]
	v_pk_fma_f32 v[224:225], v[46:47], v[220:221], v[224:225]
	v_pk_add_f32 v[222:223], v[222:223], v[224:225]
	s_nop 0
	v_add_f32_e32 v231, v222, v223
	v_cvt_pk_f32_fp8_e32 v[214:215], v168
	v_cvt_pk_f32_fp8_sdwa v[216:217], v168 src0_sel:WORD_1
	v_cvt_pk_f32_fp8_e32 v[218:219], v169
	v_cvt_pk_f32_fp8_sdwa v[220:221], v169 src0_sel:WORD_1
	v_pk_mul_f32 v[222:223], v[32:33], v[214:215]
	v_pk_mul_f32 v[224:225], v[34:35], v[216:217]
	v_cvt_pk_f32_fp8_e32 v[214:215], v170
	v_cvt_pk_f32_fp8_sdwa v[216:217], v170 src0_sel:WORD_1
	v_pk_fma_f32 v[222:223], v[36:37], v[218:219], v[222:223]
	v_pk_fma_f32 v[224:225], v[38:39], v[220:221], v[224:225]
	v_cvt_pk_f32_fp8_e32 v[218:219], v171
	v_cvt_pk_f32_fp8_sdwa v[220:221], v171 src0_sel:WORD_1
	v_pk_fma_f32 v[222:223], v[40:41], v[214:215], v[222:223]
	v_pk_fma_f32 v[224:225], v[42:43], v[216:217], v[224:225]
	v_pk_fma_f32 v[222:223], v[44:45], v[218:219], v[222:223]
	v_pk_fma_f32 v[224:225], v[46:47], v[220:221], v[224:225]
	v_pk_add_f32 v[222:223], v[222:223], v[224:225]
	s_nop 0
	v_add_f32_e32 v232, v222, v223
	v_cvt_pk_f32_fp8_e32 v[214:215], v172
	v_cvt_pk_f32_fp8_sdwa v[216:217], v172 src0_sel:WORD_1
	v_cvt_pk_f32_fp8_e32 v[218:219], v173
	v_cvt_pk_f32_fp8_sdwa v[220:221], v173 src0_sel:WORD_1
	v_pk_mul_f32 v[222:223], v[32:33], v[214:215]
	v_pk_mul_f32 v[224:225], v[34:35], v[216:217]
	v_cvt_pk_f32_fp8_e32 v[214:215], v174
	v_cvt_pk_f32_fp8_sdwa v[216:217], v174 src0_sel:WORD_1
	v_pk_fma_f32 v[222:223], v[36:37], v[218:219], v[222:223]
	v_pk_fma_f32 v[224:225], v[38:39], v[220:221], v[224:225]
	v_cvt_pk_f32_fp8_e32 v[218:219], v175
	v_cvt_pk_f32_fp8_sdwa v[220:221], v175 src0_sel:WORD_1
	v_pk_fma_f32 v[222:223], v[40:41], v[214:215], v[222:223]
	v_pk_fma_f32 v[224:225], v[42:43], v[216:217], v[224:225]
	v_pk_fma_f32 v[222:223], v[44:45], v[218:219], v[222:223]
	v_pk_fma_f32 v[224:225], v[46:47], v[220:221], v[224:225]
	v_pk_add_f32 v[222:223], v[222:223], v[224:225]
	s_nop 0
	v_add_f32_e32 v233, v222, v223
	v_permlane32_swap_b32_e32 v226, v230
	v_permlane32_swap_b32_e32 v227, v231
	v_permlane32_swap_b32_e32 v228, v232
	v_permlane32_swap_b32_e32 v229, v233
	v_add_f32_e32 v226, v226, v230
	v_add_f32_e32 v228, v228, v232
	v_add_f32_e32 v227, v227, v231
	v_add_f32_e32 v229, v229, v233
	s_nop 1
	v_permlane16_swap_b32_e32 v226, v228
; template <bool STORE>
; DI void peer_item(const Params& p, int item, char* smem) {
;     ...
; #pragma unroll
;       for (int u = 0; u < 8; ++u) {
;         int e = e_s[tl * 128 + k + u];
;         uq[u] = *(const u32x4*)(U8 + (size_t)e * 1024 + lane * 16);
;     ...
;       for (int j = 0; j < 4; ++j) {
;         float mine = b5 ? part[j + 4] : part[j];
;         float other = b5 ? part[j] : part[j + 4];
;         q4[j] = mine + __shfl_xor(other, 32);
;       }
; #pragma unroll
;       for (int j = 0; j < 2; ++j) {
;         float mine = b4 ? q4[j + 2] : q4[j];
;         float other = b4 ? q4[j] : q4[j + 2];
;         r2[j] = mine + __shfl_xor(other, 16);
;       }
;       {
;         float mine = b3 ? r2[1] : r2[0];
;         float other = b3 ? r2[0] : r2[1];
;         h = mine + __shfl_xor(other, 8);
;       }
;       h += __shfl_xor(h, 4);
;       h += __shfl_xor(h, 2);
;       h += __shfl_xor(h, 1);
	v_permlane16_swap_b32_e32 v227, v229
	v_add_f32_e32 v226, v226, v228
	v_add_f32_e32 v227, v227, v229
	s_nop 0
	v_cndmask_b32_e64 v230, v226, v227, s[24:25]
	v_cndmask_b32_e64 v231, v227, v226, s[24:25]
	s_nop 1
	v_add_f32_dpp v232, v231, v230 row_ror:8 row_mask:0xf bank_mask:0xf
	s_nop 1
	v_add_f32_dpp v233, v232, v232 quad_perm:[1,0,3,2] row_mask:0xf bank_mask:0xf
	s_nop 1
	v_add_f32_dpp v232, v233, v233 quad_perm:[2,3,0,1] row_mask:0xf bank_mask:0xf
	s_nop 1
	v_add_f32_dpp v233, v232, v232 row_half_mirror row_mask:0xf bank_mask:0xf
	ds_write_b32 v235, v233 offset:33792
	v_readlane_b32 s48, v136, s72
	v_readlane_b32 s49, v136, s73
	v_readlane_b32 s50, v136, s74
	v_readlane_b32 s51, v136, s75
	v_readlane_b32 s52, v136, s76
	v_readlane_b32 s53, v136, s77
	v_readlane_b32 s54, v136, s78
	v_readlane_b32 s55, v136, s79
	s_add_u32 s32, s0, s48
	s_addc_u32 s33, s1, 0
	s_add_u32 s34, s0, s49
	s_addc_u32 s35, s1, 0
	s_add_u32 s36, s0, s50
	s_addc_u32 s37, s1, 0
	s_add_u32 s38, s0, s51
	s_addc_u32 s39, s1, 0
	s_add_u32 s40, s0, s52
	s_addc_u32 s41, s1, 0
	s_add_u32 s42, s0, s53
	s_addc_u32 s43, s1, 0
	s_add_u32 s44, s0, s54
	s_addc_u32 s45, s1, 0
	s_add_u32 s46, s0, s55
	s_addc_u32 s47, s1, 0
	global_load_dwordx4 v[144:147], v234, s[32:33]
	global_load_dwordx4 v[148:151], v234, s[34:35]
	global_load_dwordx4 v[152:155], v234, s[36:37]
	global_load_dwordx4 v[156:159], v234, s[38:39]
	global_load_dwordx4 v[160:163], v234, s[40:41]
	global_load_dwordx4 v[164:167], v234, s[42:43]
	global_load_dwordx4 v[168:171], v234, s[44:45]
	global_load_dwordx4 v[172:175], v234, s[46:47]
	s_waitcnt vmcnt(8)
	v_cvt_pk_f32_fp8_e32 v[214:215], v176
	v_cvt_pk_f32_fp8_sdwa v[216:217], v176 src0_sel:WORD_1
	v_cvt_pk_f32_fp8_e32 v[218:219], v177
	v_cvt_pk_f32_fp8_sdwa v[220:221], v177 src0_sel:WORD_1
	v_pk_mul_f32 v[222:223], v[48:49], v[214:215]
	v_pk_mul_f32 v[224:225], v[50:51], v[216:217]
	v_cvt_pk_f32_fp8_e32 v[214:215], v178
	v_cvt_pk_f32_fp8_sdwa v[216:217], v178 src0_sel:WORD_1
	v_pk_fma_f32 v[222:223], v[52:53], v[218:219], v[222:223]
	v_pk_fma_f32 v[224:225], v[54:55], v[220:221], v[224:225]
	v_cvt_pk_f32_fp8_e32 v[218:219], v179
	v_cvt_pk_f32_fp8_sdwa v[220:221], v179 src0_sel:WORD_1
	v_pk_fma_f32 v[222:223], v[56:57], v[214:215], v[222:223]
	v_pk_fma_f32 v[224:225], v[58:59], v[216:217], v[224:225]
	v_pk_fma_f32 v[222:223], v[60:61], v[218:219], v[222:223]
	v_pk_fma_f32 v[224:225], v[62:63], v[220:221], v[224:225]
	v_pk_add_f32 v[222:223], v[222:223], v[224:225]
	s_nop 0
	v_add_f32_e32 v226, v222, v223
	v_cvt_pk_f32_fp8_e32 v[214:215], v180
	v_cvt_pk_f32_fp8_sdwa v[216:217], v180 src0_sel:WORD_1
	v_cvt_pk_f32_fp8_e32 v[218:219], v181
	v_cvt_pk_f32_fp8_sdwa v[220:221], v181 src0_sel:WORD_1
	v_pk_mul_f32 v[222:223], v[48:49], v[214:215]
	v_pk_mul_f32 v[224:225], v[50:51], v[216:217]
	v_cvt_pk_f32_fp8_e32 v[214:215], v182
	v_cvt_pk_f32_fp8_sdwa v[216:217], v182 src0_sel:WORD_1
	v_pk_fma_f32 v[222:223], v[52:53], v[218:219], v[222:223]
	v_pk_fma_f32 v[224:225], v[54:55], v[220:221], v[224:225]
	v_cvt_pk_f32_fp8_e32 v[218:219], v183
	v_cvt_pk_f32_fp8_sdwa v[220:221], v183 src0_sel:WORD_1
	v_pk_fma_f32 v[222:223], v[56:57], v[214:215], v[222:223]
	v_pk_fma_f32 v[224:225], v[58:59], v[216:217], v[224:225]
	v_pk_fma_f32 v[222:223], v[60:61], v[218:219], v[222:223]
	v_pk_fma_f32 v[224:225], v[62:63], v[220:221], v[224:225]
	v_pk_add_f32 v[222:223], v[222:223], v[224:225]
	s_nop 0
	v_add_f32_e32 v227, v222, v223
	v_cvt_pk_f32_fp8_e32 v[214:215], v184
	v_cvt_pk_f32_fp8_sdwa v[216:217], v184 src0_sel:WORD_1
	v_cvt_pk_f32_fp8_e32 v[218:219], v185
	v_cvt_pk_f32_fp8_sdwa v[220:221], v185 src0_sel:WORD_1
	v_pk_mul_f32 v[222:223], v[48:49], v[214:215]
	v_pk_mul_f32 v[224:225], v[50:51], v[216:217]
	v_cvt_pk_f32_fp8_e32 v[214:215], v186
	v_cvt_pk_f32_fp8_sdwa v[216:217], v186 src0_sel:WORD_1
	v_pk_fma_f32 v[222:223], v[52:53], v[218:219], v[222:223]
	v_pk_fma_f32 v[224:225], v[54:55], v[220:221], v[224:225]
	v_cvt_pk_f32_fp8_e32 v[218:219], v187
	v_cvt_pk_f32_fp8_sdwa v[220:221], v187 src0_sel:WORD_1
	v_pk_fma_f32 v[222:223], v[56:57], v[214:215], v[222:223]
	v_pk_fma_f32 v[224:225], v[58:59], v[216:217], v[224:225]
	v_pk_fma_f32 v[222:223], v[60:61], v[218:219], v[222:223]
	v_pk_fma_f32 v[224:225], v[62:63], v[220:221], v[224:225]
	v_pk_add_f32 v[222:223], v[222:223], v[224:225]
	s_nop 0
	v_add_f32_e32 v228, v222, v223
	v_cvt_pk_f32_fp8_e32 v[214:215], v188
	v_cvt_pk_f32_fp8_sdwa v[216:217], v188 src0_sel:WORD_1
	v_cvt_pk_f32_fp8_e32 v[218:219], v189
	v_cvt_pk_f32_fp8_sdwa v[220:221], v189 src0_sel:WORD_1
	v_pk_mul_f32 v[222:223], v[48:49], v[214:215]
	v_pk_mul_f32 v[224:225], v[50:51], v[216:217]
	v_cvt_pk_f32_fp8_e32 v[214:215], v190
	v_cvt_pk_f32_fp8_sdwa v[216:217], v190 src0_sel:WORD_1
	v_pk_fma_f32 v[222:223], v[52:53], v[218:219], v[222:223]
	v_pk_fma_f32 v[224:225], v[54:55], v[220:221], v[224:225]
	v_cvt_pk_f32_fp8_e32 v[218:219], v191
	v_cvt_pk_f32_fp8_sdwa v[220:221], v191 src0_sel:WORD_1
	v_pk_fma_f32 v[222:223], v[56:57], v[214:215], v[222:223]
	v_pk_fma_f32 v[224:225], v[58:59], v[216:217], v[224:225]
	v_pk_fma_f32 v[222:223], v[60:61], v[218:219], v[222:223]
	v_pk_fma_f32 v[224:225], v[62:63], v[220:221], v[224:225]
	v_pk_add_f32 v[222:223], v[222:223], v[224:225]
	s_nop 0
	v_add_f32_e32 v229, v222, v223
	v_cvt_pk_f32_fp8_e32 v[214:215], v192
	v_cvt_pk_f32_fp8_sdwa v[216:217], v192 src0_sel:WORD_1
	v_cvt_pk_f32_fp8_e32 v[218:219], v193
	v_cvt_pk_f32_fp8_sdwa v[220:221], v193 src0_sel:WORD_1
	v_pk_mul_f32 v[222:223], v[48:49], v[214:215]
	v_pk_mul_f32 v[224:225], v[50:51], v[216:217]
	v_cvt_pk_f32_fp8_e32 v[214:215], v194
	v_cvt_pk_f32_fp8_sdwa v[216:217], v194 src0_sel:WORD_1
; template <bool STORE>
; DI void peer_item(const Params& p, int item, char* smem) {
;     ...
; #pragma unroll
;       for (int u = 0; u < 8; ++u) {
;         int e = e_s[tl * 128 + k + u];
;         uq[u] = *(const u32x4*)(U8 + (size_t)e * 1024 + lane * 16);
;       }
;       float part[8];
; #pragma unroll
;       for (int u = 0; u < 8; ++u) {
;         float d = 0.f;
; #pragma unroll
;         for (int i = 0; i < 4; ++i) {
;           f32x2_t lo = __builtin_amdgcn_cvt_pk_f32_fp8((int)uq[u][i], false);
;           f32x2_t hi = __builtin_amdgcn_cvt_pk_f32_fp8((int)uq[u][i], true);
;           d += xf[4 * i] * lo.x + xf[4 * i + 1] * lo.y + xf[4 * i + 2] * hi.x + xf[4 * i + 3] * hi.y;
;         }
;         part[u] = d;
;       }
;       float q4[4], r2[2], h;
; #pragma unroll
;       for (int j = 0; j < 4; ++j) {
;         float mine = b5 ? part[j + 4] : part[j];
;         float other = b5 ? part[j] : part[j + 4];
;         q4[j] = mine + __shfl_xor(other, 32);
;       }
; #pragma unroll
;       for (int j = 0; j < 2; ++j) {
;         float mine = b4 ? q4[j + 2] : q4[j];
;         float other = b4 ? q4[j] : q4[j + 2];
;         r2[j] = mine + __shfl_xor(other, 16);
;       }
;       {
;         float mine = b3 ? r2[1] : r2[0];
;         float other = b3 ? r2[0] : r2[1];
;         h = mine + __shfl_xor(other, 8);
;       }
;       h += __shfl_xor(h, 4);
;       h += __shfl_xor(h, 2);
;       h += __shfl_xor(h, 1);
	v_pk_fma_f32 v[222:223], v[52:53], v[218:219], v[222:223]
	v_pk_fma_f32 v[224:225], v[54:55], v[220:221], v[224:225]
	v_cvt_pk_f32_fp8_e32 v[218:219], v195
	v_cvt_pk_f32_fp8_sdwa v[220:221], v195 src0_sel:WORD_1
	v_pk_fma_f32 v[222:223], v[56:57], v[214:215], v[222:223]
	v_pk_fma_f32 v[224:225], v[58:59], v[216:217], v[224:225]
	v_pk_fma_f32 v[222:223], v[60:61], v[218:219], v[222:223]
	v_pk_fma_f32 v[224:225], v[62:63], v[220:221], v[224:225]
	v_pk_add_f32 v[222:223], v[222:223], v[224:225]
	s_nop 0
	v_add_f32_e32 v230, v222, v223
	v_cvt_pk_f32_fp8_e32 v[214:215], v196
	v_cvt_pk_f32_fp8_sdwa v[216:217], v196 src0_sel:WORD_1
	v_cvt_pk_f32_fp8_e32 v[218:219], v197
	v_cvt_pk_f32_fp8_sdwa v[220:221], v197 src0_sel:WORD_1
	v_pk_mul_f32 v[222:223], v[48:49], v[214:215]
	v_pk_mul_f32 v[224:225], v[50:51], v[216:217]
	v_cvt_pk_f32_fp8_e32 v[214:215], v198
	v_cvt_pk_f32_fp8_sdwa v[216:217], v198 src0_sel:WORD_1
	v_pk_fma_f32 v[222:223], v[52:53], v[218:219], v[222:223]
	v_pk_fma_f32 v[224:225], v[54:55], v[220:221], v[224:225]
	v_cvt_pk_f32_fp8_e32 v[218:219], v199
	v_cvt_pk_f32_fp8_sdwa v[220:221], v199 src0_sel:WORD_1
	v_pk_fma_f32 v[222:223], v[56:57], v[214:215], v[222:223]
	v_pk_fma_f32 v[224:225], v[58:59], v[216:217], v[224:225]
	v_pk_fma_f32 v[222:223], v[60:61], v[218:219], v[222:223]
	v_pk_fma_f32 v[224:225], v[62:63], v[220:221], v[224:225]
	v_pk_add_f32 v[222:223], v[222:223], v[224:225]
	s_nop 0
	v_add_f32_e32 v231, v222, v223
	v_cvt_pk_f32_fp8_e32 v[214:215], v200
	v_cvt_pk_f32_fp8_sdwa v[216:217], v200 src0_sel:WORD_1
	v_cvt_pk_f32_fp8_e32 v[218:219], v201
	v_cvt_pk_f32_fp8_sdwa v[220:221], v201 src0_sel:WORD_1
	v_pk_mul_f32 v[222:223], v[48:49], v[214:215]
	v_pk_mul_f32 v[224:225], v[50:51], v[216:217]
	v_cvt_pk_f32_fp8_e32 v[214:215], v202
	v_cvt_pk_f32_fp8_sdwa v[216:217], v202 src0_sel:WORD_1
	v_pk_fma_f32 v[222:223], v[52:53], v[218:219], v[222:223]
	v_pk_fma_f32 v[224:225], v[54:55], v[220:221], v[224:225]
	v_cvt_pk_f32_fp8_e32 v[218:219], v203
	v_cvt_pk_f32_fp8_sdwa v[220:221], v203 src0_sel:WORD_1
	v_pk_fma_f32 v[222:223], v[56:57], v[214:215], v[222:223]
	v_pk_fma_f32 v[224:225], v[58:59], v[216:217], v[224:225]
	v_pk_fma_f32 v[222:223], v[60:61], v[218:219], v[222:223]
	v_pk_fma_f32 v[224:225], v[62:63], v[220:221], v[224:225]
	v_pk_add_f32 v[222:223], v[222:223], v[224:225]
	s_nop 0
	v_add_f32_e32 v232, v222, v223
	v_cvt_pk_f32_fp8_e32 v[214:215], v204
	v_cvt_pk_f32_fp8_sdwa v[216:217], v204 src0_sel:WORD_1
	v_cvt_pk_f32_fp8_e32 v[218:219], v205
	v_cvt_pk_f32_fp8_sdwa v[220:221], v205 src0_sel:WORD_1
	v_pk_mul_f32 v[222:223], v[48:49], v[214:215]
	v_pk_mul_f32 v[224:225], v[50:51], v[216:217]
	v_cvt_pk_f32_fp8_e32 v[214:215], v206
	v_cvt_pk_f32_fp8_sdwa v[216:217], v206 src0_sel:WORD_1
	v_pk_fma_f32 v[222:223], v[52:53], v[218:219], v[222:223]
	v_pk_fma_f32 v[224:225], v[54:55], v[220:221], v[224:225]
	v_cvt_pk_f32_fp8_e32 v[218:219], v207
	v_cvt_pk_f32_fp8_sdwa v[220:221], v207 src0_sel:WORD_1
	v_pk_fma_f32 v[222:223], v[56:57], v[214:215], v[222:223]
	v_pk_fma_f32 v[224:225], v[58:59], v[216:217], v[224:225]
	v_pk_fma_f32 v[222:223], v[60:61], v[218:219], v[222:223]
	v_pk_fma_f32 v[224:225], v[62:63], v[220:221], v[224:225]
	v_pk_add_f32 v[222:223], v[222:223], v[224:225]
	s_nop 0
	v_add_f32_e32 v233, v222, v223
	v_permlane32_swap_b32_e32 v226, v230
	v_permlane32_swap_b32_e32 v227, v231
	v_permlane32_swap_b32_e32 v228, v232
	v_permlane32_swap_b32_e32 v229, v233
	v_add_f32_e32 v226, v226, v230
	v_add_f32_e32 v228, v228, v232
	v_add_f32_e32 v227, v227, v231
	v_add_f32_e32 v229, v229, v233
	s_nop 1
	v_permlane16_swap_b32_e32 v226, v228
	v_permlane16_swap_b32_e32 v227, v229
	v_add_f32_e32 v226, v226, v228
	v_add_f32_e32 v227, v227, v229
	s_nop 0
	v_cndmask_b32_e64 v230, v226, v227, s[24:25]
	v_cndmask_b32_e64 v231, v227, v226, s[24:25]
	s_nop 1
	v_add_f32_dpp v232, v231, v230 row_ror:8 row_mask:0xf bank_mask:0xf
	s_nop 1
	v_add_f32_dpp v233, v232, v232 quad_perm:[1,0,3,2] row_mask:0xf bank_mask:0xf
	s_nop 1
	v_add_f32_dpp v232, v233, v233 quad_perm:[2,3,0,1] row_mask:0xf bank_mask:0xf
	s_nop 1
	v_add_f32_dpp v233, v232, v232 row_half_mirror row_mask:0xf bank_mask:0xf
	ds_write_b32 v235, v233 offset:34304
	v_readlane_b32 s48, v138, s72
	v_readlane_b32 s49, v138, s73
	v_readlane_b32 s50, v138, s74
	v_readlane_b32 s51, v138, s75
	v_readlane_b32 s52, v138, s76
	v_readlane_b32 s53, v138, s77
	v_readlane_b32 s54, v138, s78
	v_readlane_b32 s55, v138, s79
	s_add_u32 s32, s0, s48
	s_addc_u32 s33, s1, 0
	s_add_u32 s34, s0, s49
	s_addc_u32 s35, s1, 0
	s_add_u32 s36, s0, s50
	s_addc_u32 s37, s1, 0
	s_add_u32 s38, s0, s51
	s_addc_u32 s39, s1, 0
	s_add_u32 s40, s0, s52
	s_addc_u32 s41, s1, 0
	s_add_u32 s42, s0, s53
	s_addc_u32 s43, s1, 0
	s_add_u32 s44, s0, s54
	s_addc_u32 s45, s1, 0
	s_add_u32 s46, s0, s55
	s_addc_u32 s47, s1, 0
	global_load_dwordx4 v[176:179], v234, s[32:33]
	global_load_dwordx4 v[180:183], v234, s[34:35]
	global_load_dwordx4 v[184:187], v234, s[36:37]
	global_load_dwordx4 v[188:191], v234, s[38:39]
	global_load_dwordx4 v[192:195], v234, s[40:41]
	global_load_dwordx4 v[196:199], v234, s[42:43]
	global_load_dwordx4 v[200:203], v234, s[44:45]
	global_load_dwordx4 v[204:207], v234, s[46:47]
	s_waitcnt vmcnt(8)
; template <bool STORE>
; DI void peer_item(const Params& p, int item, char* smem) {
;     ...
; #pragma unroll
;       for (int u = 0; u < 8; ++u) {
;         float d = 0.f;
; #pragma unroll
;         for (int i = 0; i < 4; ++i) {
;           f32x2_t lo = __builtin_amdgcn_cvt_pk_f32_fp8((int)uq[u][i], false);
;           f32x2_t hi = __builtin_amdgcn_cvt_pk_f32_fp8((int)uq[u][i], true);
;           d += xf[4 * i] * lo.x + xf[4 * i + 1] * lo.y + xf[4 * i + 2] * hi.x + xf[4 * i + 3] * hi.y;
;         }
;         part[u] = d;
;       }
	v_cvt_pk_f32_fp8_e32 v[214:215], v144
	v_cvt_pk_f32_fp8_sdwa v[216:217], v144 src0_sel:WORD_1
	v_cvt_pk_f32_fp8_e32 v[218:219], v145
	v_cvt_pk_f32_fp8_sdwa v[220:221], v145 src0_sel:WORD_1
	v_pk_mul_f32 v[222:223], v[64:65], v[214:215]
	v_pk_mul_f32 v[224:225], v[66:67], v[216:217]
	v_cvt_pk_f32_fp8_e32 v[214:215], v146
	v_cvt_pk_f32_fp8_sdwa v[216:217], v146 src0_sel:WORD_1
	v_pk_fma_f32 v[222:223], v[68:69], v[218:219], v[222:223]
	v_pk_fma_f32 v[224:225], v[70:71], v[220:221], v[224:225]
	v_cvt_pk_f32_fp8_e32 v[218:219], v147
	v_cvt_pk_f32_fp8_sdwa v[220:221], v147 src0_sel:WORD_1
	v_pk_fma_f32 v[222:223], v[72:73], v[214:215], v[222:223]
	v_pk_fma_f32 v[224:225], v[74:75], v[216:217], v[224:225]
	v_pk_fma_f32 v[222:223], v[76:77], v[218:219], v[222:223]
	v_pk_fma_f32 v[224:225], v[78:79], v[220:221], v[224:225]
	v_pk_add_f32 v[222:223], v[222:223], v[224:225]
	s_nop 0
	v_add_f32_e32 v226, v222, v223
	v_cvt_pk_f32_fp8_e32 v[214:215], v148
	v_cvt_pk_f32_fp8_sdwa v[216:217], v148 src0_sel:WORD_1
	v_cvt_pk_f32_fp8_e32 v[218:219], v149
	v_cvt_pk_f32_fp8_sdwa v[220:221], v149 src0_sel:WORD_1
	v_pk_mul_f32 v[222:223], v[64:65], v[214:215]
	v_pk_mul_f32 v[224:225], v[66:67], v[216:217]
	v_cvt_pk_f32_fp8_e32 v[214:215], v150
	v_cvt_pk_f32_fp8_sdwa v[216:217], v150 src0_sel:WORD_1
	v_pk_fma_f32 v[222:223], v[68:69], v[218:219], v[222:223]
	v_pk_fma_f32 v[224:225], v[70:71], v[220:221], v[224:225]
	v_cvt_pk_f32_fp8_e32 v[218:219], v151
	v_cvt_pk_f32_fp8_sdwa v[220:221], v151 src0_sel:WORD_1
	v_pk_fma_f32 v[222:223], v[72:73], v[214:215], v[222:223]
	v_pk_fma_f32 v[224:225], v[74:75], v[216:217], v[224:225]
	v_pk_fma_f32 v[222:223], v[76:77], v[218:219], v[222:223]
	v_pk_fma_f32 v[224:225], v[78:79], v[220:221], v[224:225]
	v_pk_add_f32 v[222:223], v[222:223], v[224:225]
	s_nop 0
	v_add_f32_e32 v227, v222, v223
	v_cvt_pk_f32_fp8_e32 v[214:215], v152
	v_cvt_pk_f32_fp8_sdwa v[216:217], v152 src0_sel:WORD_1
	v_cvt_pk_f32_fp8_e32 v[218:219], v153
	v_cvt_pk_f32_fp8_sdwa v[220:221], v153 src0_sel:WORD_1
	v_pk_mul_f32 v[222:223], v[64:65], v[214:215]
	v_pk_mul_f32 v[224:225], v[66:67], v[216:217]
	v_cvt_pk_f32_fp8_e32 v[214:215], v154
	v_cvt_pk_f32_fp8_sdwa v[216:217], v154 src0_sel:WORD_1
	v_pk_fma_f32 v[222:223], v[68:69], v[218:219], v[222:223]
	v_pk_fma_f32 v[224:225], v[70:71], v[220:221], v[224:225]
	v_cvt_pk_f32_fp8_e32 v[218:219], v155
	v_cvt_pk_f32_fp8_sdwa v[220:221], v155 src0_sel:WORD_1
	v_pk_fma_f32 v[222:223], v[72:73], v[214:215], v[222:223]
	v_pk_fma_f32 v[224:225], v[74:75], v[216:217], v[224:225]
	v_pk_fma_f32 v[222:223], v[76:77], v[218:219], v[222:223]
	v_pk_fma_f32 v[224:225], v[78:79], v[220:221], v[224:225]
	v_pk_add_f32 v[222:223], v[222:223], v[224:225]
	s_nop 0
	v_add_f32_e32 v228, v222, v223
	v_cvt_pk_f32_fp8_e32 v[214:215], v156
	v_cvt_pk_f32_fp8_sdwa v[216:217], v156 src0_sel:WORD_1
	v_cvt_pk_f32_fp8_e32 v[218:219], v157
	v_cvt_pk_f32_fp8_sdwa v[220:221], v157 src0_sel:WORD_1
	v_pk_mul_f32 v[222:223], v[64:65], v[214:215]
	v_pk_mul_f32 v[224:225], v[66:67], v[216:217]
	v_cvt_pk_f32_fp8_e32 v[214:215], v158
	v_cvt_pk_f32_fp8_sdwa v[216:217], v158 src0_sel:WORD_1
	v_pk_fma_f32 v[222:223], v[68:69], v[218:219], v[222:223]
	v_pk_fma_f32 v[224:225], v[70:71], v[220:221], v[224:225]
	v_cvt_pk_f32_fp8_e32 v[218:219], v159
	v_cvt_pk_f32_fp8_sdwa v[220:221], v159 src0_sel:WORD_1
	v_pk_fma_f32 v[222:223], v[72:73], v[214:215], v[222:223]
	v_pk_fma_f32 v[224:225], v[74:75], v[216:217], v[224:225]
	v_pk_fma_f32 v[222:223], v[76:77], v[218:219], v[222:223]
	v_pk_fma_f32 v[224:225], v[78:79], v[220:221], v[224:225]
	v_pk_add_f32 v[222:223], v[222:223], v[224:225]
	s_nop 0
	v_add_f32_e32 v229, v222, v223
	v_cvt_pk_f32_fp8_e32 v[214:215], v160
	v_cvt_pk_f32_fp8_sdwa v[216:217], v160 src0_sel:WORD_1
	v_cvt_pk_f32_fp8_e32 v[218:219], v161
	v_cvt_pk_f32_fp8_sdwa v[220:221], v161 src0_sel:WORD_1
	v_pk_mul_f32 v[222:223], v[64:65], v[214:215]
	v_pk_mul_f32 v[224:225], v[66:67], v[216:217]
	v_cvt_pk_f32_fp8_e32 v[214:215], v162
	v_cvt_pk_f32_fp8_sdwa v[216:217], v162 src0_sel:WORD_1
	v_pk_fma_f32 v[222:223], v[68:69], v[218:219], v[222:223]
	v_pk_fma_f32 v[224:225], v[70:71], v[220:221], v[224:225]
	v_cvt_pk_f32_fp8_e32 v[218:219], v163
	v_cvt_pk_f32_fp8_sdwa v[220:221], v163 src0_sel:WORD_1
	v_pk_fma_f32 v[222:223], v[72:73], v[214:215], v[222:223]
	v_pk_fma_f32 v[224:225], v[74:75], v[216:217], v[224:225]
	v_pk_fma_f32 v[222:223], v[76:77], v[218:219], v[222:223]
	v_pk_fma_f32 v[224:225], v[78:79], v[220:221], v[224:225]
	v_pk_add_f32 v[222:223], v[222:223], v[224:225]
	s_nop 0
	v_add_f32_e32 v230, v222, v223
	v_cvt_pk_f32_fp8_e32 v[214:215], v164
	v_cvt_pk_f32_fp8_sdwa v[216:217], v164 src0_sel:WORD_1
	v_cvt_pk_f32_fp8_e32 v[218:219], v165
	v_cvt_pk_f32_fp8_sdwa v[220:221], v165 src0_sel:WORD_1
	v_pk_mul_f32 v[222:223], v[64:65], v[214:215]
	v_pk_mul_f32 v[224:225], v[66:67], v[216:217]
	v_cvt_pk_f32_fp8_e32 v[214:215], v166
	v_cvt_pk_f32_fp8_sdwa v[216:217], v166 src0_sel:WORD_1
	v_pk_fma_f32 v[222:223], v[68:69], v[218:219], v[222:223]
	v_pk_fma_f32 v[224:225], v[70:71], v[220:221], v[224:225]
	v_cvt_pk_f32_fp8_e32 v[218:219], v167
	v_cvt_pk_f32_fp8_sdwa v[220:221], v167 src0_sel:WORD_1
	v_pk_fma_f32 v[222:223], v[72:73], v[214:215], v[222:223]
	v_pk_fma_f32 v[224:225], v[74:75], v[216:217], v[224:225]
	v_pk_fma_f32 v[222:223], v[76:77], v[218:219], v[222:223]
	v_pk_fma_f32 v[224:225], v[78:79], v[220:221], v[224:225]
	v_pk_add_f32 v[222:223], v[222:223], v[224:225]
	s_nop 0
	v_add_f32_e32 v231, v222, v223
	v_cvt_pk_f32_fp8_e32 v[214:215], v168
	v_cvt_pk_f32_fp8_sdwa v[216:217], v168 src0_sel:WORD_1
	v_cvt_pk_f32_fp8_e32 v[218:219], v169
; template <bool STORE>
; DI void peer_item(const Params& p, int item, char* smem) {
;     ...
; #pragma unroll
;       for (int u = 0; u < 8; ++u) {
;         int e = e_s[tl * 128 + k + u];
;         uq[u] = *(const u32x4*)(U8 + (size_t)e * 1024 + lane * 16);
;       }
;       float part[8];
; #pragma unroll
;       for (int u = 0; u < 8; ++u) {
;         float d = 0.f;
; #pragma unroll
;         for (int i = 0; i < 4; ++i) {
;           f32x2_t lo = __builtin_amdgcn_cvt_pk_f32_fp8((int)uq[u][i], false);
;           f32x2_t hi = __builtin_amdgcn_cvt_pk_f32_fp8((int)uq[u][i], true);
;           d += xf[4 * i] * lo.x + xf[4 * i + 1] * lo.y + xf[4 * i + 2] * hi.x + xf[4 * i + 3] * hi.y;
;         }
;         part[u] = d;
;       }
;       float q4[4], r2[2], h;
; #pragma unroll
;       for (int j = 0; j < 4; ++j) {
;         float mine = b5 ? part[j + 4] : part[j];
;         float other = b5 ? part[j] : part[j + 4];
;         q4[j] = mine + __shfl_xor(other, 32);
;       }
; #pragma unroll
;       for (int j = 0; j < 2; ++j) {
;         float mine = b4 ? q4[j + 2] : q4[j];
;         float other = b4 ? q4[j] : q4[j + 2];
;         r2[j] = mine + __shfl_xor(other, 16);
;       }
;       {
;         float mine = b3 ? r2[1] : r2[0];
;         float other = b3 ? r2[0] : r2[1];
;         h = mine + __shfl_xor(other, 8);
;       }
;       h += __shfl_xor(h, 4);
;       h += __shfl_xor(h, 2);
;       h += __shfl_xor(h, 1);
	v_cvt_pk_f32_fp8_sdwa v[220:221], v169 src0_sel:WORD_1
	v_pk_mul_f32 v[222:223], v[64:65], v[214:215]
	v_pk_mul_f32 v[224:225], v[66:67], v[216:217]
	v_cvt_pk_f32_fp8_e32 v[214:215], v170
	v_cvt_pk_f32_fp8_sdwa v[216:217], v170 src0_sel:WORD_1
	v_pk_fma_f32 v[222:223], v[68:69], v[218:219], v[222:223]
	v_pk_fma_f32 v[224:225], v[70:71], v[220:221], v[224:225]
	v_cvt_pk_f32_fp8_e32 v[218:219], v171
	v_cvt_pk_f32_fp8_sdwa v[220:221], v171 src0_sel:WORD_1
	v_pk_fma_f32 v[222:223], v[72:73], v[214:215], v[222:223]
	v_pk_fma_f32 v[224:225], v[74:75], v[216:217], v[224:225]
	v_pk_fma_f32 v[222:223], v[76:77], v[218:219], v[222:223]
	v_pk_fma_f32 v[224:225], v[78:79], v[220:221], v[224:225]
	v_pk_add_f32 v[222:223], v[222:223], v[224:225]
	s_nop 0
	v_add_f32_e32 v232, v222, v223
	v_cvt_pk_f32_fp8_e32 v[214:215], v172
	v_cvt_pk_f32_fp8_sdwa v[216:217], v172 src0_sel:WORD_1
	v_cvt_pk_f32_fp8_e32 v[218:219], v173
	v_cvt_pk_f32_fp8_sdwa v[220:221], v173 src0_sel:WORD_1
	v_pk_mul_f32 v[222:223], v[64:65], v[214:215]
	v_pk_mul_f32 v[224:225], v[66:67], v[216:217]
	v_cvt_pk_f32_fp8_e32 v[214:215], v174
	v_cvt_pk_f32_fp8_sdwa v[216:217], v174 src0_sel:WORD_1
	v_pk_fma_f32 v[222:223], v[68:69], v[218:219], v[222:223]
	v_pk_fma_f32 v[224:225], v[70:71], v[220:221], v[224:225]
	v_cvt_pk_f32_fp8_e32 v[218:219], v175
	v_cvt_pk_f32_fp8_sdwa v[220:221], v175 src0_sel:WORD_1
	v_pk_fma_f32 v[222:223], v[72:73], v[214:215], v[222:223]
	v_pk_fma_f32 v[224:225], v[74:75], v[216:217], v[224:225]
	v_pk_fma_f32 v[222:223], v[76:77], v[218:219], v[222:223]
	v_pk_fma_f32 v[224:225], v[78:79], v[220:221], v[224:225]
	v_pk_add_f32 v[222:223], v[222:223], v[224:225]
	s_nop 0
	v_add_f32_e32 v233, v222, v223
	v_permlane32_swap_b32_e32 v226, v230
	v_permlane32_swap_b32_e32 v227, v231
	v_permlane32_swap_b32_e32 v228, v232
	v_permlane32_swap_b32_e32 v229, v233
	v_add_f32_e32 v226, v226, v230
	v_add_f32_e32 v228, v228, v232
	v_add_f32_e32 v227, v227, v231
	v_add_f32_e32 v229, v229, v233
	s_nop 1
	v_permlane16_swap_b32_e32 v226, v228
	v_permlane16_swap_b32_e32 v227, v229
	v_add_f32_e32 v226, v226, v228
	v_add_f32_e32 v227, v227, v229
	s_nop 0
	v_cndmask_b32_e64 v230, v226, v227, s[24:25]
	v_cndmask_b32_e64 v231, v227, v226, s[24:25]
	s_nop 1
	v_add_f32_dpp v232, v231, v230 row_ror:8 row_mask:0xf bank_mask:0xf
	s_nop 1
	v_add_f32_dpp v233, v232, v232 quad_perm:[1,0,3,2] row_mask:0xf bank_mask:0xf
	s_nop 1
	v_add_f32_dpp v232, v233, v233 quad_perm:[2,3,0,1] row_mask:0xf bank_mask:0xf
	s_nop 1
	v_add_f32_dpp v233, v232, v232 row_half_mirror row_mask:0xf bank_mask:0xf
	ds_write_b32 v235, v233 offset:34816
	v_readlane_b32 s48, v140, s72
	v_readlane_b32 s49, v140, s73
	v_readlane_b32 s50, v140, s74
	v_readlane_b32 s51, v140, s75
	v_readlane_b32 s52, v140, s76
	v_readlane_b32 s53, v140, s77
	v_readlane_b32 s54, v140, s78
	v_readlane_b32 s55, v140, s79
	s_add_u32 s32, s0, s48
	s_addc_u32 s33, s1, 0
	s_add_u32 s34, s0, s49
	s_addc_u32 s35, s1, 0
	s_add_u32 s36, s0, s50
	s_addc_u32 s37, s1, 0
	s_add_u32 s38, s0, s51
	s_addc_u32 s39, s1, 0
	s_add_u32 s40, s0, s52
	s_addc_u32 s41, s1, 0
	s_add_u32 s42, s0, s53
	s_addc_u32 s43, s1, 0
	s_add_u32 s44, s0, s54
	s_addc_u32 s45, s1, 0
	s_add_u32 s46, s0, s55
	s_addc_u32 s47, s1, 0
	global_load_dwordx4 v[144:147], v234, s[32:33]
	global_load_dwordx4 v[148:151], v234, s[34:35]
	global_load_dwordx4 v[152:155], v234, s[36:37]
	global_load_dwordx4 v[156:159], v234, s[38:39]
	global_load_dwordx4 v[160:163], v234, s[40:41]
	global_load_dwordx4 v[164:167], v234, s[42:43]
	global_load_dwordx4 v[168:171], v234, s[44:45]
	global_load_dwordx4 v[172:175], v234, s[46:47]
	s_waitcnt vmcnt(8)
	v_cvt_pk_f32_fp8_e32 v[214:215], v176
	v_cvt_pk_f32_fp8_sdwa v[216:217], v176 src0_sel:WORD_1
	v_cvt_pk_f32_fp8_e32 v[218:219], v177
	v_cvt_pk_f32_fp8_sdwa v[220:221], v177 src0_sel:WORD_1
	v_pk_mul_f32 v[222:223], v[80:81], v[214:215]
	v_pk_mul_f32 v[224:225], v[82:83], v[216:217]
	v_cvt_pk_f32_fp8_e32 v[214:215], v178
	v_cvt_pk_f32_fp8_sdwa v[216:217], v178 src0_sel:WORD_1
	v_pk_fma_f32 v[222:223], v[84:85], v[218:219], v[222:223]
	v_pk_fma_f32 v[224:225], v[86:87], v[220:221], v[224:225]
	v_cvt_pk_f32_fp8_e32 v[218:219], v179
	v_cvt_pk_f32_fp8_sdwa v[220:221], v179 src0_sel:WORD_1
	v_pk_fma_f32 v[222:223], v[88:89], v[214:215], v[222:223]
	v_pk_fma_f32 v[224:225], v[90:91], v[216:217], v[224:225]
	v_pk_fma_f32 v[222:223], v[92:93], v[218:219], v[222:223]
	v_pk_fma_f32 v[224:225], v[94:95], v[220:221], v[224:225]
	v_pk_add_f32 v[222:223], v[222:223], v[224:225]
	s_nop 0
	v_add_f32_e32 v226, v222, v223
	v_cvt_pk_f32_fp8_e32 v[214:215], v180
	v_cvt_pk_f32_fp8_sdwa v[216:217], v180 src0_sel:WORD_1
	v_cvt_pk_f32_fp8_e32 v[218:219], v181
	v_cvt_pk_f32_fp8_sdwa v[220:221], v181 src0_sel:WORD_1
	v_pk_mul_f32 v[222:223], v[80:81], v[214:215]
	v_pk_mul_f32 v[224:225], v[82:83], v[216:217]
	v_cvt_pk_f32_fp8_e32 v[214:215], v182
	v_cvt_pk_f32_fp8_sdwa v[216:217], v182 src0_sel:WORD_1
	v_pk_fma_f32 v[222:223], v[84:85], v[218:219], v[222:223]
	v_pk_fma_f32 v[224:225], v[86:87], v[220:221], v[224:225]
	v_cvt_pk_f32_fp8_e32 v[218:219], v183
	v_cvt_pk_f32_fp8_sdwa v[220:221], v183 src0_sel:WORD_1
	v_pk_fma_f32 v[222:223], v[88:89], v[214:215], v[222:223]
	v_pk_fma_f32 v[224:225], v[90:91], v[216:217], v[224:225]
	v_pk_fma_f32 v[222:223], v[92:93], v[218:219], v[222:223]
	v_pk_fma_f32 v[224:225], v[94:95], v[220:221], v[224:225]
	v_pk_add_f32 v[222:223], v[222:223], v[224:225]
	s_nop 0
	v_add_f32_e32 v227, v222, v223
	v_cvt_pk_f32_fp8_e32 v[214:215], v184
	v_cvt_pk_f32_fp8_sdwa v[216:217], v184 src0_sel:WORD_1
	v_cvt_pk_f32_fp8_e32 v[218:219], v185
	v_cvt_pk_f32_fp8_sdwa v[220:221], v185 src0_sel:WORD_1
; template <bool STORE>
; DI void peer_item(const Params& p, int item, char* smem) {
;     ...
; #pragma unroll
;       for (int u = 0; u < 8; ++u) {
;         float d = 0.f;
; #pragma unroll
;         for (int i = 0; i < 4; ++i) {
;           f32x2_t lo = __builtin_amdgcn_cvt_pk_f32_fp8((int)uq[u][i], false);
;           f32x2_t hi = __builtin_amdgcn_cvt_pk_f32_fp8((int)uq[u][i], true);
;           d += xf[4 * i] * lo.x + xf[4 * i + 1] * lo.y + xf[4 * i + 2] * hi.x + xf[4 * i + 3] * hi.y;
;         }
;         part[u] = d;
;       }
;       float q4[4], r2[2], h;
; #pragma unroll
;       for (int j = 0; j < 4; ++j) {
;         float mine = b5 ? part[j + 4] : part[j];
;         float other = b5 ? part[j] : part[j + 4];
;         q4[j] = mine + __shfl_xor(other, 32);
;       }
; #pragma unroll
;       for (int j = 0; j < 2; ++j) {
;         float mine = b4 ? q4[j + 2] : q4[j];
;         float other = b4 ? q4[j] : q4[j + 2];
;         r2[j] = mine + __shfl_xor(other, 16);
;       }
;       {
;         float mine = b3 ? r2[1] : r2[0];
;         float other = b3 ? r2[0] : r2[1];
;         h = mine + __shfl_xor(other, 8);
;       }
;       h += __shfl_xor(h, 4);
;       h += __shfl_xor(h, 2);
;       h += __shfl_xor(h, 1);
	v_pk_mul_f32 v[222:223], v[80:81], v[214:215]
	v_pk_mul_f32 v[224:225], v[82:83], v[216:217]
	v_cvt_pk_f32_fp8_e32 v[214:215], v186
	v_cvt_pk_f32_fp8_sdwa v[216:217], v186 src0_sel:WORD_1
	v_pk_fma_f32 v[222:223], v[84:85], v[218:219], v[222:223]
	v_pk_fma_f32 v[224:225], v[86:87], v[220:221], v[224:225]
	v_cvt_pk_f32_fp8_e32 v[218:219], v187
	v_cvt_pk_f32_fp8_sdwa v[220:221], v187 src0_sel:WORD_1
	v_pk_fma_f32 v[222:223], v[88:89], v[214:215], v[222:223]
	v_pk_fma_f32 v[224:225], v[90:91], v[216:217], v[224:225]
	v_pk_fma_f32 v[222:223], v[92:93], v[218:219], v[222:223]
	v_pk_fma_f32 v[224:225], v[94:95], v[220:221], v[224:225]
	v_pk_add_f32 v[222:223], v[222:223], v[224:225]
	s_nop 0
	v_add_f32_e32 v228, v222, v223
	v_cvt_pk_f32_fp8_e32 v[214:215], v188
	v_cvt_pk_f32_fp8_sdwa v[216:217], v188 src0_sel:WORD_1
	v_cvt_pk_f32_fp8_e32 v[218:219], v189
	v_cvt_pk_f32_fp8_sdwa v[220:221], v189 src0_sel:WORD_1
	v_pk_mul_f32 v[222:223], v[80:81], v[214:215]
	v_pk_mul_f32 v[224:225], v[82:83], v[216:217]
	v_cvt_pk_f32_fp8_e32 v[214:215], v190
	v_cvt_pk_f32_fp8_sdwa v[216:217], v190 src0_sel:WORD_1
	v_pk_fma_f32 v[222:223], v[84:85], v[218:219], v[222:223]
	v_pk_fma_f32 v[224:225], v[86:87], v[220:221], v[224:225]
	v_cvt_pk_f32_fp8_e32 v[218:219], v191
	v_cvt_pk_f32_fp8_sdwa v[220:221], v191 src0_sel:WORD_1
	v_pk_fma_f32 v[222:223], v[88:89], v[214:215], v[222:223]
	v_pk_fma_f32 v[224:225], v[90:91], v[216:217], v[224:225]
	v_pk_fma_f32 v[222:223], v[92:93], v[218:219], v[222:223]
	v_pk_fma_f32 v[224:225], v[94:95], v[220:221], v[224:225]
	v_pk_add_f32 v[222:223], v[222:223], v[224:225]
	s_nop 0
	v_add_f32_e32 v229, v222, v223
	v_cvt_pk_f32_fp8_e32 v[214:215], v192
	v_cvt_pk_f32_fp8_sdwa v[216:217], v192 src0_sel:WORD_1
	v_cvt_pk_f32_fp8_e32 v[218:219], v193
	v_cvt_pk_f32_fp8_sdwa v[220:221], v193 src0_sel:WORD_1
	v_pk_mul_f32 v[222:223], v[80:81], v[214:215]
	v_pk_mul_f32 v[224:225], v[82:83], v[216:217]
	v_cvt_pk_f32_fp8_e32 v[214:215], v194
	v_cvt_pk_f32_fp8_sdwa v[216:217], v194 src0_sel:WORD_1
	v_pk_fma_f32 v[222:223], v[84:85], v[218:219], v[222:223]
	v_pk_fma_f32 v[224:225], v[86:87], v[220:221], v[224:225]
	v_cvt_pk_f32_fp8_e32 v[218:219], v195
	v_cvt_pk_f32_fp8_sdwa v[220:221], v195 src0_sel:WORD_1
	v_pk_fma_f32 v[222:223], v[88:89], v[214:215], v[222:223]
	v_pk_fma_f32 v[224:225], v[90:91], v[216:217], v[224:225]
	v_pk_fma_f32 v[222:223], v[92:93], v[218:219], v[222:223]
	v_pk_fma_f32 v[224:225], v[94:95], v[220:221], v[224:225]
	v_pk_add_f32 v[222:223], v[222:223], v[224:225]
	s_nop 0
	v_add_f32_e32 v230, v222, v223
	v_cvt_pk_f32_fp8_e32 v[214:215], v196
	v_cvt_pk_f32_fp8_sdwa v[216:217], v196 src0_sel:WORD_1
	v_cvt_pk_f32_fp8_e32 v[218:219], v197
	v_cvt_pk_f32_fp8_sdwa v[220:221], v197 src0_sel:WORD_1
	v_pk_mul_f32 v[222:223], v[80:81], v[214:215]
	v_pk_mul_f32 v[224:225], v[82:83], v[216:217]
	v_cvt_pk_f32_fp8_e32 v[214:215], v198
	v_cvt_pk_f32_fp8_sdwa v[216:217], v198 src0_sel:WORD_1
	v_pk_fma_f32 v[222:223], v[84:85], v[218:219], v[222:223]
	v_pk_fma_f32 v[224:225], v[86:87], v[220:221], v[224:225]
	v_cvt_pk_f32_fp8_e32 v[218:219], v199
	v_cvt_pk_f32_fp8_sdwa v[220:221], v199 src0_sel:WORD_1
	v_pk_fma_f32 v[222:223], v[88:89], v[214:215], v[222:223]
	v_pk_fma_f32 v[224:225], v[90:91], v[216:217], v[224:225]
	v_pk_fma_f32 v[222:223], v[92:93], v[218:219], v[222:223]
	v_pk_fma_f32 v[224:225], v[94:95], v[220:221], v[224:225]
	v_pk_add_f32 v[222:223], v[222:223], v[224:225]
	s_nop 0
	v_add_f32_e32 v231, v222, v223
	v_cvt_pk_f32_fp8_e32 v[214:215], v200
	v_cvt_pk_f32_fp8_sdwa v[216:217], v200 src0_sel:WORD_1
	v_cvt_pk_f32_fp8_e32 v[218:219], v201
	v_cvt_pk_f32_fp8_sdwa v[220:221], v201 src0_sel:WORD_1
	v_pk_mul_f32 v[222:223], v[80:81], v[214:215]
	v_pk_mul_f32 v[224:225], v[82:83], v[216:217]
	v_cvt_pk_f32_fp8_e32 v[214:215], v202
	v_cvt_pk_f32_fp8_sdwa v[216:217], v202 src0_sel:WORD_1
	v_pk_fma_f32 v[222:223], v[84:85], v[218:219], v[222:223]
	v_pk_fma_f32 v[224:225], v[86:87], v[220:221], v[224:225]
	v_cvt_pk_f32_fp8_e32 v[218:219], v203
	v_cvt_pk_f32_fp8_sdwa v[220:221], v203 src0_sel:WORD_1
	v_pk_fma_f32 v[222:223], v[88:89], v[214:215], v[222:223]
	v_pk_fma_f32 v[224:225], v[90:91], v[216:217], v[224:225]
	v_pk_fma_f32 v[222:223], v[92:93], v[218:219], v[222:223]
	v_pk_fma_f32 v[224:225], v[94:95], v[220:221], v[224:225]
	v_pk_add_f32 v[222:223], v[222:223], v[224:225]
	s_nop 0
	v_add_f32_e32 v232, v222, v223
	v_cvt_pk_f32_fp8_e32 v[214:215], v204
	v_cvt_pk_f32_fp8_sdwa v[216:217], v204 src0_sel:WORD_1
	v_cvt_pk_f32_fp8_e32 v[218:219], v205
	v_cvt_pk_f32_fp8_sdwa v[220:221], v205 src0_sel:WORD_1
	v_pk_mul_f32 v[222:223], v[80:81], v[214:215]
	v_pk_mul_f32 v[224:225], v[82:83], v[216:217]
	v_cvt_pk_f32_fp8_e32 v[214:215], v206
	v_cvt_pk_f32_fp8_sdwa v[216:217], v206 src0_sel:WORD_1
	v_pk_fma_f32 v[222:223], v[84:85], v[218:219], v[222:223]
	v_pk_fma_f32 v[224:225], v[86:87], v[220:221], v[224:225]
	v_cvt_pk_f32_fp8_e32 v[218:219], v207
	v_cvt_pk_f32_fp8_sdwa v[220:221], v207 src0_sel:WORD_1
	v_pk_fma_f32 v[222:223], v[88:89], v[214:215], v[222:223]
	v_pk_fma_f32 v[224:225], v[90:91], v[216:217], v[224:225]
	v_pk_fma_f32 v[222:223], v[92:93], v[218:219], v[222:223]
	v_pk_fma_f32 v[224:225], v[94:95], v[220:221], v[224:225]
	v_pk_add_f32 v[222:223], v[222:223], v[224:225]
	s_nop 0
	v_add_f32_e32 v233, v222, v223
	v_permlane32_swap_b32_e32 v226, v230
	v_permlane32_swap_b32_e32 v227, v231
	v_permlane32_swap_b32_e32 v228, v232
	v_permlane32_swap_b32_e32 v229, v233
	v_add_f32_e32 v226, v226, v230
	v_add_f32_e32 v228, v228, v232
	v_add_f32_e32 v227, v227, v231
	v_add_f32_e32 v229, v229, v233
	s_nop 1
	v_permlane16_swap_b32_e32 v226, v228
; template <bool STORE>
; DI void peer_item(const Params& p, int item, char* smem) {
;     ...
; #pragma unroll
;       for (int u = 0; u < 8; ++u) {
;         int e = e_s[tl * 128 + k + u];
;         uq[u] = *(const u32x4*)(U8 + (size_t)e * 1024 + lane * 16);
;       }
;       float part[8];
; #pragma unroll
;       for (int u = 0; u < 8; ++u) {
;         float d = 0.f;
; #pragma unroll
;         for (int i = 0; i < 4; ++i) {
;           f32x2_t lo = __builtin_amdgcn_cvt_pk_f32_fp8((int)uq[u][i], false);
;           f32x2_t hi = __builtin_amdgcn_cvt_pk_f32_fp8((int)uq[u][i], true);
;           d += xf[4 * i] * lo.x + xf[4 * i + 1] * lo.y + xf[4 * i + 2] * hi.x + xf[4 * i + 3] * hi.y;
;         }
;         part[u] = d;
;       }
;       float q4[4], r2[2], h;
; #pragma unroll
;       for (int j = 0; j < 4; ++j) {
;         float mine = b5 ? part[j + 4] : part[j];
;         float other = b5 ? part[j] : part[j + 4];
;         q4[j] = mine + __shfl_xor(other, 32);
;       }
; #pragma unroll
;       for (int j = 0; j < 2; ++j) {
;         float mine = b4 ? q4[j + 2] : q4[j];
;         float other = b4 ? q4[j] : q4[j + 2];
;         r2[j] = mine + __shfl_xor(other, 16);
;       }
;       {
;         float mine = b3 ? r2[1] : r2[0];
;         float other = b3 ? r2[0] : r2[1];
;         h = mine + __shfl_xor(other, 8);
;       }
;       h += __shfl_xor(h, 4);
;       h += __shfl_xor(h, 2);
;       h += __shfl_xor(h, 1);
	v_permlane16_swap_b32_e32 v227, v229
	v_add_f32_e32 v226, v226, v228
	v_add_f32_e32 v227, v227, v229
	s_nop 0
	v_cndmask_b32_e64 v230, v226, v227, s[24:25]
	v_cndmask_b32_e64 v231, v227, v226, s[24:25]
	s_nop 1
	v_add_f32_dpp v232, v231, v230 row_ror:8 row_mask:0xf bank_mask:0xf
	s_nop 1
	v_add_f32_dpp v233, v232, v232 quad_perm:[1,0,3,2] row_mask:0xf bank_mask:0xf
	s_nop 1
	v_add_f32_dpp v232, v233, v233 quad_perm:[2,3,0,1] row_mask:0xf bank_mask:0xf
	s_nop 1
	v_add_f32_dpp v233, v232, v232 row_half_mirror row_mask:0xf bank_mask:0xf
	ds_write_b32 v235, v233 offset:35328
	v_readlane_b32 s48, v142, s72
	v_readlane_b32 s49, v142, s73
	v_readlane_b32 s50, v142, s74
	v_readlane_b32 s51, v142, s75
	v_readlane_b32 s52, v142, s76
	v_readlane_b32 s53, v142, s77
	v_readlane_b32 s54, v142, s78
	v_readlane_b32 s55, v142, s79
	s_add_u32 s32, s0, s48
	s_addc_u32 s33, s1, 0
	s_add_u32 s34, s0, s49
	s_addc_u32 s35, s1, 0
	s_add_u32 s36, s0, s50
	s_addc_u32 s37, s1, 0
	s_add_u32 s38, s0, s51
	s_addc_u32 s39, s1, 0
	s_add_u32 s40, s0, s52
	s_addc_u32 s41, s1, 0
	s_add_u32 s42, s0, s53
	s_addc_u32 s43, s1, 0
	s_add_u32 s44, s0, s54
	s_addc_u32 s45, s1, 0
	s_add_u32 s46, s0, s55
	s_addc_u32 s47, s1, 0
	global_load_dwordx4 v[176:179], v234, s[32:33]
	global_load_dwordx4 v[180:183], v234, s[34:35]
	global_load_dwordx4 v[184:187], v234, s[36:37]
	global_load_dwordx4 v[188:191], v234, s[38:39]
	global_load_dwordx4 v[192:195], v234, s[40:41]
	global_load_dwordx4 v[196:199], v234, s[42:43]
	global_load_dwordx4 v[200:203], v234, s[44:45]
	global_load_dwordx4 v[204:207], v234, s[46:47]
	s_waitcnt vmcnt(8)
	v_cvt_pk_f32_fp8_e32 v[214:215], v144
	v_cvt_pk_f32_fp8_sdwa v[216:217], v144 src0_sel:WORD_1
	v_cvt_pk_f32_fp8_e32 v[218:219], v145
	v_cvt_pk_f32_fp8_sdwa v[220:221], v145 src0_sel:WORD_1
	v_pk_mul_f32 v[222:223], v[96:97], v[214:215]
	v_pk_mul_f32 v[224:225], v[98:99], v[216:217]
	v_cvt_pk_f32_fp8_e32 v[214:215], v146
	v_cvt_pk_f32_fp8_sdwa v[216:217], v146 src0_sel:WORD_1
	v_pk_fma_f32 v[222:223], v[100:101], v[218:219], v[222:223]
	v_pk_fma_f32 v[224:225], v[102:103], v[220:221], v[224:225]
	v_cvt_pk_f32_fp8_e32 v[218:219], v147
	v_cvt_pk_f32_fp8_sdwa v[220:221], v147 src0_sel:WORD_1
	v_pk_fma_f32 v[222:223], v[104:105], v[214:215], v[222:223]
	v_pk_fma_f32 v[224:225], v[106:107], v[216:217], v[224:225]
	v_pk_fma_f32 v[222:223], v[108:109], v[218:219], v[222:223]
	v_pk_fma_f32 v[224:225], v[110:111], v[220:221], v[224:225]
	v_pk_add_f32 v[222:223], v[222:223], v[224:225]
	s_nop 0
	v_add_f32_e32 v226, v222, v223
	v_cvt_pk_f32_fp8_e32 v[214:215], v148
	v_cvt_pk_f32_fp8_sdwa v[216:217], v148 src0_sel:WORD_1
	v_cvt_pk_f32_fp8_e32 v[218:219], v149
	v_cvt_pk_f32_fp8_sdwa v[220:221], v149 src0_sel:WORD_1
	v_pk_mul_f32 v[222:223], v[96:97], v[214:215]
	v_pk_mul_f32 v[224:225], v[98:99], v[216:217]
	v_cvt_pk_f32_fp8_e32 v[214:215], v150
	v_cvt_pk_f32_fp8_sdwa v[216:217], v150 src0_sel:WORD_1
	v_pk_fma_f32 v[222:223], v[100:101], v[218:219], v[222:223]
	v_pk_fma_f32 v[224:225], v[102:103], v[220:221], v[224:225]
	v_cvt_pk_f32_fp8_e32 v[218:219], v151
	v_cvt_pk_f32_fp8_sdwa v[220:221], v151 src0_sel:WORD_1
	v_pk_fma_f32 v[222:223], v[104:105], v[214:215], v[222:223]
	v_pk_fma_f32 v[224:225], v[106:107], v[216:217], v[224:225]
	v_pk_fma_f32 v[222:223], v[108:109], v[218:219], v[222:223]
	v_pk_fma_f32 v[224:225], v[110:111], v[220:221], v[224:225]
	v_pk_add_f32 v[222:223], v[222:223], v[224:225]
	s_nop 0
	v_add_f32_e32 v227, v222, v223
	v_cvt_pk_f32_fp8_e32 v[214:215], v152
	v_cvt_pk_f32_fp8_sdwa v[216:217], v152 src0_sel:WORD_1
	v_cvt_pk_f32_fp8_e32 v[218:219], v153
	v_cvt_pk_f32_fp8_sdwa v[220:221], v153 src0_sel:WORD_1
	v_pk_mul_f32 v[222:223], v[96:97], v[214:215]
	v_pk_mul_f32 v[224:225], v[98:99], v[216:217]
	v_cvt_pk_f32_fp8_e32 v[214:215], v154
	v_cvt_pk_f32_fp8_sdwa v[216:217], v154 src0_sel:WORD_1
	v_pk_fma_f32 v[222:223], v[100:101], v[218:219], v[222:223]
	v_pk_fma_f32 v[224:225], v[102:103], v[220:221], v[224:225]
	v_cvt_pk_f32_fp8_e32 v[218:219], v155
	v_cvt_pk_f32_fp8_sdwa v[220:221], v155 src0_sel:WORD_1
	v_pk_fma_f32 v[222:223], v[104:105], v[214:215], v[222:223]
	v_pk_fma_f32 v[224:225], v[106:107], v[216:217], v[224:225]
	v_pk_fma_f32 v[222:223], v[108:109], v[218:219], v[222:223]
	v_pk_fma_f32 v[224:225], v[110:111], v[220:221], v[224:225]
	v_pk_add_f32 v[222:223], v[222:223], v[224:225]
	s_nop 0
	v_add_f32_e32 v228, v222, v223
	v_cvt_pk_f32_fp8_e32 v[214:215], v156
	v_cvt_pk_f32_fp8_sdwa v[216:217], v156 src0_sel:WORD_1
	v_cvt_pk_f32_fp8_e32 v[218:219], v157
	v_cvt_pk_f32_fp8_sdwa v[220:221], v157 src0_sel:WORD_1
	v_pk_mul_f32 v[222:223], v[96:97], v[214:215]
	v_pk_mul_f32 v[224:225], v[98:99], v[216:217]
	v_cvt_pk_f32_fp8_e32 v[214:215], v158
	v_cvt_pk_f32_fp8_sdwa v[216:217], v158 src0_sel:WORD_1
	v_pk_fma_f32 v[222:223], v[100:101], v[218:219], v[222:223]
	v_pk_fma_f32 v[224:225], v[102:103], v[220:221], v[224:225]
	v_cvt_pk_f32_fp8_e32 v[218:219], v159
	v_cvt_pk_f32_fp8_sdwa v[220:221], v159 src0_sel:WORD_1
	v_pk_fma_f32 v[222:223], v[104:105], v[214:215], v[222:223]
	v_pk_fma_f32 v[224:225], v[106:107], v[216:217], v[224:225]
	v_pk_fma_f32 v[222:223], v[108:109], v[218:219], v[222:223]
	v_pk_fma_f32 v[224:225], v[110:111], v[220:221], v[224:225]
	v_pk_add_f32 v[222:223], v[222:223], v[224:225]
	s_nop 0
	v_add_f32_e32 v229, v222, v223
	v_cvt_pk_f32_fp8_e32 v[214:215], v160
	v_cvt_pk_f32_fp8_sdwa v[216:217], v160 src0_sel:WORD_1
	v_cvt_pk_f32_fp8_e32 v[218:219], v161
	v_cvt_pk_f32_fp8_sdwa v[220:221], v161 src0_sel:WORD_1
	v_pk_mul_f32 v[222:223], v[96:97], v[214:215]
	v_pk_mul_f32 v[224:225], v[98:99], v[216:217]
	v_cvt_pk_f32_fp8_e32 v[214:215], v162
; template <bool STORE>
; DI void peer_item(const Params& p, int item, char* smem) {
;     ...
; #pragma unroll
;       for (int u = 0; u < 8; ++u) {
;         int e = e_s[tl * 128 + k + u];
;         uq[u] = *(const u32x4*)(U8 + (size_t)e * 1024 + lane * 16);
;       }
;       float part[8];
; #pragma unroll
;       for (int u = 0; u < 8; ++u) {
;         float d = 0.f;
; #pragma unroll
;         for (int i = 0; i < 4; ++i) {
;           f32x2_t lo = __builtin_amdgcn_cvt_pk_f32_fp8((int)uq[u][i], false);
;           f32x2_t hi = __builtin_amdgcn_cvt_pk_f32_fp8((int)uq[u][i], true);
;           d += xf[4 * i] * lo.x + xf[4 * i + 1] * lo.y + xf[4 * i + 2] * hi.x + xf[4 * i + 3] * hi.y;
;         }
;         part[u] = d;
;       }
;       float q4[4], r2[2], h;
; #pragma unroll
;       for (int j = 0; j < 4; ++j) {
;         float mine = b5 ? part[j + 4] : part[j];
;         float other = b5 ? part[j] : part[j + 4];
;         q4[j] = mine + __shfl_xor(other, 32);
;       }
; #pragma unroll
;       for (int j = 0; j < 2; ++j) {
;         float mine = b4 ? q4[j + 2] : q4[j];
;         float other = b4 ? q4[j] : q4[j + 2];
;         r2[j] = mine + __shfl_xor(other, 16);
;       }
;       {
;         float mine = b3 ? r2[1] : r2[0];
;         float other = b3 ? r2[0] : r2[1];
;         h = mine + __shfl_xor(other, 8);
;       }
;       h += __shfl_xor(h, 4);
;       h += __shfl_xor(h, 2);
;       h += __shfl_xor(h, 1);
	v_cvt_pk_f32_fp8_sdwa v[216:217], v162 src0_sel:WORD_1
	v_pk_fma_f32 v[222:223], v[100:101], v[218:219], v[222:223]
	v_pk_fma_f32 v[224:225], v[102:103], v[220:221], v[224:225]
	v_cvt_pk_f32_fp8_e32 v[218:219], v163
	v_cvt_pk_f32_fp8_sdwa v[220:221], v163 src0_sel:WORD_1
	v_pk_fma_f32 v[222:223], v[104:105], v[214:215], v[222:223]
	v_pk_fma_f32 v[224:225], v[106:107], v[216:217], v[224:225]
	v_pk_fma_f32 v[222:223], v[108:109], v[218:219], v[222:223]
	v_pk_fma_f32 v[224:225], v[110:111], v[220:221], v[224:225]
	v_pk_add_f32 v[222:223], v[222:223], v[224:225]
	s_nop 0
	v_add_f32_e32 v230, v222, v223
	v_cvt_pk_f32_fp8_e32 v[214:215], v164
	v_cvt_pk_f32_fp8_sdwa v[216:217], v164 src0_sel:WORD_1
	v_cvt_pk_f32_fp8_e32 v[218:219], v165
	v_cvt_pk_f32_fp8_sdwa v[220:221], v165 src0_sel:WORD_1
	v_pk_mul_f32 v[222:223], v[96:97], v[214:215]
	v_pk_mul_f32 v[224:225], v[98:99], v[216:217]
	v_cvt_pk_f32_fp8_e32 v[214:215], v166
	v_cvt_pk_f32_fp8_sdwa v[216:217], v166 src0_sel:WORD_1
	v_pk_fma_f32 v[222:223], v[100:101], v[218:219], v[222:223]
	v_pk_fma_f32 v[224:225], v[102:103], v[220:221], v[224:225]
	v_cvt_pk_f32_fp8_e32 v[218:219], v167
	v_cvt_pk_f32_fp8_sdwa v[220:221], v167 src0_sel:WORD_1
	v_pk_fma_f32 v[222:223], v[104:105], v[214:215], v[222:223]
	v_pk_fma_f32 v[224:225], v[106:107], v[216:217], v[224:225]
	v_pk_fma_f32 v[222:223], v[108:109], v[218:219], v[222:223]
	v_pk_fma_f32 v[224:225], v[110:111], v[220:221], v[224:225]
	v_pk_add_f32 v[222:223], v[222:223], v[224:225]
	s_nop 0
	v_add_f32_e32 v231, v222, v223
	v_cvt_pk_f32_fp8_e32 v[214:215], v168
	v_cvt_pk_f32_fp8_sdwa v[216:217], v168 src0_sel:WORD_1
	v_cvt_pk_f32_fp8_e32 v[218:219], v169
	v_cvt_pk_f32_fp8_sdwa v[220:221], v169 src0_sel:WORD_1
	v_pk_mul_f32 v[222:223], v[96:97], v[214:215]
	v_pk_mul_f32 v[224:225], v[98:99], v[216:217]
	v_cvt_pk_f32_fp8_e32 v[214:215], v170
	v_cvt_pk_f32_fp8_sdwa v[216:217], v170 src0_sel:WORD_1
	v_pk_fma_f32 v[222:223], v[100:101], v[218:219], v[222:223]
	v_pk_fma_f32 v[224:225], v[102:103], v[220:221], v[224:225]
	v_cvt_pk_f32_fp8_e32 v[218:219], v171
	v_cvt_pk_f32_fp8_sdwa v[220:221], v171 src0_sel:WORD_1
	v_pk_fma_f32 v[222:223], v[104:105], v[214:215], v[222:223]
	v_pk_fma_f32 v[224:225], v[106:107], v[216:217], v[224:225]
	v_pk_fma_f32 v[222:223], v[108:109], v[218:219], v[222:223]
	v_pk_fma_f32 v[224:225], v[110:111], v[220:221], v[224:225]
	v_pk_add_f32 v[222:223], v[222:223], v[224:225]
	s_nop 0
	v_add_f32_e32 v232, v222, v223
	v_cvt_pk_f32_fp8_e32 v[214:215], v172
	v_cvt_pk_f32_fp8_sdwa v[216:217], v172 src0_sel:WORD_1
	v_cvt_pk_f32_fp8_e32 v[218:219], v173
	v_cvt_pk_f32_fp8_sdwa v[220:221], v173 src0_sel:WORD_1
	v_pk_mul_f32 v[222:223], v[96:97], v[214:215]
	v_pk_mul_f32 v[224:225], v[98:99], v[216:217]
	v_cvt_pk_f32_fp8_e32 v[214:215], v174
	v_cvt_pk_f32_fp8_sdwa v[216:217], v174 src0_sel:WORD_1
	v_pk_fma_f32 v[222:223], v[100:101], v[218:219], v[222:223]
	v_pk_fma_f32 v[224:225], v[102:103], v[220:221], v[224:225]
	v_cvt_pk_f32_fp8_e32 v[218:219], v175
	v_cvt_pk_f32_fp8_sdwa v[220:221], v175 src0_sel:WORD_1
	v_pk_fma_f32 v[222:223], v[104:105], v[214:215], v[222:223]
	v_pk_fma_f32 v[224:225], v[106:107], v[216:217], v[224:225]
	v_pk_fma_f32 v[222:223], v[108:109], v[218:219], v[222:223]
	v_pk_fma_f32 v[224:225], v[110:111], v[220:221], v[224:225]
	v_pk_add_f32 v[222:223], v[222:223], v[224:225]
	s_nop 0
	v_add_f32_e32 v233, v222, v223
	v_permlane32_swap_b32_e32 v226, v230
	v_permlane32_swap_b32_e32 v227, v231
	v_permlane32_swap_b32_e32 v228, v232
	v_permlane32_swap_b32_e32 v229, v233
	v_add_f32_e32 v226, v226, v230
	v_add_f32_e32 v228, v228, v232
	v_add_f32_e32 v227, v227, v231
	v_add_f32_e32 v229, v229, v233
	s_nop 1
	v_permlane16_swap_b32_e32 v226, v228
	v_permlane16_swap_b32_e32 v227, v229
	v_add_f32_e32 v226, v226, v228
	v_add_f32_e32 v227, v227, v229
	s_nop 0
	v_cndmask_b32_e64 v230, v226, v227, s[24:25]
	v_cndmask_b32_e64 v231, v227, v226, s[24:25]
	s_nop 1
	v_add_f32_dpp v232, v231, v230 row_ror:8 row_mask:0xf bank_mask:0xf
	s_nop 1
	v_add_f32_dpp v233, v232, v232 quad_perm:[1,0,3,2] row_mask:0xf bank_mask:0xf
	s_nop 1
	v_add_f32_dpp v232, v233, v233 quad_perm:[2,3,0,1] row_mask:0xf bank_mask:0xf
	s_nop 1
	v_add_f32_dpp v233, v232, v232 row_half_mirror row_mask:0xf bank_mask:0xf
	ds_write_b32 v235, v233 offset:35840
	v_readlane_b32 s48, v129, s72
	v_readlane_b32 s49, v129, s73
	v_readlane_b32 s50, v129, s74
	v_readlane_b32 s51, v129, s75
	v_readlane_b32 s52, v129, s76
	v_readlane_b32 s53, v129, s77
	v_readlane_b32 s54, v129, s78
	v_readlane_b32 s55, v129, s79
	s_add_u32 s32, s0, s48
	s_addc_u32 s33, s1, 0
	s_add_u32 s34, s0, s49
	s_addc_u32 s35, s1, 0
	s_add_u32 s36, s0, s50
	s_addc_u32 s37, s1, 0
	s_add_u32 s38, s0, s51
	s_addc_u32 s39, s1, 0
	s_add_u32 s40, s0, s52
	s_addc_u32 s41, s1, 0
	s_add_u32 s42, s0, s53
	s_addc_u32 s43, s1, 0
	s_add_u32 s44, s0, s54
	s_addc_u32 s45, s1, 0
	s_add_u32 s46, s0, s55
	s_addc_u32 s47, s1, 0
	global_load_dwordx4 v[144:147], v234, s[32:33]
	global_load_dwordx4 v[148:151], v234, s[34:35]
	global_load_dwordx4 v[152:155], v234, s[36:37]
	global_load_dwordx4 v[156:159], v234, s[38:39]
	global_load_dwordx4 v[160:163], v234, s[40:41]
	global_load_dwordx4 v[164:167], v234, s[42:43]
	global_load_dwordx4 v[168:171], v234, s[44:45]
	global_load_dwordx4 v[172:175], v234, s[46:47]
	s_waitcnt vmcnt(8)
; template <bool STORE>
; DI void peer_item(const Params& p, int item, char* smem) {
;     ...
; #pragma unroll
;       for (int u = 0; u < 8; ++u) {
;         float d = 0.f;
; #pragma unroll
;         for (int i = 0; i < 4; ++i) {
;           f32x2_t lo = __builtin_amdgcn_cvt_pk_f32_fp8((int)uq[u][i], false);
;           f32x2_t hi = __builtin_amdgcn_cvt_pk_f32_fp8((int)uq[u][i], true);
;           d += xf[4 * i] * lo.x + xf[4 * i + 1] * lo.y + xf[4 * i + 2] * hi.x + xf[4 * i + 3] * hi.y;
;         }
;         part[u] = d;
;       }
	v_cvt_pk_f32_fp8_e32 v[214:215], v176
	v_cvt_pk_f32_fp8_sdwa v[216:217], v176 src0_sel:WORD_1
	v_cvt_pk_f32_fp8_e32 v[218:219], v177
	v_cvt_pk_f32_fp8_sdwa v[220:221], v177 src0_sel:WORD_1
	v_pk_mul_f32 v[222:223], v[112:113], v[214:215]
	v_pk_mul_f32 v[224:225], v[114:115], v[216:217]
	v_cvt_pk_f32_fp8_e32 v[214:215], v178
	v_cvt_pk_f32_fp8_sdwa v[216:217], v178 src0_sel:WORD_1
	v_pk_fma_f32 v[222:223], v[116:117], v[218:219], v[222:223]
	v_pk_fma_f32 v[224:225], v[118:119], v[220:221], v[224:225]
	v_cvt_pk_f32_fp8_e32 v[218:219], v179
	v_cvt_pk_f32_fp8_sdwa v[220:221], v179 src0_sel:WORD_1
	v_pk_fma_f32 v[222:223], v[120:121], v[214:215], v[222:223]
	v_pk_fma_f32 v[224:225], v[122:123], v[216:217], v[224:225]
	v_pk_fma_f32 v[222:223], v[124:125], v[218:219], v[222:223]
	v_pk_fma_f32 v[224:225], v[126:127], v[220:221], v[224:225]
	v_pk_add_f32 v[222:223], v[222:223], v[224:225]
	s_nop 0
	v_add_f32_e32 v226, v222, v223
	v_cvt_pk_f32_fp8_e32 v[214:215], v180
	v_cvt_pk_f32_fp8_sdwa v[216:217], v180 src0_sel:WORD_1
	v_cvt_pk_f32_fp8_e32 v[218:219], v181
	v_cvt_pk_f32_fp8_sdwa v[220:221], v181 src0_sel:WORD_1
	v_pk_mul_f32 v[222:223], v[112:113], v[214:215]
	v_pk_mul_f32 v[224:225], v[114:115], v[216:217]
	v_cvt_pk_f32_fp8_e32 v[214:215], v182
	v_cvt_pk_f32_fp8_sdwa v[216:217], v182 src0_sel:WORD_1
	v_pk_fma_f32 v[222:223], v[116:117], v[218:219], v[222:223]
	v_pk_fma_f32 v[224:225], v[118:119], v[220:221], v[224:225]
	v_cvt_pk_f32_fp8_e32 v[218:219], v183
	v_cvt_pk_f32_fp8_sdwa v[220:221], v183 src0_sel:WORD_1
	v_pk_fma_f32 v[222:223], v[120:121], v[214:215], v[222:223]
	v_pk_fma_f32 v[224:225], v[122:123], v[216:217], v[224:225]
	v_pk_fma_f32 v[222:223], v[124:125], v[218:219], v[222:223]
	v_pk_fma_f32 v[224:225], v[126:127], v[220:221], v[224:225]
	v_pk_add_f32 v[222:223], v[222:223], v[224:225]
	s_nop 0
	v_add_f32_e32 v227, v222, v223
	v_cvt_pk_f32_fp8_e32 v[214:215], v184
	v_cvt_pk_f32_fp8_sdwa v[216:217], v184 src0_sel:WORD_1
	v_cvt_pk_f32_fp8_e32 v[218:219], v185
	v_cvt_pk_f32_fp8_sdwa v[220:221], v185 src0_sel:WORD_1
	v_pk_mul_f32 v[222:223], v[112:113], v[214:215]
	v_pk_mul_f32 v[224:225], v[114:115], v[216:217]
	v_cvt_pk_f32_fp8_e32 v[214:215], v186
	v_cvt_pk_f32_fp8_sdwa v[216:217], v186 src0_sel:WORD_1
	v_pk_fma_f32 v[222:223], v[116:117], v[218:219], v[222:223]
	v_pk_fma_f32 v[224:225], v[118:119], v[220:221], v[224:225]
	v_cvt_pk_f32_fp8_e32 v[218:219], v187
	v_cvt_pk_f32_fp8_sdwa v[220:221], v187 src0_sel:WORD_1
	v_pk_fma_f32 v[222:223], v[120:121], v[214:215], v[222:223]
	v_pk_fma_f32 v[224:225], v[122:123], v[216:217], v[224:225]
	v_pk_fma_f32 v[222:223], v[124:125], v[218:219], v[222:223]
	v_pk_fma_f32 v[224:225], v[126:127], v[220:221], v[224:225]
	v_pk_add_f32 v[222:223], v[222:223], v[224:225]
	s_nop 0
	v_add_f32_e32 v228, v222, v223
	v_cvt_pk_f32_fp8_e32 v[214:215], v188
	v_cvt_pk_f32_fp8_sdwa v[216:217], v188 src0_sel:WORD_1
	v_cvt_pk_f32_fp8_e32 v[218:219], v189
	v_cvt_pk_f32_fp8_sdwa v[220:221], v189 src0_sel:WORD_1
	v_pk_mul_f32 v[222:223], v[112:113], v[214:215]
	v_pk_mul_f32 v[224:225], v[114:115], v[216:217]
	v_cvt_pk_f32_fp8_e32 v[214:215], v190
	v_cvt_pk_f32_fp8_sdwa v[216:217], v190 src0_sel:WORD_1
	v_pk_fma_f32 v[222:223], v[116:117], v[218:219], v[222:223]
	v_pk_fma_f32 v[224:225], v[118:119], v[220:221], v[224:225]
	v_cvt_pk_f32_fp8_e32 v[218:219], v191
	v_cvt_pk_f32_fp8_sdwa v[220:221], v191 src0_sel:WORD_1
	v_pk_fma_f32 v[222:223], v[120:121], v[214:215], v[222:223]
	v_pk_fma_f32 v[224:225], v[122:123], v[216:217], v[224:225]
	v_pk_fma_f32 v[222:223], v[124:125], v[218:219], v[222:223]
	v_pk_fma_f32 v[224:225], v[126:127], v[220:221], v[224:225]
	v_pk_add_f32 v[222:223], v[222:223], v[224:225]
	s_nop 0
	v_add_f32_e32 v229, v222, v223
	v_cvt_pk_f32_fp8_e32 v[214:215], v192
	v_cvt_pk_f32_fp8_sdwa v[216:217], v192 src0_sel:WORD_1
	v_cvt_pk_f32_fp8_e32 v[218:219], v193
	v_cvt_pk_f32_fp8_sdwa v[220:221], v193 src0_sel:WORD_1
	v_pk_mul_f32 v[222:223], v[112:113], v[214:215]
	v_pk_mul_f32 v[224:225], v[114:115], v[216:217]
	v_cvt_pk_f32_fp8_e32 v[214:215], v194
	v_cvt_pk_f32_fp8_sdwa v[216:217], v194 src0_sel:WORD_1
	v_pk_fma_f32 v[222:223], v[116:117], v[218:219], v[222:223]
	v_pk_fma_f32 v[224:225], v[118:119], v[220:221], v[224:225]
	v_cvt_pk_f32_fp8_e32 v[218:219], v195
	v_cvt_pk_f32_fp8_sdwa v[220:221], v195 src0_sel:WORD_1
	v_pk_fma_f32 v[222:223], v[120:121], v[214:215], v[222:223]
	v_pk_fma_f32 v[224:225], v[122:123], v[216:217], v[224:225]
	v_pk_fma_f32 v[222:223], v[124:125], v[218:219], v[222:223]
	v_pk_fma_f32 v[224:225], v[126:127], v[220:221], v[224:225]
	v_pk_add_f32 v[222:223], v[222:223], v[224:225]
	s_nop 0
	v_add_f32_e32 v230, v222, v223
	v_cvt_pk_f32_fp8_e32 v[214:215], v196
	v_cvt_pk_f32_fp8_sdwa v[216:217], v196 src0_sel:WORD_1
	v_cvt_pk_f32_fp8_e32 v[218:219], v197
	v_cvt_pk_f32_fp8_sdwa v[220:221], v197 src0_sel:WORD_1
	v_pk_mul_f32 v[222:223], v[112:113], v[214:215]
	v_pk_mul_f32 v[224:225], v[114:115], v[216:217]
	v_cvt_pk_f32_fp8_e32 v[214:215], v198
	v_cvt_pk_f32_fp8_sdwa v[216:217], v198 src0_sel:WORD_1
	v_pk_fma_f32 v[222:223], v[116:117], v[218:219], v[222:223]
	v_pk_fma_f32 v[224:225], v[118:119], v[220:221], v[224:225]
	v_cvt_pk_f32_fp8_e32 v[218:219], v199
	v_cvt_pk_f32_fp8_sdwa v[220:221], v199 src0_sel:WORD_1
	v_pk_fma_f32 v[222:223], v[120:121], v[214:215], v[222:223]
	v_pk_fma_f32 v[224:225], v[122:123], v[216:217], v[224:225]
	v_pk_fma_f32 v[222:223], v[124:125], v[218:219], v[222:223]
	v_pk_fma_f32 v[224:225], v[126:127], v[220:221], v[224:225]
	v_pk_add_f32 v[222:223], v[222:223], v[224:225]
	s_nop 0
	v_add_f32_e32 v231, v222, v223
	v_cvt_pk_f32_fp8_e32 v[214:215], v200
; template <bool STORE>
; DI void peer_item(const Params& p, int item, char* smem) {
;     ...
; #pragma unroll
;       for (int u = 0; u < 8; ++u) {
;         int e = e_s[tl * 128 + k + u];
;         uq[u] = *(const u32x4*)(U8 + (size_t)e * 1024 + lane * 16);
;       }
;       float part[8];
; #pragma unroll
;       for (int u = 0; u < 8; ++u) {
;         float d = 0.f;
; #pragma unroll
;         for (int i = 0; i < 4; ++i) {
;           f32x2_t lo = __builtin_amdgcn_cvt_pk_f32_fp8((int)uq[u][i], false);
;           f32x2_t hi = __builtin_amdgcn_cvt_pk_f32_fp8((int)uq[u][i], true);
;           d += xf[4 * i] * lo.x + xf[4 * i + 1] * lo.y + xf[4 * i + 2] * hi.x + xf[4 * i + 3] * hi.y;
;         }
;         part[u] = d;
;       }
;       float q4[4], r2[2], h;
; #pragma unroll
;       for (int j = 0; j < 4; ++j) {
;         float mine = b5 ? part[j + 4] : part[j];
;         float other = b5 ? part[j] : part[j + 4];
;         q4[j] = mine + __shfl_xor(other, 32);
;       }
; #pragma unroll
;       for (int j = 0; j < 2; ++j) {
;         float mine = b4 ? q4[j + 2] : q4[j];
;         float other = b4 ? q4[j] : q4[j + 2];
;         r2[j] = mine + __shfl_xor(other, 16);
;       }
;       {
;         float mine = b3 ? r2[1] : r2[0];
;         float other = b3 ? r2[0] : r2[1];
;         h = mine + __shfl_xor(other, 8);
;       }
;       h += __shfl_xor(h, 4);
;       h += __shfl_xor(h, 2);
;       h += __shfl_xor(h, 1);
	v_cvt_pk_f32_fp8_sdwa v[216:217], v200 src0_sel:WORD_1
	v_cvt_pk_f32_fp8_e32 v[218:219], v201
	v_cvt_pk_f32_fp8_sdwa v[220:221], v201 src0_sel:WORD_1
	v_pk_mul_f32 v[222:223], v[112:113], v[214:215]
	v_pk_mul_f32 v[224:225], v[114:115], v[216:217]
	v_cvt_pk_f32_fp8_e32 v[214:215], v202
	v_cvt_pk_f32_fp8_sdwa v[216:217], v202 src0_sel:WORD_1
	v_pk_fma_f32 v[222:223], v[116:117], v[218:219], v[222:223]
	v_pk_fma_f32 v[224:225], v[118:119], v[220:221], v[224:225]
	v_cvt_pk_f32_fp8_e32 v[218:219], v203
	v_cvt_pk_f32_fp8_sdwa v[220:221], v203 src0_sel:WORD_1
	v_pk_fma_f32 v[222:223], v[120:121], v[214:215], v[222:223]
	v_pk_fma_f32 v[224:225], v[122:123], v[216:217], v[224:225]
	v_pk_fma_f32 v[222:223], v[124:125], v[218:219], v[222:223]
	v_pk_fma_f32 v[224:225], v[126:127], v[220:221], v[224:225]
	v_pk_add_f32 v[222:223], v[222:223], v[224:225]
	s_nop 0
	v_add_f32_e32 v232, v222, v223
	v_cvt_pk_f32_fp8_e32 v[214:215], v204
	v_cvt_pk_f32_fp8_sdwa v[216:217], v204 src0_sel:WORD_1
	v_cvt_pk_f32_fp8_e32 v[218:219], v205
	v_cvt_pk_f32_fp8_sdwa v[220:221], v205 src0_sel:WORD_1
	v_pk_mul_f32 v[222:223], v[112:113], v[214:215]
	v_pk_mul_f32 v[224:225], v[114:115], v[216:217]
	v_cvt_pk_f32_fp8_e32 v[214:215], v206
	v_cvt_pk_f32_fp8_sdwa v[216:217], v206 src0_sel:WORD_1
	v_pk_fma_f32 v[222:223], v[116:117], v[218:219], v[222:223]
	v_pk_fma_f32 v[224:225], v[118:119], v[220:221], v[224:225]
	v_cvt_pk_f32_fp8_e32 v[218:219], v207
	v_cvt_pk_f32_fp8_sdwa v[220:221], v207 src0_sel:WORD_1
	v_pk_fma_f32 v[222:223], v[120:121], v[214:215], v[222:223]
	v_pk_fma_f32 v[224:225], v[122:123], v[216:217], v[224:225]
	v_pk_fma_f32 v[222:223], v[124:125], v[218:219], v[222:223]
	v_pk_fma_f32 v[224:225], v[126:127], v[220:221], v[224:225]
	v_pk_add_f32 v[222:223], v[222:223], v[224:225]
	s_nop 0
	v_add_f32_e32 v233, v222, v223
	v_permlane32_swap_b32_e32 v226, v230
	v_permlane32_swap_b32_e32 v227, v231
	v_permlane32_swap_b32_e32 v228, v232
	v_permlane32_swap_b32_e32 v229, v233
	v_add_f32_e32 v226, v226, v230
	v_add_f32_e32 v228, v228, v232
	v_add_f32_e32 v227, v227, v231
	v_add_f32_e32 v229, v229, v233
	s_nop 1
	v_permlane16_swap_b32_e32 v226, v228
	v_permlane16_swap_b32_e32 v227, v229
	v_add_f32_e32 v226, v226, v228
	v_add_f32_e32 v227, v227, v229
	s_nop 0
	v_cndmask_b32_e64 v230, v226, v227, s[24:25]
	v_cndmask_b32_e64 v231, v227, v226, s[24:25]
	s_nop 1
	v_add_f32_dpp v232, v231, v230 row_ror:8 row_mask:0xf bank_mask:0xf
	s_nop 1
	v_add_f32_dpp v233, v232, v232 quad_perm:[1,0,3,2] row_mask:0xf bank_mask:0xf
	s_nop 1
	v_add_f32_dpp v232, v233, v233 quad_perm:[2,3,0,1] row_mask:0xf bank_mask:0xf
	s_nop 1
	v_add_f32_dpp v233, v232, v232 row_half_mirror row_mask:0xf bank_mask:0xf
	ds_write_b32 v235, v233 offset:36352
	v_readlane_b32 s48, v131, s72
	v_readlane_b32 s49, v131, s73
	v_readlane_b32 s50, v131, s74
	v_readlane_b32 s51, v131, s75
	v_readlane_b32 s52, v131, s76
	v_readlane_b32 s53, v131, s77
	v_readlane_b32 s54, v131, s78
	v_readlane_b32 s55, v131, s79
	s_add_u32 s32, s0, s48
	s_addc_u32 s33, s1, 0
	s_add_u32 s34, s0, s49
	s_addc_u32 s35, s1, 0
	s_add_u32 s36, s0, s50
	s_addc_u32 s37, s1, 0
	s_add_u32 s38, s0, s51
	s_addc_u32 s39, s1, 0
	s_add_u32 s40, s0, s52
	s_addc_u32 s41, s1, 0
	s_add_u32 s42, s0, s53
	s_addc_u32 s43, s1, 0
	s_add_u32 s44, s0, s54
	s_addc_u32 s45, s1, 0
	s_add_u32 s46, s0, s55
	s_addc_u32 s47, s1, 0
	global_load_dwordx4 v[176:179], v234, s[32:33]
	global_load_dwordx4 v[180:183], v234, s[34:35]
	global_load_dwordx4 v[184:187], v234, s[36:37]
	global_load_dwordx4 v[188:191], v234, s[38:39]
	global_load_dwordx4 v[192:195], v234, s[40:41]
	global_load_dwordx4 v[196:199], v234, s[42:43]
	global_load_dwordx4 v[200:203], v234, s[44:45]
	global_load_dwordx4 v[204:207], v234, s[46:47]
	s_waitcnt vmcnt(8)
	v_cvt_pk_f32_fp8_e32 v[214:215], v144
	v_cvt_pk_f32_fp8_sdwa v[216:217], v144 src0_sel:WORD_1
	v_cvt_pk_f32_fp8_e32 v[218:219], v145
	v_cvt_pk_f32_fp8_sdwa v[220:221], v145 src0_sel:WORD_1
	v_pk_mul_f32 v[222:223], v[0:1], v[214:215]
	v_pk_mul_f32 v[224:225], v[2:3], v[216:217]
	v_cvt_pk_f32_fp8_e32 v[214:215], v146
	v_cvt_pk_f32_fp8_sdwa v[216:217], v146 src0_sel:WORD_1
	v_pk_fma_f32 v[222:223], v[4:5], v[218:219], v[222:223]
	v_pk_fma_f32 v[224:225], v[6:7], v[220:221], v[224:225]
	v_cvt_pk_f32_fp8_e32 v[218:219], v147
	v_cvt_pk_f32_fp8_sdwa v[220:221], v147 src0_sel:WORD_1
	v_pk_fma_f32 v[222:223], v[8:9], v[214:215], v[222:223]
	v_pk_fma_f32 v[224:225], v[10:11], v[216:217], v[224:225]
	v_pk_fma_f32 v[222:223], v[12:13], v[218:219], v[222:223]
	v_pk_fma_f32 v[224:225], v[14:15], v[220:221], v[224:225]
	v_pk_add_f32 v[222:223], v[222:223], v[224:225]
	s_nop 0
	v_add_f32_e32 v226, v222, v223
	v_cvt_pk_f32_fp8_e32 v[214:215], v148
	v_cvt_pk_f32_fp8_sdwa v[216:217], v148 src0_sel:WORD_1
	v_cvt_pk_f32_fp8_e32 v[218:219], v149
	v_cvt_pk_f32_fp8_sdwa v[220:221], v149 src0_sel:WORD_1
	v_pk_mul_f32 v[222:223], v[0:1], v[214:215]
	v_pk_mul_f32 v[224:225], v[2:3], v[216:217]
	v_cvt_pk_f32_fp8_e32 v[214:215], v150
	v_cvt_pk_f32_fp8_sdwa v[216:217], v150 src0_sel:WORD_1
	v_pk_fma_f32 v[222:223], v[4:5], v[218:219], v[222:223]
	v_pk_fma_f32 v[224:225], v[6:7], v[220:221], v[224:225]
	v_cvt_pk_f32_fp8_e32 v[218:219], v151
	v_cvt_pk_f32_fp8_sdwa v[220:221], v151 src0_sel:WORD_1
	v_pk_fma_f32 v[222:223], v[8:9], v[214:215], v[222:223]
	v_pk_fma_f32 v[224:225], v[10:11], v[216:217], v[224:225]
	v_pk_fma_f32 v[222:223], v[12:13], v[218:219], v[222:223]
	v_pk_fma_f32 v[224:225], v[14:15], v[220:221], v[224:225]
	v_pk_add_f32 v[222:223], v[222:223], v[224:225]
	s_nop 0
	v_add_f32_e32 v227, v222, v223
	v_cvt_pk_f32_fp8_e32 v[214:215], v152
; template <bool STORE>
; DI void peer_item(const Params& p, int item, char* smem) {
;     ...
; #pragma unroll
;       for (int u = 0; u < 8; ++u) {
;         float d = 0.f;
; #pragma unroll
;         for (int i = 0; i < 4; ++i) {
;           f32x2_t lo = __builtin_amdgcn_cvt_pk_f32_fp8((int)uq[u][i], false);
;           f32x2_t hi = __builtin_amdgcn_cvt_pk_f32_fp8((int)uq[u][i], true);
;           d += xf[4 * i] * lo.x + xf[4 * i + 1] * lo.y + xf[4 * i + 2] * hi.x + xf[4 * i + 3] * hi.y;
;         }
;         part[u] = d;
;       }
;       float q4[4], r2[2], h;
; #pragma unroll
;       for (int j = 0; j < 4; ++j) {
;         float mine = b5 ? part[j + 4] : part[j];
;         float other = b5 ? part[j] : part[j + 4];
;         q4[j] = mine + __shfl_xor(other, 32);
;       }
; #pragma unroll
;       for (int j = 0; j < 2; ++j) {
;         float mine = b4 ? q4[j + 2] : q4[j];
;         float other = b4 ? q4[j] : q4[j + 2];
;         r2[j] = mine + __shfl_xor(other, 16);
;       }
;       {
;         float mine = b3 ? r2[1] : r2[0];
;         float other = b3 ? r2[0] : r2[1];
;         h = mine + __shfl_xor(other, 8);
;       }
;       h += __shfl_xor(h, 4);
;       h += __shfl_xor(h, 2);
;       h += __shfl_xor(h, 1);
	v_cvt_pk_f32_fp8_sdwa v[216:217], v152 src0_sel:WORD_1
	v_cvt_pk_f32_fp8_e32 v[218:219], v153
	v_cvt_pk_f32_fp8_sdwa v[220:221], v153 src0_sel:WORD_1
	v_pk_mul_f32 v[222:223], v[0:1], v[214:215]
	v_pk_mul_f32 v[224:225], v[2:3], v[216:217]
	v_cvt_pk_f32_fp8_e32 v[214:215], v154
	v_cvt_pk_f32_fp8_sdwa v[216:217], v154 src0_sel:WORD_1
	v_pk_fma_f32 v[222:223], v[4:5], v[218:219], v[222:223]
	v_pk_fma_f32 v[224:225], v[6:7], v[220:221], v[224:225]
	v_cvt_pk_f32_fp8_e32 v[218:219], v155
	v_cvt_pk_f32_fp8_sdwa v[220:221], v155 src0_sel:WORD_1
	v_pk_fma_f32 v[222:223], v[8:9], v[214:215], v[222:223]
	v_pk_fma_f32 v[224:225], v[10:11], v[216:217], v[224:225]
	v_pk_fma_f32 v[222:223], v[12:13], v[218:219], v[222:223]
	v_pk_fma_f32 v[224:225], v[14:15], v[220:221], v[224:225]
	v_pk_add_f32 v[222:223], v[222:223], v[224:225]
	s_nop 0
	v_add_f32_e32 v228, v222, v223
	v_cvt_pk_f32_fp8_e32 v[214:215], v156
	v_cvt_pk_f32_fp8_sdwa v[216:217], v156 src0_sel:WORD_1
	v_cvt_pk_f32_fp8_e32 v[218:219], v157
	v_cvt_pk_f32_fp8_sdwa v[220:221], v157 src0_sel:WORD_1
	v_pk_mul_f32 v[222:223], v[0:1], v[214:215]
	v_pk_mul_f32 v[224:225], v[2:3], v[216:217]
	v_cvt_pk_f32_fp8_e32 v[214:215], v158
	v_cvt_pk_f32_fp8_sdwa v[216:217], v158 src0_sel:WORD_1
	v_pk_fma_f32 v[222:223], v[4:5], v[218:219], v[222:223]
	v_pk_fma_f32 v[224:225], v[6:7], v[220:221], v[224:225]
	v_cvt_pk_f32_fp8_e32 v[218:219], v159
	v_cvt_pk_f32_fp8_sdwa v[220:221], v159 src0_sel:WORD_1
	v_pk_fma_f32 v[222:223], v[8:9], v[214:215], v[222:223]
	v_pk_fma_f32 v[224:225], v[10:11], v[216:217], v[224:225]
	v_pk_fma_f32 v[222:223], v[12:13], v[218:219], v[222:223]
	v_pk_fma_f32 v[224:225], v[14:15], v[220:221], v[224:225]
	v_pk_add_f32 v[222:223], v[222:223], v[224:225]
	s_nop 0
	v_add_f32_e32 v229, v222, v223
	v_cvt_pk_f32_fp8_e32 v[214:215], v160
	v_cvt_pk_f32_fp8_sdwa v[216:217], v160 src0_sel:WORD_1
	v_cvt_pk_f32_fp8_e32 v[218:219], v161
	v_cvt_pk_f32_fp8_sdwa v[220:221], v161 src0_sel:WORD_1
	v_pk_mul_f32 v[222:223], v[0:1], v[214:215]
	v_pk_mul_f32 v[224:225], v[2:3], v[216:217]
	v_cvt_pk_f32_fp8_e32 v[214:215], v162
	v_cvt_pk_f32_fp8_sdwa v[216:217], v162 src0_sel:WORD_1
	v_pk_fma_f32 v[222:223], v[4:5], v[218:219], v[222:223]
	v_pk_fma_f32 v[224:225], v[6:7], v[220:221], v[224:225]
	v_cvt_pk_f32_fp8_e32 v[218:219], v163
	v_cvt_pk_f32_fp8_sdwa v[220:221], v163 src0_sel:WORD_1
	v_pk_fma_f32 v[222:223], v[8:9], v[214:215], v[222:223]
	v_pk_fma_f32 v[224:225], v[10:11], v[216:217], v[224:225]
	v_pk_fma_f32 v[222:223], v[12:13], v[218:219], v[222:223]
	v_pk_fma_f32 v[224:225], v[14:15], v[220:221], v[224:225]
	v_pk_add_f32 v[222:223], v[222:223], v[224:225]
	s_nop 0
	v_add_f32_e32 v230, v222, v223
	v_cvt_pk_f32_fp8_e32 v[214:215], v164
	v_cvt_pk_f32_fp8_sdwa v[216:217], v164 src0_sel:WORD_1
	v_cvt_pk_f32_fp8_e32 v[218:219], v165
	v_cvt_pk_f32_fp8_sdwa v[220:221], v165 src0_sel:WORD_1
	v_pk_mul_f32 v[222:223], v[0:1], v[214:215]
	v_pk_mul_f32 v[224:225], v[2:3], v[216:217]
	v_cvt_pk_f32_fp8_e32 v[214:215], v166
	v_cvt_pk_f32_fp8_sdwa v[216:217], v166 src0_sel:WORD_1
	v_pk_fma_f32 v[222:223], v[4:5], v[218:219], v[222:223]
	v_pk_fma_f32 v[224:225], v[6:7], v[220:221], v[224:225]
	v_cvt_pk_f32_fp8_e32 v[218:219], v167
	v_cvt_pk_f32_fp8_sdwa v[220:221], v167 src0_sel:WORD_1
	v_pk_fma_f32 v[222:223], v[8:9], v[214:215], v[222:223]
	v_pk_fma_f32 v[224:225], v[10:11], v[216:217], v[224:225]
	v_pk_fma_f32 v[222:223], v[12:13], v[218:219], v[222:223]
	v_pk_fma_f32 v[224:225], v[14:15], v[220:221], v[224:225]
	v_pk_add_f32 v[222:223], v[222:223], v[224:225]
	s_nop 0
	v_add_f32_e32 v231, v222, v223
	v_cvt_pk_f32_fp8_e32 v[214:215], v168
	v_cvt_pk_f32_fp8_sdwa v[216:217], v168 src0_sel:WORD_1
	v_cvt_pk_f32_fp8_e32 v[218:219], v169
	v_cvt_pk_f32_fp8_sdwa v[220:221], v169 src0_sel:WORD_1
	v_pk_mul_f32 v[222:223], v[0:1], v[214:215]
	v_pk_mul_f32 v[224:225], v[2:3], v[216:217]
	v_cvt_pk_f32_fp8_e32 v[214:215], v170
	v_cvt_pk_f32_fp8_sdwa v[216:217], v170 src0_sel:WORD_1
	v_pk_fma_f32 v[222:223], v[4:5], v[218:219], v[222:223]
	v_pk_fma_f32 v[224:225], v[6:7], v[220:221], v[224:225]
	v_cvt_pk_f32_fp8_e32 v[218:219], v171
	v_cvt_pk_f32_fp8_sdwa v[220:221], v171 src0_sel:WORD_1
	v_pk_fma_f32 v[222:223], v[8:9], v[214:215], v[222:223]
	v_pk_fma_f32 v[224:225], v[10:11], v[216:217], v[224:225]
	v_pk_fma_f32 v[222:223], v[12:13], v[218:219], v[222:223]
	v_pk_fma_f32 v[224:225], v[14:15], v[220:221], v[224:225]
	v_pk_add_f32 v[222:223], v[222:223], v[224:225]
	s_nop 0
	v_add_f32_e32 v232, v222, v223
	v_cvt_pk_f32_fp8_e32 v[214:215], v172
	v_cvt_pk_f32_fp8_sdwa v[216:217], v172 src0_sel:WORD_1
	v_cvt_pk_f32_fp8_e32 v[218:219], v173
	v_cvt_pk_f32_fp8_sdwa v[220:221], v173 src0_sel:WORD_1
	v_pk_mul_f32 v[222:223], v[0:1], v[214:215]
	v_pk_mul_f32 v[224:225], v[2:3], v[216:217]
	v_cvt_pk_f32_fp8_e32 v[214:215], v174
	v_cvt_pk_f32_fp8_sdwa v[216:217], v174 src0_sel:WORD_1
	v_pk_fma_f32 v[222:223], v[4:5], v[218:219], v[222:223]
	v_pk_fma_f32 v[224:225], v[6:7], v[220:221], v[224:225]
	v_cvt_pk_f32_fp8_e32 v[218:219], v175
	v_cvt_pk_f32_fp8_sdwa v[220:221], v175 src0_sel:WORD_1
	v_pk_fma_f32 v[222:223], v[8:9], v[214:215], v[222:223]
	v_pk_fma_f32 v[224:225], v[10:11], v[216:217], v[224:225]
	v_pk_fma_f32 v[222:223], v[12:13], v[218:219], v[222:223]
	v_pk_fma_f32 v[224:225], v[14:15], v[220:221], v[224:225]
	v_pk_add_f32 v[222:223], v[222:223], v[224:225]
	s_nop 0
	v_add_f32_e32 v233, v222, v223
	v_permlane32_swap_b32_e32 v226, v230
	v_permlane32_swap_b32_e32 v227, v231
	v_permlane32_swap_b32_e32 v228, v232
	v_permlane32_swap_b32_e32 v229, v233
	v_add_f32_e32 v226, v226, v230
	v_add_f32_e32 v228, v228, v232
; template <bool STORE>
; DI void peer_item(const Params& p, int item, char* smem) {
;     ...
; #pragma unroll
;       for (int u = 0; u < 8; ++u) {
;         int e = e_s[tl * 128 + k + u];
;         uq[u] = *(const u32x4*)(U8 + (size_t)e * 1024 + lane * 16);
;       }
;       float part[8];
; #pragma unroll
;       for (int u = 0; u < 8; ++u) {
;         float d = 0.f;
; #pragma unroll
;         for (int i = 0; i < 4; ++i) {
;           f32x2_t lo = __builtin_amdgcn_cvt_pk_f32_fp8((int)uq[u][i], false);
;           f32x2_t hi = __builtin_amdgcn_cvt_pk_f32_fp8((int)uq[u][i], true);
;           d += xf[4 * i] * lo.x + xf[4 * i + 1] * lo.y + xf[4 * i + 2] * hi.x + xf[4 * i + 3] * hi.y;
;         }
;         part[u] = d;
;       }
;       float q4[4], r2[2], h;
; #pragma unroll
;       for (int j = 0; j < 4; ++j) {
;         float mine = b5 ? part[j + 4] : part[j];
;         float other = b5 ? part[j] : part[j + 4];
;         q4[j] = mine + __shfl_xor(other, 32);
;       }
; #pragma unroll
;       for (int j = 0; j < 2; ++j) {
;         float mine = b4 ? q4[j + 2] : q4[j];
;         float other = b4 ? q4[j] : q4[j + 2];
;         r2[j] = mine + __shfl_xor(other, 16);
;       }
;       {
;         float mine = b3 ? r2[1] : r2[0];
;         float other = b3 ? r2[0] : r2[1];
;         h = mine + __shfl_xor(other, 8);
;       }
;       h += __shfl_xor(h, 4);
;       h += __shfl_xor(h, 2);
;       h += __shfl_xor(h, 1);
	v_add_f32_e32 v227, v227, v231
	v_add_f32_e32 v229, v229, v233
	s_nop 1
	v_permlane16_swap_b32_e32 v226, v228
	v_permlane16_swap_b32_e32 v227, v229
	v_add_f32_e32 v226, v226, v228
	v_add_f32_e32 v227, v227, v229
	s_nop 0
	v_cndmask_b32_e64 v230, v226, v227, s[24:25]
	v_cndmask_b32_e64 v231, v227, v226, s[24:25]
	s_nop 1
	v_add_f32_dpp v232, v231, v230 row_ror:8 row_mask:0xf bank_mask:0xf
	s_nop 1
	v_add_f32_dpp v233, v232, v232 quad_perm:[1,0,3,2] row_mask:0xf bank_mask:0xf
	s_nop 1
	v_add_f32_dpp v232, v233, v233 quad_perm:[2,3,0,1] row_mask:0xf bank_mask:0xf
	s_nop 1
	v_add_f32_dpp v233, v232, v232 row_half_mirror row_mask:0xf bank_mask:0xf
	ds_write_b32 v235, v233 offset:32800
	v_readlane_b32 s48, v133, s72
	v_readlane_b32 s49, v133, s73
	v_readlane_b32 s50, v133, s74
	v_readlane_b32 s51, v133, s75
	v_readlane_b32 s52, v133, s76
	v_readlane_b32 s53, v133, s77
	v_readlane_b32 s54, v133, s78
	v_readlane_b32 s55, v133, s79
	s_add_u32 s32, s0, s48
	s_addc_u32 s33, s1, 0
	s_add_u32 s34, s0, s49
	s_addc_u32 s35, s1, 0
	s_add_u32 s36, s0, s50
	s_addc_u32 s37, s1, 0
	s_add_u32 s38, s0, s51
	s_addc_u32 s39, s1, 0
	s_add_u32 s40, s0, s52
	s_addc_u32 s41, s1, 0
	s_add_u32 s42, s0, s53
	s_addc_u32 s43, s1, 0
	s_add_u32 s44, s0, s54
	s_addc_u32 s45, s1, 0
	s_add_u32 s46, s0, s55
	s_addc_u32 s47, s1, 0
	global_load_dwordx4 v[144:147], v234, s[32:33]
	global_load_dwordx4 v[148:151], v234, s[34:35]
	global_load_dwordx4 v[152:155], v234, s[36:37]
	global_load_dwordx4 v[156:159], v234, s[38:39]
	global_load_dwordx4 v[160:163], v234, s[40:41]
	global_load_dwordx4 v[164:167], v234, s[42:43]
	global_load_dwordx4 v[168:171], v234, s[44:45]
	global_load_dwordx4 v[172:175], v234, s[46:47]
	s_waitcnt vmcnt(8)
	v_cvt_pk_f32_fp8_e32 v[214:215], v176
	v_cvt_pk_f32_fp8_sdwa v[216:217], v176 src0_sel:WORD_1
	v_cvt_pk_f32_fp8_e32 v[218:219], v177
	v_cvt_pk_f32_fp8_sdwa v[220:221], v177 src0_sel:WORD_1
	v_pk_mul_f32 v[222:223], v[16:17], v[214:215]
	v_pk_mul_f32 v[224:225], v[18:19], v[216:217]
	v_cvt_pk_f32_fp8_e32 v[214:215], v178
	v_cvt_pk_f32_fp8_sdwa v[216:217], v178 src0_sel:WORD_1
	v_pk_fma_f32 v[222:223], v[20:21], v[218:219], v[222:223]
	v_pk_fma_f32 v[224:225], v[22:23], v[220:221], v[224:225]
	v_cvt_pk_f32_fp8_e32 v[218:219], v179
	v_cvt_pk_f32_fp8_sdwa v[220:221], v179 src0_sel:WORD_1
	v_pk_fma_f32 v[222:223], v[24:25], v[214:215], v[222:223]
	v_pk_fma_f32 v[224:225], v[26:27], v[216:217], v[224:225]
	v_pk_fma_f32 v[222:223], v[28:29], v[218:219], v[222:223]
	v_pk_fma_f32 v[224:225], v[30:31], v[220:221], v[224:225]
	v_pk_add_f32 v[222:223], v[222:223], v[224:225]
	s_nop 0
	v_add_f32_e32 v226, v222, v223
	v_cvt_pk_f32_fp8_e32 v[214:215], v180
	v_cvt_pk_f32_fp8_sdwa v[216:217], v180 src0_sel:WORD_1
	v_cvt_pk_f32_fp8_e32 v[218:219], v181
	v_cvt_pk_f32_fp8_sdwa v[220:221], v181 src0_sel:WORD_1
	v_pk_mul_f32 v[222:223], v[16:17], v[214:215]
	v_pk_mul_f32 v[224:225], v[18:19], v[216:217]
	v_cvt_pk_f32_fp8_e32 v[214:215], v182
	v_cvt_pk_f32_fp8_sdwa v[216:217], v182 src0_sel:WORD_1
	v_pk_fma_f32 v[222:223], v[20:21], v[218:219], v[222:223]
	v_pk_fma_f32 v[224:225], v[22:23], v[220:221], v[224:225]
	v_cvt_pk_f32_fp8_e32 v[218:219], v183
	v_cvt_pk_f32_fp8_sdwa v[220:221], v183 src0_sel:WORD_1
	v_pk_fma_f32 v[222:223], v[24:25], v[214:215], v[222:223]
	v_pk_fma_f32 v[224:225], v[26:27], v[216:217], v[224:225]
	v_pk_fma_f32 v[222:223], v[28:29], v[218:219], v[222:223]
	v_pk_fma_f32 v[224:225], v[30:31], v[220:221], v[224:225]
	v_pk_add_f32 v[222:223], v[222:223], v[224:225]
	s_nop 0
	v_add_f32_e32 v227, v222, v223
	v_cvt_pk_f32_fp8_e32 v[214:215], v184
	v_cvt_pk_f32_fp8_sdwa v[216:217], v184 src0_sel:WORD_1
	v_cvt_pk_f32_fp8_e32 v[218:219], v185
	v_cvt_pk_f32_fp8_sdwa v[220:221], v185 src0_sel:WORD_1
	v_pk_mul_f32 v[222:223], v[16:17], v[214:215]
	v_pk_mul_f32 v[224:225], v[18:19], v[216:217]
	v_cvt_pk_f32_fp8_e32 v[214:215], v186
	v_cvt_pk_f32_fp8_sdwa v[216:217], v186 src0_sel:WORD_1
	v_pk_fma_f32 v[222:223], v[20:21], v[218:219], v[222:223]
	v_pk_fma_f32 v[224:225], v[22:23], v[220:221], v[224:225]
	v_cvt_pk_f32_fp8_e32 v[218:219], v187
	v_cvt_pk_f32_fp8_sdwa v[220:221], v187 src0_sel:WORD_1
	v_pk_fma_f32 v[222:223], v[24:25], v[214:215], v[222:223]
	v_pk_fma_f32 v[224:225], v[26:27], v[216:217], v[224:225]
	v_pk_fma_f32 v[222:223], v[28:29], v[218:219], v[222:223]
	v_pk_fma_f32 v[224:225], v[30:31], v[220:221], v[224:225]
	v_pk_add_f32 v[222:223], v[222:223], v[224:225]
	s_nop 0
	v_add_f32_e32 v228, v222, v223
	v_cvt_pk_f32_fp8_e32 v[214:215], v188
	v_cvt_pk_f32_fp8_sdwa v[216:217], v188 src0_sel:WORD_1
	v_cvt_pk_f32_fp8_e32 v[218:219], v189
	v_cvt_pk_f32_fp8_sdwa v[220:221], v189 src0_sel:WORD_1
	v_pk_mul_f32 v[222:223], v[16:17], v[214:215]
	v_pk_mul_f32 v[224:225], v[18:19], v[216:217]
	v_cvt_pk_f32_fp8_e32 v[214:215], v190
	v_cvt_pk_f32_fp8_sdwa v[216:217], v190 src0_sel:WORD_1
	v_pk_fma_f32 v[222:223], v[20:21], v[218:219], v[222:223]
	v_pk_fma_f32 v[224:225], v[22:23], v[220:221], v[224:225]
	v_cvt_pk_f32_fp8_e32 v[218:219], v191
	v_cvt_pk_f32_fp8_sdwa v[220:221], v191 src0_sel:WORD_1
	v_pk_fma_f32 v[222:223], v[24:25], v[214:215], v[222:223]
	v_pk_fma_f32 v[224:225], v[26:27], v[216:217], v[224:225]
	v_pk_fma_f32 v[222:223], v[28:29], v[218:219], v[222:223]
	v_pk_fma_f32 v[224:225], v[30:31], v[220:221], v[224:225]
	v_pk_add_f32 v[222:223], v[222:223], v[224:225]
	s_nop 0
	v_add_f32_e32 v229, v222, v223
	v_cvt_pk_f32_fp8_e32 v[214:215], v192
	v_cvt_pk_f32_fp8_sdwa v[216:217], v192 src0_sel:WORD_1
	v_cvt_pk_f32_fp8_e32 v[218:219], v193
	v_cvt_pk_f32_fp8_sdwa v[220:221], v193 src0_sel:WORD_1
	v_pk_mul_f32 v[222:223], v[16:17], v[214:215]
; template <bool STORE>
; DI void peer_item(const Params& p, int item, char* smem) {
;     ...
; #pragma unroll
;       for (int u = 0; u < 8; ++u) {
;         int e = e_s[tl * 128 + k + u];
;         uq[u] = *(const u32x4*)(U8 + (size_t)e * 1024 + lane * 16);
;       }
;       float part[8];
; #pragma unroll
;       for (int u = 0; u < 8; ++u) {
;         float d = 0.f;
; #pragma unroll
;         for (int i = 0; i < 4; ++i) {
;           f32x2_t lo = __builtin_amdgcn_cvt_pk_f32_fp8((int)uq[u][i], false);
;           f32x2_t hi = __builtin_amdgcn_cvt_pk_f32_fp8((int)uq[u][i], true);
;           d += xf[4 * i] * lo.x + xf[4 * i + 1] * lo.y + xf[4 * i + 2] * hi.x + xf[4 * i + 3] * hi.y;
;         }
;         part[u] = d;
;       }
;       float q4[4], r2[2], h;
; #pragma unroll
;       for (int j = 0; j < 4; ++j) {
;         float mine = b5 ? part[j + 4] : part[j];
;         float other = b5 ? part[j] : part[j + 4];
;         q4[j] = mine + __shfl_xor(other, 32);
;       }
; #pragma unroll
;       for (int j = 0; j < 2; ++j) {
;         float mine = b4 ? q4[j + 2] : q4[j];
;         float other = b4 ? q4[j] : q4[j + 2];
;         r2[j] = mine + __shfl_xor(other, 16);
;       }
;       {
;         float mine = b3 ? r2[1] : r2[0];
;         float other = b3 ? r2[0] : r2[1];
;         h = mine + __shfl_xor(other, 8);
;       }
;       h += __shfl_xor(h, 4);
;       h += __shfl_xor(h, 2);
;       h += __shfl_xor(h, 1);
	v_pk_mul_f32 v[224:225], v[18:19], v[216:217]
	v_cvt_pk_f32_fp8_e32 v[214:215], v194
	v_cvt_pk_f32_fp8_sdwa v[216:217], v194 src0_sel:WORD_1
	v_pk_fma_f32 v[222:223], v[20:21], v[218:219], v[222:223]
	v_pk_fma_f32 v[224:225], v[22:23], v[220:221], v[224:225]
	v_cvt_pk_f32_fp8_e32 v[218:219], v195
	v_cvt_pk_f32_fp8_sdwa v[220:221], v195 src0_sel:WORD_1
	v_pk_fma_f32 v[222:223], v[24:25], v[214:215], v[222:223]
	v_pk_fma_f32 v[224:225], v[26:27], v[216:217], v[224:225]
	v_pk_fma_f32 v[222:223], v[28:29], v[218:219], v[222:223]
	v_pk_fma_f32 v[224:225], v[30:31], v[220:221], v[224:225]
	v_pk_add_f32 v[222:223], v[222:223], v[224:225]
	s_nop 0
	v_add_f32_e32 v230, v222, v223
	v_cvt_pk_f32_fp8_e32 v[214:215], v196
	v_cvt_pk_f32_fp8_sdwa v[216:217], v196 src0_sel:WORD_1
	v_cvt_pk_f32_fp8_e32 v[218:219], v197
	v_cvt_pk_f32_fp8_sdwa v[220:221], v197 src0_sel:WORD_1
	v_pk_mul_f32 v[222:223], v[16:17], v[214:215]
	v_pk_mul_f32 v[224:225], v[18:19], v[216:217]
	v_cvt_pk_f32_fp8_e32 v[214:215], v198
	v_cvt_pk_f32_fp8_sdwa v[216:217], v198 src0_sel:WORD_1
	v_pk_fma_f32 v[222:223], v[20:21], v[218:219], v[222:223]
	v_pk_fma_f32 v[224:225], v[22:23], v[220:221], v[224:225]
	v_cvt_pk_f32_fp8_e32 v[218:219], v199
	v_cvt_pk_f32_fp8_sdwa v[220:221], v199 src0_sel:WORD_1
	v_pk_fma_f32 v[222:223], v[24:25], v[214:215], v[222:223]
	v_pk_fma_f32 v[224:225], v[26:27], v[216:217], v[224:225]
	v_pk_fma_f32 v[222:223], v[28:29], v[218:219], v[222:223]
	v_pk_fma_f32 v[224:225], v[30:31], v[220:221], v[224:225]
	v_pk_add_f32 v[222:223], v[222:223], v[224:225]
	s_nop 0
	v_add_f32_e32 v231, v222, v223
	v_cvt_pk_f32_fp8_e32 v[214:215], v200
	v_cvt_pk_f32_fp8_sdwa v[216:217], v200 src0_sel:WORD_1
	v_cvt_pk_f32_fp8_e32 v[218:219], v201
	v_cvt_pk_f32_fp8_sdwa v[220:221], v201 src0_sel:WORD_1
	v_pk_mul_f32 v[222:223], v[16:17], v[214:215]
	v_pk_mul_f32 v[224:225], v[18:19], v[216:217]
	v_cvt_pk_f32_fp8_e32 v[214:215], v202
	v_cvt_pk_f32_fp8_sdwa v[216:217], v202 src0_sel:WORD_1
	v_pk_fma_f32 v[222:223], v[20:21], v[218:219], v[222:223]
	v_pk_fma_f32 v[224:225], v[22:23], v[220:221], v[224:225]
	v_cvt_pk_f32_fp8_e32 v[218:219], v203
	v_cvt_pk_f32_fp8_sdwa v[220:221], v203 src0_sel:WORD_1
	v_pk_fma_f32 v[222:223], v[24:25], v[214:215], v[222:223]
	v_pk_fma_f32 v[224:225], v[26:27], v[216:217], v[224:225]
	v_pk_fma_f32 v[222:223], v[28:29], v[218:219], v[222:223]
	v_pk_fma_f32 v[224:225], v[30:31], v[220:221], v[224:225]
	v_pk_add_f32 v[222:223], v[222:223], v[224:225]
	s_nop 0
	v_add_f32_e32 v232, v222, v223
	v_cvt_pk_f32_fp8_e32 v[214:215], v204
	v_cvt_pk_f32_fp8_sdwa v[216:217], v204 src0_sel:WORD_1
	v_cvt_pk_f32_fp8_e32 v[218:219], v205
	v_cvt_pk_f32_fp8_sdwa v[220:221], v205 src0_sel:WORD_1
	v_pk_mul_f32 v[222:223], v[16:17], v[214:215]
	v_pk_mul_f32 v[224:225], v[18:19], v[216:217]
	v_cvt_pk_f32_fp8_e32 v[214:215], v206
	v_cvt_pk_f32_fp8_sdwa v[216:217], v206 src0_sel:WORD_1
	v_pk_fma_f32 v[222:223], v[20:21], v[218:219], v[222:223]
	v_pk_fma_f32 v[224:225], v[22:23], v[220:221], v[224:225]
	v_cvt_pk_f32_fp8_e32 v[218:219], v207
	v_cvt_pk_f32_fp8_sdwa v[220:221], v207 src0_sel:WORD_1
	v_pk_fma_f32 v[222:223], v[24:25], v[214:215], v[222:223]
	v_pk_fma_f32 v[224:225], v[26:27], v[216:217], v[224:225]
	v_pk_fma_f32 v[222:223], v[28:29], v[218:219], v[222:223]
	v_pk_fma_f32 v[224:225], v[30:31], v[220:221], v[224:225]
	v_pk_add_f32 v[222:223], v[222:223], v[224:225]
	s_nop 0
	v_add_f32_e32 v233, v222, v223
	v_permlane32_swap_b32_e32 v226, v230
	v_permlane32_swap_b32_e32 v227, v231
	v_permlane32_swap_b32_e32 v228, v232
	v_permlane32_swap_b32_e32 v229, v233
	v_add_f32_e32 v226, v226, v230
	v_add_f32_e32 v228, v228, v232
	v_add_f32_e32 v227, v227, v231
	v_add_f32_e32 v229, v229, v233
	s_nop 1
	v_permlane16_swap_b32_e32 v226, v228
	v_permlane16_swap_b32_e32 v227, v229
	v_add_f32_e32 v226, v226, v228
	v_add_f32_e32 v227, v227, v229
	s_nop 0
	v_cndmask_b32_e64 v230, v226, v227, s[24:25]
	v_cndmask_b32_e64 v231, v227, v226, s[24:25]
	s_nop 1
	v_add_f32_dpp v232, v231, v230 row_ror:8 row_mask:0xf bank_mask:0xf
	s_nop 1
	v_add_f32_dpp v233, v232, v232 quad_perm:[1,0,3,2] row_mask:0xf bank_mask:0xf
	s_nop 1
	v_add_f32_dpp v232, v233, v233 quad_perm:[2,3,0,1] row_mask:0xf bank_mask:0xf
	s_nop 1
	v_add_f32_dpp v233, v232, v232 row_half_mirror row_mask:0xf bank_mask:0xf
	ds_write_b32 v235, v233 offset:33312
	v_readlane_b32 s48, v135, s72
	v_readlane_b32 s49, v135, s73
	v_readlane_b32 s50, v135, s74
	v_readlane_b32 s51, v135, s75
	v_readlane_b32 s52, v135, s76
	v_readlane_b32 s53, v135, s77
	v_readlane_b32 s54, v135, s78
	v_readlane_b32 s55, v135, s79
	s_add_u32 s32, s0, s48
	s_addc_u32 s33, s1, 0
	s_add_u32 s34, s0, s49
	s_addc_u32 s35, s1, 0
	s_add_u32 s36, s0, s50
	s_addc_u32 s37, s1, 0
	s_add_u32 s38, s0, s51
	s_addc_u32 s39, s1, 0
	s_add_u32 s40, s0, s52
	s_addc_u32 s41, s1, 0
	s_add_u32 s42, s0, s53
	s_addc_u32 s43, s1, 0
	s_add_u32 s44, s0, s54
	s_addc_u32 s45, s1, 0
	s_add_u32 s46, s0, s55
	s_addc_u32 s47, s1, 0
	global_load_dwordx4 v[176:179], v234, s[32:33]
	global_load_dwordx4 v[180:183], v234, s[34:35]
	global_load_dwordx4 v[184:187], v234, s[36:37]
	global_load_dwordx4 v[188:191], v234, s[38:39]
	global_load_dwordx4 v[192:195], v234, s[40:41]
	global_load_dwordx4 v[196:199], v234, s[42:43]
	global_load_dwordx4 v[200:203], v234, s[44:45]
	global_load_dwordx4 v[204:207], v234, s[46:47]
	s_waitcnt vmcnt(8)
; template <bool STORE>
; DI void peer_item(const Params& p, int item, char* smem) {
;     ...
; #pragma unroll
;       for (int u = 0; u < 8; ++u) {
;         float d = 0.f;
; #pragma unroll
;         for (int i = 0; i < 4; ++i) {
;           f32x2_t lo = __builtin_amdgcn_cvt_pk_f32_fp8((int)uq[u][i], false);
;           f32x2_t hi = __builtin_amdgcn_cvt_pk_f32_fp8((int)uq[u][i], true);
;           d += xf[4 * i] * lo.x + xf[4 * i + 1] * lo.y + xf[4 * i + 2] * hi.x + xf[4 * i + 3] * hi.y;
;         }
;         part[u] = d;
;       }
	v_cvt_pk_f32_fp8_e32 v[214:215], v144
	v_cvt_pk_f32_fp8_sdwa v[216:217], v144 src0_sel:WORD_1
	v_cvt_pk_f32_fp8_e32 v[218:219], v145
	v_cvt_pk_f32_fp8_sdwa v[220:221], v145 src0_sel:WORD_1
	v_pk_mul_f32 v[222:223], v[32:33], v[214:215]
	v_pk_mul_f32 v[224:225], v[34:35], v[216:217]
	v_cvt_pk_f32_fp8_e32 v[214:215], v146
	v_cvt_pk_f32_fp8_sdwa v[216:217], v146 src0_sel:WORD_1
	v_pk_fma_f32 v[222:223], v[36:37], v[218:219], v[222:223]
	v_pk_fma_f32 v[224:225], v[38:39], v[220:221], v[224:225]
	v_cvt_pk_f32_fp8_e32 v[218:219], v147
	v_cvt_pk_f32_fp8_sdwa v[220:221], v147 src0_sel:WORD_1
	v_pk_fma_f32 v[222:223], v[40:41], v[214:215], v[222:223]
	v_pk_fma_f32 v[224:225], v[42:43], v[216:217], v[224:225]
	v_pk_fma_f32 v[222:223], v[44:45], v[218:219], v[222:223]
	v_pk_fma_f32 v[224:225], v[46:47], v[220:221], v[224:225]
	v_pk_add_f32 v[222:223], v[222:223], v[224:225]
	s_nop 0
	v_add_f32_e32 v226, v222, v223
	v_cvt_pk_f32_fp8_e32 v[214:215], v148
	v_cvt_pk_f32_fp8_sdwa v[216:217], v148 src0_sel:WORD_1
	v_cvt_pk_f32_fp8_e32 v[218:219], v149
	v_cvt_pk_f32_fp8_sdwa v[220:221], v149 src0_sel:WORD_1
	v_pk_mul_f32 v[222:223], v[32:33], v[214:215]
	v_pk_mul_f32 v[224:225], v[34:35], v[216:217]
	v_cvt_pk_f32_fp8_e32 v[214:215], v150
	v_cvt_pk_f32_fp8_sdwa v[216:217], v150 src0_sel:WORD_1
	v_pk_fma_f32 v[222:223], v[36:37], v[218:219], v[222:223]
	v_pk_fma_f32 v[224:225], v[38:39], v[220:221], v[224:225]
	v_cvt_pk_f32_fp8_e32 v[218:219], v151
	v_cvt_pk_f32_fp8_sdwa v[220:221], v151 src0_sel:WORD_1
	v_pk_fma_f32 v[222:223], v[40:41], v[214:215], v[222:223]
	v_pk_fma_f32 v[224:225], v[42:43], v[216:217], v[224:225]
	v_pk_fma_f32 v[222:223], v[44:45], v[218:219], v[222:223]
	v_pk_fma_f32 v[224:225], v[46:47], v[220:221], v[224:225]
	v_pk_add_f32 v[222:223], v[222:223], v[224:225]
	s_nop 0
	v_add_f32_e32 v227, v222, v223
	v_cvt_pk_f32_fp8_e32 v[214:215], v152
	v_cvt_pk_f32_fp8_sdwa v[216:217], v152 src0_sel:WORD_1
	v_cvt_pk_f32_fp8_e32 v[218:219], v153
	v_cvt_pk_f32_fp8_sdwa v[220:221], v153 src0_sel:WORD_1
	v_pk_mul_f32 v[222:223], v[32:33], v[214:215]
	v_pk_mul_f32 v[224:225], v[34:35], v[216:217]
	v_cvt_pk_f32_fp8_e32 v[214:215], v154
	v_cvt_pk_f32_fp8_sdwa v[216:217], v154 src0_sel:WORD_1
	v_pk_fma_f32 v[222:223], v[36:37], v[218:219], v[222:223]
	v_pk_fma_f32 v[224:225], v[38:39], v[220:221], v[224:225]
	v_cvt_pk_f32_fp8_e32 v[218:219], v155
	v_cvt_pk_f32_fp8_sdwa v[220:221], v155 src0_sel:WORD_1
	v_pk_fma_f32 v[222:223], v[40:41], v[214:215], v[222:223]
	v_pk_fma_f32 v[224:225], v[42:43], v[216:217], v[224:225]
	v_pk_fma_f32 v[222:223], v[44:45], v[218:219], v[222:223]
	v_pk_fma_f32 v[224:225], v[46:47], v[220:221], v[224:225]
	v_pk_add_f32 v[222:223], v[222:223], v[224:225]
	s_nop 0
	v_add_f32_e32 v228, v222, v223
	v_cvt_pk_f32_fp8_e32 v[214:215], v156
	v_cvt_pk_f32_fp8_sdwa v[216:217], v156 src0_sel:WORD_1
	v_cvt_pk_f32_fp8_e32 v[218:219], v157
	v_cvt_pk_f32_fp8_sdwa v[220:221], v157 src0_sel:WORD_1
	v_pk_mul_f32 v[222:223], v[32:33], v[214:215]
	v_pk_mul_f32 v[224:225], v[34:35], v[216:217]
	v_cvt_pk_f32_fp8_e32 v[214:215], v158
	v_cvt_pk_f32_fp8_sdwa v[216:217], v158 src0_sel:WORD_1
	v_pk_fma_f32 v[222:223], v[36:37], v[218:219], v[222:223]
	v_pk_fma_f32 v[224:225], v[38:39], v[220:221], v[224:225]
	v_cvt_pk_f32_fp8_e32 v[218:219], v159
	v_cvt_pk_f32_fp8_sdwa v[220:221], v159 src0_sel:WORD_1
	v_pk_fma_f32 v[222:223], v[40:41], v[214:215], v[222:223]
	v_pk_fma_f32 v[224:225], v[42:43], v[216:217], v[224:225]
	v_pk_fma_f32 v[222:223], v[44:45], v[218:219], v[222:223]
	v_pk_fma_f32 v[224:225], v[46:47], v[220:221], v[224:225]
	v_pk_add_f32 v[222:223], v[222:223], v[224:225]
	s_nop 0
	v_add_f32_e32 v229, v222, v223
	v_cvt_pk_f32_fp8_e32 v[214:215], v160
	v_cvt_pk_f32_fp8_sdwa v[216:217], v160 src0_sel:WORD_1
	v_cvt_pk_f32_fp8_e32 v[218:219], v161
	v_cvt_pk_f32_fp8_sdwa v[220:221], v161 src0_sel:WORD_1
	v_pk_mul_f32 v[222:223], v[32:33], v[214:215]
	v_pk_mul_f32 v[224:225], v[34:35], v[216:217]
	v_cvt_pk_f32_fp8_e32 v[214:215], v162
	v_cvt_pk_f32_fp8_sdwa v[216:217], v162 src0_sel:WORD_1
	v_pk_fma_f32 v[222:223], v[36:37], v[218:219], v[222:223]
	v_pk_fma_f32 v[224:225], v[38:39], v[220:221], v[224:225]
	v_cvt_pk_f32_fp8_e32 v[218:219], v163
	v_cvt_pk_f32_fp8_sdwa v[220:221], v163 src0_sel:WORD_1
	v_pk_fma_f32 v[222:223], v[40:41], v[214:215], v[222:223]
	v_pk_fma_f32 v[224:225], v[42:43], v[216:217], v[224:225]
	v_pk_fma_f32 v[222:223], v[44:45], v[218:219], v[222:223]
	v_pk_fma_f32 v[224:225], v[46:47], v[220:221], v[224:225]
	v_pk_add_f32 v[222:223], v[222:223], v[224:225]
	s_nop 0
	v_add_f32_e32 v230, v222, v223
	v_cvt_pk_f32_fp8_e32 v[214:215], v164
	v_cvt_pk_f32_fp8_sdwa v[216:217], v164 src0_sel:WORD_1
	v_cvt_pk_f32_fp8_e32 v[218:219], v165
	v_cvt_pk_f32_fp8_sdwa v[220:221], v165 src0_sel:WORD_1
	v_pk_mul_f32 v[222:223], v[32:33], v[214:215]
	v_pk_mul_f32 v[224:225], v[34:35], v[216:217]
	v_cvt_pk_f32_fp8_e32 v[214:215], v166
	v_cvt_pk_f32_fp8_sdwa v[216:217], v166 src0_sel:WORD_1
	v_pk_fma_f32 v[222:223], v[36:37], v[218:219], v[222:223]
	v_pk_fma_f32 v[224:225], v[38:39], v[220:221], v[224:225]
	v_cvt_pk_f32_fp8_e32 v[218:219], v167
	v_cvt_pk_f32_fp8_sdwa v[220:221], v167 src0_sel:WORD_1
	v_pk_fma_f32 v[222:223], v[40:41], v[214:215], v[222:223]
	v_pk_fma_f32 v[224:225], v[42:43], v[216:217], v[224:225]
	v_pk_fma_f32 v[222:223], v[44:45], v[218:219], v[222:223]
	v_pk_fma_f32 v[224:225], v[46:47], v[220:221], v[224:225]
	v_pk_add_f32 v[222:223], v[222:223], v[224:225]
	s_nop 0
	v_add_f32_e32 v231, v222, v223
	v_cvt_pk_f32_fp8_e32 v[214:215], v168
	v_cvt_pk_f32_fp8_sdwa v[216:217], v168 src0_sel:WORD_1
	v_cvt_pk_f32_fp8_e32 v[218:219], v169
; template <bool STORE>
; DI void peer_item(const Params& p, int item, char* smem) {
;     ...
; #pragma unroll
;       for (int u = 0; u < 8; ++u) {
;         int e = e_s[tl * 128 + k + u];
;         uq[u] = *(const u32x4*)(U8 + (size_t)e * 1024 + lane * 16);
;       }
;       float part[8];
; #pragma unroll
;       for (int u = 0; u < 8; ++u) {
;         float d = 0.f;
; #pragma unroll
;         for (int i = 0; i < 4; ++i) {
;           f32x2_t lo = __builtin_amdgcn_cvt_pk_f32_fp8((int)uq[u][i], false);
;           f32x2_t hi = __builtin_amdgcn_cvt_pk_f32_fp8((int)uq[u][i], true);
;           d += xf[4 * i] * lo.x + xf[4 * i + 1] * lo.y + xf[4 * i + 2] * hi.x + xf[4 * i + 3] * hi.y;
;         }
;         part[u] = d;
;       }
;       float q4[4], r2[2], h;
; #pragma unroll
;       for (int j = 0; j < 4; ++j) {
;         float mine = b5 ? part[j + 4] : part[j];
;         float other = b5 ? part[j] : part[j + 4];
;         q4[j] = mine + __shfl_xor(other, 32);
;       }
; #pragma unroll
;       for (int j = 0; j < 2; ++j) {
;         float mine = b4 ? q4[j + 2] : q4[j];
;         float other = b4 ? q4[j] : q4[j + 2];
;         r2[j] = mine + __shfl_xor(other, 16);
;       }
;       {
;         float mine = b3 ? r2[1] : r2[0];
;         float other = b3 ? r2[0] : r2[1];
;         h = mine + __shfl_xor(other, 8);
;       }
;       h += __shfl_xor(h, 4);
;       h += __shfl_xor(h, 2);
;       h += __shfl_xor(h, 1);
	v_cvt_pk_f32_fp8_sdwa v[220:221], v169 src0_sel:WORD_1
	v_pk_mul_f32 v[222:223], v[32:33], v[214:215]
	v_pk_mul_f32 v[224:225], v[34:35], v[216:217]
	v_cvt_pk_f32_fp8_e32 v[214:215], v170
	v_cvt_pk_f32_fp8_sdwa v[216:217], v170 src0_sel:WORD_1
	v_pk_fma_f32 v[222:223], v[36:37], v[218:219], v[222:223]
	v_pk_fma_f32 v[224:225], v[38:39], v[220:221], v[224:225]
	v_cvt_pk_f32_fp8_e32 v[218:219], v171
	v_cvt_pk_f32_fp8_sdwa v[220:221], v171 src0_sel:WORD_1
	v_pk_fma_f32 v[222:223], v[40:41], v[214:215], v[222:223]
	v_pk_fma_f32 v[224:225], v[42:43], v[216:217], v[224:225]
	v_pk_fma_f32 v[222:223], v[44:45], v[218:219], v[222:223]
	v_pk_fma_f32 v[224:225], v[46:47], v[220:221], v[224:225]
	v_pk_add_f32 v[222:223], v[222:223], v[224:225]
	s_nop 0
	v_add_f32_e32 v232, v222, v223
	v_cvt_pk_f32_fp8_e32 v[214:215], v172
	v_cvt_pk_f32_fp8_sdwa v[216:217], v172 src0_sel:WORD_1
	v_cvt_pk_f32_fp8_e32 v[218:219], v173
	v_cvt_pk_f32_fp8_sdwa v[220:221], v173 src0_sel:WORD_1
	v_pk_mul_f32 v[222:223], v[32:33], v[214:215]
	v_pk_mul_f32 v[224:225], v[34:35], v[216:217]
	v_cvt_pk_f32_fp8_e32 v[214:215], v174
	v_cvt_pk_f32_fp8_sdwa v[216:217], v174 src0_sel:WORD_1
	v_pk_fma_f32 v[222:223], v[36:37], v[218:219], v[222:223]
	v_pk_fma_f32 v[224:225], v[38:39], v[220:221], v[224:225]
	v_cvt_pk_f32_fp8_e32 v[218:219], v175
	v_cvt_pk_f32_fp8_sdwa v[220:221], v175 src0_sel:WORD_1
	v_pk_fma_f32 v[222:223], v[40:41], v[214:215], v[222:223]
	v_pk_fma_f32 v[224:225], v[42:43], v[216:217], v[224:225]
	v_pk_fma_f32 v[222:223], v[44:45], v[218:219], v[222:223]
	v_pk_fma_f32 v[224:225], v[46:47], v[220:221], v[224:225]
	v_pk_add_f32 v[222:223], v[222:223], v[224:225]
	s_nop 0
	v_add_f32_e32 v233, v222, v223
	v_permlane32_swap_b32_e32 v226, v230
	v_permlane32_swap_b32_e32 v227, v231
	v_permlane32_swap_b32_e32 v228, v232
	v_permlane32_swap_b32_e32 v229, v233
	v_add_f32_e32 v226, v226, v230
	v_add_f32_e32 v228, v228, v232
	v_add_f32_e32 v227, v227, v231
	v_add_f32_e32 v229, v229, v233
	s_nop 1
	v_permlane16_swap_b32_e32 v226, v228
	v_permlane16_swap_b32_e32 v227, v229
	v_add_f32_e32 v226, v226, v228
	v_add_f32_e32 v227, v227, v229
	s_nop 0
	v_cndmask_b32_e64 v230, v226, v227, s[24:25]
	v_cndmask_b32_e64 v231, v227, v226, s[24:25]
	s_nop 1
	v_add_f32_dpp v232, v231, v230 row_ror:8 row_mask:0xf bank_mask:0xf
	s_nop 1
	v_add_f32_dpp v233, v232, v232 quad_perm:[1,0,3,2] row_mask:0xf bank_mask:0xf
	s_nop 1
	v_add_f32_dpp v232, v233, v233 quad_perm:[2,3,0,1] row_mask:0xf bank_mask:0xf
	s_nop 1
	v_add_f32_dpp v233, v232, v232 row_half_mirror row_mask:0xf bank_mask:0xf
	ds_write_b32 v235, v233 offset:33824
	v_readlane_b32 s48, v137, s72
	v_readlane_b32 s49, v137, s73
	v_readlane_b32 s50, v137, s74
	v_readlane_b32 s51, v137, s75
	v_readlane_b32 s52, v137, s76
	v_readlane_b32 s53, v137, s77
	v_readlane_b32 s54, v137, s78
	v_readlane_b32 s55, v137, s79
	s_add_u32 s32, s0, s48
	s_addc_u32 s33, s1, 0
	s_add_u32 s34, s0, s49
	s_addc_u32 s35, s1, 0
	s_add_u32 s36, s0, s50
	s_addc_u32 s37, s1, 0
	s_add_u32 s38, s0, s51
	s_addc_u32 s39, s1, 0
	s_add_u32 s40, s0, s52
	s_addc_u32 s41, s1, 0
	s_add_u32 s42, s0, s53
	s_addc_u32 s43, s1, 0
	s_add_u32 s44, s0, s54
	s_addc_u32 s45, s1, 0
	s_add_u32 s46, s0, s55
	s_addc_u32 s47, s1, 0
	global_load_dwordx4 v[144:147], v234, s[32:33]
	global_load_dwordx4 v[148:151], v234, s[34:35]
	global_load_dwordx4 v[152:155], v234, s[36:37]
	global_load_dwordx4 v[156:159], v234, s[38:39]
	global_load_dwordx4 v[160:163], v234, s[40:41]
	global_load_dwordx4 v[164:167], v234, s[42:43]
	global_load_dwordx4 v[168:171], v234, s[44:45]
	global_load_dwordx4 v[172:175], v234, s[46:47]
	s_waitcnt vmcnt(8)
	v_cvt_pk_f32_fp8_e32 v[214:215], v176
	v_cvt_pk_f32_fp8_sdwa v[216:217], v176 src0_sel:WORD_1
	v_cvt_pk_f32_fp8_e32 v[218:219], v177
	v_cvt_pk_f32_fp8_sdwa v[220:221], v177 src0_sel:WORD_1
	v_pk_mul_f32 v[222:223], v[48:49], v[214:215]
	v_pk_mul_f32 v[224:225], v[50:51], v[216:217]
	v_cvt_pk_f32_fp8_e32 v[214:215], v178
	v_cvt_pk_f32_fp8_sdwa v[216:217], v178 src0_sel:WORD_1
	v_pk_fma_f32 v[222:223], v[52:53], v[218:219], v[222:223]
	v_pk_fma_f32 v[224:225], v[54:55], v[220:221], v[224:225]
	v_cvt_pk_f32_fp8_e32 v[218:219], v179
	v_cvt_pk_f32_fp8_sdwa v[220:221], v179 src0_sel:WORD_1
	v_pk_fma_f32 v[222:223], v[56:57], v[214:215], v[222:223]
	v_pk_fma_f32 v[224:225], v[58:59], v[216:217], v[224:225]
	v_pk_fma_f32 v[222:223], v[60:61], v[218:219], v[222:223]
	v_pk_fma_f32 v[224:225], v[62:63], v[220:221], v[224:225]
	v_pk_add_f32 v[222:223], v[222:223], v[224:225]
	s_nop 0
	v_add_f32_e32 v226, v222, v223
	v_cvt_pk_f32_fp8_e32 v[214:215], v180
	v_cvt_pk_f32_fp8_sdwa v[216:217], v180 src0_sel:WORD_1
	v_cvt_pk_f32_fp8_e32 v[218:219], v181
	v_cvt_pk_f32_fp8_sdwa v[220:221], v181 src0_sel:WORD_1
	v_pk_mul_f32 v[222:223], v[48:49], v[214:215]
	v_pk_mul_f32 v[224:225], v[50:51], v[216:217]
	v_cvt_pk_f32_fp8_e32 v[214:215], v182
	v_cvt_pk_f32_fp8_sdwa v[216:217], v182 src0_sel:WORD_1
	v_pk_fma_f32 v[222:223], v[52:53], v[218:219], v[222:223]
	v_pk_fma_f32 v[224:225], v[54:55], v[220:221], v[224:225]
	v_cvt_pk_f32_fp8_e32 v[218:219], v183
	v_cvt_pk_f32_fp8_sdwa v[220:221], v183 src0_sel:WORD_1
	v_pk_fma_f32 v[222:223], v[56:57], v[214:215], v[222:223]
	v_pk_fma_f32 v[224:225], v[58:59], v[216:217], v[224:225]
	v_pk_fma_f32 v[222:223], v[60:61], v[218:219], v[222:223]
	v_pk_fma_f32 v[224:225], v[62:63], v[220:221], v[224:225]
	v_pk_add_f32 v[222:223], v[222:223], v[224:225]
	s_nop 0
	v_add_f32_e32 v227, v222, v223
	v_cvt_pk_f32_fp8_e32 v[214:215], v184
	v_cvt_pk_f32_fp8_sdwa v[216:217], v184 src0_sel:WORD_1
	v_cvt_pk_f32_fp8_e32 v[218:219], v185
	v_cvt_pk_f32_fp8_sdwa v[220:221], v185 src0_sel:WORD_1
; template <bool STORE>
; DI void peer_item(const Params& p, int item, char* smem) {
;     ...
; #pragma unroll
;       for (int u = 0; u < 8; ++u) {
;         float d = 0.f;
; #pragma unroll
;         for (int i = 0; i < 4; ++i) {
;           f32x2_t lo = __builtin_amdgcn_cvt_pk_f32_fp8((int)uq[u][i], false);
;           f32x2_t hi = __builtin_amdgcn_cvt_pk_f32_fp8((int)uq[u][i], true);
;           d += xf[4 * i] * lo.x + xf[4 * i + 1] * lo.y + xf[4 * i + 2] * hi.x + xf[4 * i + 3] * hi.y;
;         }
;         part[u] = d;
;       }
;       float q4[4], r2[2], h;
; #pragma unroll
;       for (int j = 0; j < 4; ++j) {
;         float mine = b5 ? part[j + 4] : part[j];
;         float other = b5 ? part[j] : part[j + 4];
;         q4[j] = mine + __shfl_xor(other, 32);
;       }
; #pragma unroll
;       for (int j = 0; j < 2; ++j) {
;         float mine = b4 ? q4[j + 2] : q4[j];
;         float other = b4 ? q4[j] : q4[j + 2];
;         r2[j] = mine + __shfl_xor(other, 16);
;       }
;       {
;         float mine = b3 ? r2[1] : r2[0];
;         float other = b3 ? r2[0] : r2[1];
;         h = mine + __shfl_xor(other, 8);
;       }
;       h += __shfl_xor(h, 4);
;       h += __shfl_xor(h, 2);
;       h += __shfl_xor(h, 1);
	v_pk_mul_f32 v[222:223], v[48:49], v[214:215]
	v_pk_mul_f32 v[224:225], v[50:51], v[216:217]
	v_cvt_pk_f32_fp8_e32 v[214:215], v186
	v_cvt_pk_f32_fp8_sdwa v[216:217], v186 src0_sel:WORD_1
	v_pk_fma_f32 v[222:223], v[52:53], v[218:219], v[222:223]
	v_pk_fma_f32 v[224:225], v[54:55], v[220:221], v[224:225]
	v_cvt_pk_f32_fp8_e32 v[218:219], v187
	v_cvt_pk_f32_fp8_sdwa v[220:221], v187 src0_sel:WORD_1
	v_pk_fma_f32 v[222:223], v[56:57], v[214:215], v[222:223]
	v_pk_fma_f32 v[224:225], v[58:59], v[216:217], v[224:225]
	v_pk_fma_f32 v[222:223], v[60:61], v[218:219], v[222:223]
	v_pk_fma_f32 v[224:225], v[62:63], v[220:221], v[224:225]
	v_pk_add_f32 v[222:223], v[222:223], v[224:225]
	s_nop 0
	v_add_f32_e32 v228, v222, v223
	v_cvt_pk_f32_fp8_e32 v[214:215], v188
	v_cvt_pk_f32_fp8_sdwa v[216:217], v188 src0_sel:WORD_1
	v_cvt_pk_f32_fp8_e32 v[218:219], v189
	v_cvt_pk_f32_fp8_sdwa v[220:221], v189 src0_sel:WORD_1
	v_pk_mul_f32 v[222:223], v[48:49], v[214:215]
	v_pk_mul_f32 v[224:225], v[50:51], v[216:217]
	v_cvt_pk_f32_fp8_e32 v[214:215], v190
	v_cvt_pk_f32_fp8_sdwa v[216:217], v190 src0_sel:WORD_1
	v_pk_fma_f32 v[222:223], v[52:53], v[218:219], v[222:223]
	v_pk_fma_f32 v[224:225], v[54:55], v[220:221], v[224:225]
	v_cvt_pk_f32_fp8_e32 v[218:219], v191
	v_cvt_pk_f32_fp8_sdwa v[220:221], v191 src0_sel:WORD_1
	v_pk_fma_f32 v[222:223], v[56:57], v[214:215], v[222:223]
	v_pk_fma_f32 v[224:225], v[58:59], v[216:217], v[224:225]
	v_pk_fma_f32 v[222:223], v[60:61], v[218:219], v[222:223]
	v_pk_fma_f32 v[224:225], v[62:63], v[220:221], v[224:225]
	v_pk_add_f32 v[222:223], v[222:223], v[224:225]
	s_nop 0
	v_add_f32_e32 v229, v222, v223
	v_cvt_pk_f32_fp8_e32 v[214:215], v192
	v_cvt_pk_f32_fp8_sdwa v[216:217], v192 src0_sel:WORD_1
	v_cvt_pk_f32_fp8_e32 v[218:219], v193
	v_cvt_pk_f32_fp8_sdwa v[220:221], v193 src0_sel:WORD_1
	v_pk_mul_f32 v[222:223], v[48:49], v[214:215]
	v_pk_mul_f32 v[224:225], v[50:51], v[216:217]
	v_cvt_pk_f32_fp8_e32 v[214:215], v194
	v_cvt_pk_f32_fp8_sdwa v[216:217], v194 src0_sel:WORD_1
	v_pk_fma_f32 v[222:223], v[52:53], v[218:219], v[222:223]
	v_pk_fma_f32 v[224:225], v[54:55], v[220:221], v[224:225]
	v_cvt_pk_f32_fp8_e32 v[218:219], v195
	v_cvt_pk_f32_fp8_sdwa v[220:221], v195 src0_sel:WORD_1
	v_pk_fma_f32 v[222:223], v[56:57], v[214:215], v[222:223]
	v_pk_fma_f32 v[224:225], v[58:59], v[216:217], v[224:225]
	v_pk_fma_f32 v[222:223], v[60:61], v[218:219], v[222:223]
	v_pk_fma_f32 v[224:225], v[62:63], v[220:221], v[224:225]
	v_pk_add_f32 v[222:223], v[222:223], v[224:225]
	s_nop 0
	v_add_f32_e32 v230, v222, v223
	v_cvt_pk_f32_fp8_e32 v[214:215], v196
	v_cvt_pk_f32_fp8_sdwa v[216:217], v196 src0_sel:WORD_1
	v_cvt_pk_f32_fp8_e32 v[218:219], v197
	v_cvt_pk_f32_fp8_sdwa v[220:221], v197 src0_sel:WORD_1
	v_pk_mul_f32 v[222:223], v[48:49], v[214:215]
	v_pk_mul_f32 v[224:225], v[50:51], v[216:217]
	v_cvt_pk_f32_fp8_e32 v[214:215], v198
	v_cvt_pk_f32_fp8_sdwa v[216:217], v198 src0_sel:WORD_1
	v_pk_fma_f32 v[222:223], v[52:53], v[218:219], v[222:223]
	v_pk_fma_f32 v[224:225], v[54:55], v[220:221], v[224:225]
	v_cvt_pk_f32_fp8_e32 v[218:219], v199
	v_cvt_pk_f32_fp8_sdwa v[220:221], v199 src0_sel:WORD_1
	v_pk_fma_f32 v[222:223], v[56:57], v[214:215], v[222:223]
	v_pk_fma_f32 v[224:225], v[58:59], v[216:217], v[224:225]
	v_pk_fma_f32 v[222:223], v[60:61], v[218:219], v[222:223]
	v_pk_fma_f32 v[224:225], v[62:63], v[220:221], v[224:225]
	v_pk_add_f32 v[222:223], v[222:223], v[224:225]
	s_nop 0
	v_add_f32_e32 v231, v222, v223
	v_cvt_pk_f32_fp8_e32 v[214:215], v200
	v_cvt_pk_f32_fp8_sdwa v[216:217], v200 src0_sel:WORD_1
	v_cvt_pk_f32_fp8_e32 v[218:219], v201
	v_cvt_pk_f32_fp8_sdwa v[220:221], v201 src0_sel:WORD_1
	v_pk_mul_f32 v[222:223], v[48:49], v[214:215]
	v_pk_mul_f32 v[224:225], v[50:51], v[216:217]
	v_cvt_pk_f32_fp8_e32 v[214:215], v202
	v_cvt_pk_f32_fp8_sdwa v[216:217], v202 src0_sel:WORD_1
	v_pk_fma_f32 v[222:223], v[52:53], v[218:219], v[222:223]
	v_pk_fma_f32 v[224:225], v[54:55], v[220:221], v[224:225]
	v_cvt_pk_f32_fp8_e32 v[218:219], v203
	v_cvt_pk_f32_fp8_sdwa v[220:221], v203 src0_sel:WORD_1
	v_pk_fma_f32 v[222:223], v[56:57], v[214:215], v[222:223]
	v_pk_fma_f32 v[224:225], v[58:59], v[216:217], v[224:225]
	v_pk_fma_f32 v[222:223], v[60:61], v[218:219], v[222:223]
	v_pk_fma_f32 v[224:225], v[62:63], v[220:221], v[224:225]
	v_pk_add_f32 v[222:223], v[222:223], v[224:225]
	s_nop 0
	v_add_f32_e32 v232, v222, v223
	v_cvt_pk_f32_fp8_e32 v[214:215], v204
	v_cvt_pk_f32_fp8_sdwa v[216:217], v204 src0_sel:WORD_1
	v_cvt_pk_f32_fp8_e32 v[218:219], v205
	v_cvt_pk_f32_fp8_sdwa v[220:221], v205 src0_sel:WORD_1
	v_pk_mul_f32 v[222:223], v[48:49], v[214:215]
	v_pk_mul_f32 v[224:225], v[50:51], v[216:217]
	v_cvt_pk_f32_fp8_e32 v[214:215], v206
	v_cvt_pk_f32_fp8_sdwa v[216:217], v206 src0_sel:WORD_1
	v_pk_fma_f32 v[222:223], v[52:53], v[218:219], v[222:223]
	v_pk_fma_f32 v[224:225], v[54:55], v[220:221], v[224:225]
	v_cvt_pk_f32_fp8_e32 v[218:219], v207
	v_cvt_pk_f32_fp8_sdwa v[220:221], v207 src0_sel:WORD_1
	v_pk_fma_f32 v[222:223], v[56:57], v[214:215], v[222:223]
	v_pk_fma_f32 v[224:225], v[58:59], v[216:217], v[224:225]
	v_pk_fma_f32 v[222:223], v[60:61], v[218:219], v[222:223]
	v_pk_fma_f32 v[224:225], v[62:63], v[220:221], v[224:225]
	v_pk_add_f32 v[222:223], v[222:223], v[224:225]
	s_nop 0
	v_add_f32_e32 v233, v222, v223
	v_permlane32_swap_b32_e32 v226, v230
	v_permlane32_swap_b32_e32 v227, v231
	v_permlane32_swap_b32_e32 v228, v232
	v_permlane32_swap_b32_e32 v229, v233
	v_add_f32_e32 v226, v226, v230
	v_add_f32_e32 v228, v228, v232
	v_add_f32_e32 v227, v227, v231
	v_add_f32_e32 v229, v229, v233
	s_nop 1
	v_permlane16_swap_b32_e32 v226, v228
; template <bool STORE>
; DI void peer_item(const Params& p, int item, char* smem) {
;     ...
; #pragma unroll
;       for (int u = 0; u < 8; ++u) {
;         int e = e_s[tl * 128 + k + u];
;         uq[u] = *(const u32x4*)(U8 + (size_t)e * 1024 + lane * 16);
;       }
;       float part[8];
; #pragma unroll
;       for (int u = 0; u < 8; ++u) {
;         float d = 0.f;
; #pragma unroll
;         for (int i = 0; i < 4; ++i) {
;           f32x2_t lo = __builtin_amdgcn_cvt_pk_f32_fp8((int)uq[u][i], false);
;           f32x2_t hi = __builtin_amdgcn_cvt_pk_f32_fp8((int)uq[u][i], true);
;           d += xf[4 * i] * lo.x + xf[4 * i + 1] * lo.y + xf[4 * i + 2] * hi.x + xf[4 * i + 3] * hi.y;
;         }
;         part[u] = d;
;       }
;       float q4[4], r2[2], h;
; #pragma unroll
;       for (int j = 0; j < 4; ++j) {
;         float mine = b5 ? part[j + 4] : part[j];
;         float other = b5 ? part[j] : part[j + 4];
;         q4[j] = mine + __shfl_xor(other, 32);
;       }
; #pragma unroll
;       for (int j = 0; j < 2; ++j) {
;         float mine = b4 ? q4[j + 2] : q4[j];
;         float other = b4 ? q4[j] : q4[j + 2];
;         r2[j] = mine + __shfl_xor(other, 16);
;       }
;       {
;         float mine = b3 ? r2[1] : r2[0];
;         float other = b3 ? r2[0] : r2[1];
;         h = mine + __shfl_xor(other, 8);
;       }
;       h += __shfl_xor(h, 4);
;       h += __shfl_xor(h, 2);
;       h += __shfl_xor(h, 1);
	v_permlane16_swap_b32_e32 v227, v229
	v_add_f32_e32 v226, v226, v228
	v_add_f32_e32 v227, v227, v229
	s_nop 0
	v_cndmask_b32_e64 v230, v226, v227, s[24:25]
	v_cndmask_b32_e64 v231, v227, v226, s[24:25]
	s_nop 1
	v_add_f32_dpp v232, v231, v230 row_ror:8 row_mask:0xf bank_mask:0xf
	s_nop 1
	v_add_f32_dpp v233, v232, v232 quad_perm:[1,0,3,2] row_mask:0xf bank_mask:0xf
	s_nop 1
	v_add_f32_dpp v232, v233, v233 quad_perm:[2,3,0,1] row_mask:0xf bank_mask:0xf
	s_nop 1
	v_add_f32_dpp v233, v232, v232 row_half_mirror row_mask:0xf bank_mask:0xf
	ds_write_b32 v235, v233 offset:34336
	v_readlane_b32 s48, v139, s72
	v_readlane_b32 s49, v139, s73
	v_readlane_b32 s50, v139, s74
	v_readlane_b32 s51, v139, s75
	v_readlane_b32 s52, v139, s76
	v_readlane_b32 s53, v139, s77
	v_readlane_b32 s54, v139, s78
	v_readlane_b32 s55, v139, s79
	s_add_u32 s32, s0, s48
	s_addc_u32 s33, s1, 0
	s_add_u32 s34, s0, s49
	s_addc_u32 s35, s1, 0
	s_add_u32 s36, s0, s50
	s_addc_u32 s37, s1, 0
	s_add_u32 s38, s0, s51
	s_addc_u32 s39, s1, 0
	s_add_u32 s40, s0, s52
	s_addc_u32 s41, s1, 0
	s_add_u32 s42, s0, s53
	s_addc_u32 s43, s1, 0
	s_add_u32 s44, s0, s54
	s_addc_u32 s45, s1, 0
	s_add_u32 s46, s0, s55
	s_addc_u32 s47, s1, 0
	global_load_dwordx4 v[176:179], v234, s[32:33]
	global_load_dwordx4 v[180:183], v234, s[34:35]
	global_load_dwordx4 v[184:187], v234, s[36:37]
	global_load_dwordx4 v[188:191], v234, s[38:39]
	global_load_dwordx4 v[192:195], v234, s[40:41]
	global_load_dwordx4 v[196:199], v234, s[42:43]
	global_load_dwordx4 v[200:203], v234, s[44:45]
	global_load_dwordx4 v[204:207], v234, s[46:47]
	s_waitcnt vmcnt(8)
	v_cvt_pk_f32_fp8_e32 v[214:215], v144
	v_cvt_pk_f32_fp8_sdwa v[216:217], v144 src0_sel:WORD_1
	v_cvt_pk_f32_fp8_e32 v[218:219], v145
	v_cvt_pk_f32_fp8_sdwa v[220:221], v145 src0_sel:WORD_1
	v_pk_mul_f32 v[222:223], v[64:65], v[214:215]
	v_pk_mul_f32 v[224:225], v[66:67], v[216:217]
	v_cvt_pk_f32_fp8_e32 v[214:215], v146
	v_cvt_pk_f32_fp8_sdwa v[216:217], v146 src0_sel:WORD_1
	v_pk_fma_f32 v[222:223], v[68:69], v[218:219], v[222:223]
	v_pk_fma_f32 v[224:225], v[70:71], v[220:221], v[224:225]
	v_cvt_pk_f32_fp8_e32 v[218:219], v147
	v_cvt_pk_f32_fp8_sdwa v[220:221], v147 src0_sel:WORD_1
	v_pk_fma_f32 v[222:223], v[72:73], v[214:215], v[222:223]
	v_pk_fma_f32 v[224:225], v[74:75], v[216:217], v[224:225]
	v_pk_fma_f32 v[222:223], v[76:77], v[218:219], v[222:223]
	v_pk_fma_f32 v[224:225], v[78:79], v[220:221], v[224:225]
	v_pk_add_f32 v[222:223], v[222:223], v[224:225]
	s_nop 0
	v_add_f32_e32 v226, v222, v223
	v_cvt_pk_f32_fp8_e32 v[214:215], v148
	v_cvt_pk_f32_fp8_sdwa v[216:217], v148 src0_sel:WORD_1
	v_cvt_pk_f32_fp8_e32 v[218:219], v149
	v_cvt_pk_f32_fp8_sdwa v[220:221], v149 src0_sel:WORD_1
	v_pk_mul_f32 v[222:223], v[64:65], v[214:215]
	v_pk_mul_f32 v[224:225], v[66:67], v[216:217]
	v_cvt_pk_f32_fp8_e32 v[214:215], v150
	v_cvt_pk_f32_fp8_sdwa v[216:217], v150 src0_sel:WORD_1
	v_pk_fma_f32 v[222:223], v[68:69], v[218:219], v[222:223]
	v_pk_fma_f32 v[224:225], v[70:71], v[220:221], v[224:225]
	v_cvt_pk_f32_fp8_e32 v[218:219], v151
	v_cvt_pk_f32_fp8_sdwa v[220:221], v151 src0_sel:WORD_1
	v_pk_fma_f32 v[222:223], v[72:73], v[214:215], v[222:223]
	v_pk_fma_f32 v[224:225], v[74:75], v[216:217], v[224:225]
	v_pk_fma_f32 v[222:223], v[76:77], v[218:219], v[222:223]
	v_pk_fma_f32 v[224:225], v[78:79], v[220:221], v[224:225]
	v_pk_add_f32 v[222:223], v[222:223], v[224:225]
	s_nop 0
	v_add_f32_e32 v227, v222, v223
	v_cvt_pk_f32_fp8_e32 v[214:215], v152
	v_cvt_pk_f32_fp8_sdwa v[216:217], v152 src0_sel:WORD_1
	v_cvt_pk_f32_fp8_e32 v[218:219], v153
	v_cvt_pk_f32_fp8_sdwa v[220:221], v153 src0_sel:WORD_1
	v_pk_mul_f32 v[222:223], v[64:65], v[214:215]
	v_pk_mul_f32 v[224:225], v[66:67], v[216:217]
	v_cvt_pk_f32_fp8_e32 v[214:215], v154
	v_cvt_pk_f32_fp8_sdwa v[216:217], v154 src0_sel:WORD_1
	v_pk_fma_f32 v[222:223], v[68:69], v[218:219], v[222:223]
	v_pk_fma_f32 v[224:225], v[70:71], v[220:221], v[224:225]
	v_cvt_pk_f32_fp8_e32 v[218:219], v155
	v_cvt_pk_f32_fp8_sdwa v[220:221], v155 src0_sel:WORD_1
	v_pk_fma_f32 v[222:223], v[72:73], v[214:215], v[222:223]
	v_pk_fma_f32 v[224:225], v[74:75], v[216:217], v[224:225]
	v_pk_fma_f32 v[222:223], v[76:77], v[218:219], v[222:223]
	v_pk_fma_f32 v[224:225], v[78:79], v[220:221], v[224:225]
	v_pk_add_f32 v[222:223], v[222:223], v[224:225]
	s_nop 0
	v_add_f32_e32 v228, v222, v223
	v_cvt_pk_f32_fp8_e32 v[214:215], v156
	v_cvt_pk_f32_fp8_sdwa v[216:217], v156 src0_sel:WORD_1
	v_cvt_pk_f32_fp8_e32 v[218:219], v157
	v_cvt_pk_f32_fp8_sdwa v[220:221], v157 src0_sel:WORD_1
	v_pk_mul_f32 v[222:223], v[64:65], v[214:215]
	v_pk_mul_f32 v[224:225], v[66:67], v[216:217]
	v_cvt_pk_f32_fp8_e32 v[214:215], v158
	v_cvt_pk_f32_fp8_sdwa v[216:217], v158 src0_sel:WORD_1
	v_pk_fma_f32 v[222:223], v[68:69], v[218:219], v[222:223]
	v_pk_fma_f32 v[224:225], v[70:71], v[220:221], v[224:225]
	v_cvt_pk_f32_fp8_e32 v[218:219], v159
	v_cvt_pk_f32_fp8_sdwa v[220:221], v159 src0_sel:WORD_1
	v_pk_fma_f32 v[222:223], v[72:73], v[214:215], v[222:223]
	v_pk_fma_f32 v[224:225], v[74:75], v[216:217], v[224:225]
	v_pk_fma_f32 v[222:223], v[76:77], v[218:219], v[222:223]
	v_pk_fma_f32 v[224:225], v[78:79], v[220:221], v[224:225]
	v_pk_add_f32 v[222:223], v[222:223], v[224:225]
	s_nop 0
	v_add_f32_e32 v229, v222, v223
	v_cvt_pk_f32_fp8_e32 v[214:215], v160
	v_cvt_pk_f32_fp8_sdwa v[216:217], v160 src0_sel:WORD_1
	v_cvt_pk_f32_fp8_e32 v[218:219], v161
	v_cvt_pk_f32_fp8_sdwa v[220:221], v161 src0_sel:WORD_1
	v_pk_mul_f32 v[222:223], v[64:65], v[214:215]
	v_pk_mul_f32 v[224:225], v[66:67], v[216:217]
	v_cvt_pk_f32_fp8_e32 v[214:215], v162
	v_cvt_pk_f32_fp8_sdwa v[216:217], v162 src0_sel:WORD_1
; template <bool STORE>
; DI void peer_item(const Params& p, int item, char* smem) {
;     ...
; #pragma unroll
;       for (int u = 0; u < 8; ++u) {
;         int e = e_s[tl * 128 + k + u];
;         uq[u] = *(const u32x4*)(U8 + (size_t)e * 1024 + lane * 16);
;       }
;       float part[8];
; #pragma unroll
;       for (int u = 0; u < 8; ++u) {
;         float d = 0.f;
; #pragma unroll
;         for (int i = 0; i < 4; ++i) {
;           f32x2_t lo = __builtin_amdgcn_cvt_pk_f32_fp8((int)uq[u][i], false);
;           f32x2_t hi = __builtin_amdgcn_cvt_pk_f32_fp8((int)uq[u][i], true);
;           d += xf[4 * i] * lo.x + xf[4 * i + 1] * lo.y + xf[4 * i + 2] * hi.x + xf[4 * i + 3] * hi.y;
;         }
;         part[u] = d;
;       }
;       float q4[4], r2[2], h;
; #pragma unroll
;       for (int j = 0; j < 4; ++j) {
;         float mine = b5 ? part[j + 4] : part[j];
;         float other = b5 ? part[j] : part[j + 4];
;         q4[j] = mine + __shfl_xor(other, 32);
;       }
; #pragma unroll
;       for (int j = 0; j < 2; ++j) {
;         float mine = b4 ? q4[j + 2] : q4[j];
;         float other = b4 ? q4[j] : q4[j + 2];
;         r2[j] = mine + __shfl_xor(other, 16);
;       }
;       {
;         float mine = b3 ? r2[1] : r2[0];
;         float other = b3 ? r2[0] : r2[1];
;         h = mine + __shfl_xor(other, 8);
;       }
;       h += __shfl_xor(h, 4);
;       h += __shfl_xor(h, 2);
;       h += __shfl_xor(h, 1);
	v_pk_fma_f32 v[222:223], v[68:69], v[218:219], v[222:223]
	v_pk_fma_f32 v[224:225], v[70:71], v[220:221], v[224:225]
	v_cvt_pk_f32_fp8_e32 v[218:219], v163
	v_cvt_pk_f32_fp8_sdwa v[220:221], v163 src0_sel:WORD_1
	v_pk_fma_f32 v[222:223], v[72:73], v[214:215], v[222:223]
	v_pk_fma_f32 v[224:225], v[74:75], v[216:217], v[224:225]
	v_pk_fma_f32 v[222:223], v[76:77], v[218:219], v[222:223]
	v_pk_fma_f32 v[224:225], v[78:79], v[220:221], v[224:225]
	v_pk_add_f32 v[222:223], v[222:223], v[224:225]
	s_nop 0
	v_add_f32_e32 v230, v222, v223
	v_cvt_pk_f32_fp8_e32 v[214:215], v164
	v_cvt_pk_f32_fp8_sdwa v[216:217], v164 src0_sel:WORD_1
	v_cvt_pk_f32_fp8_e32 v[218:219], v165
	v_cvt_pk_f32_fp8_sdwa v[220:221], v165 src0_sel:WORD_1
	v_pk_mul_f32 v[222:223], v[64:65], v[214:215]
	v_pk_mul_f32 v[224:225], v[66:67], v[216:217]
	v_cvt_pk_f32_fp8_e32 v[214:215], v166
	v_cvt_pk_f32_fp8_sdwa v[216:217], v166 src0_sel:WORD_1
	v_pk_fma_f32 v[222:223], v[68:69], v[218:219], v[222:223]
	v_pk_fma_f32 v[224:225], v[70:71], v[220:221], v[224:225]
	v_cvt_pk_f32_fp8_e32 v[218:219], v167
	v_cvt_pk_f32_fp8_sdwa v[220:221], v167 src0_sel:WORD_1
	v_pk_fma_f32 v[222:223], v[72:73], v[214:215], v[222:223]
	v_pk_fma_f32 v[224:225], v[74:75], v[216:217], v[224:225]
	v_pk_fma_f32 v[222:223], v[76:77], v[218:219], v[222:223]
	v_pk_fma_f32 v[224:225], v[78:79], v[220:221], v[224:225]
	v_pk_add_f32 v[222:223], v[222:223], v[224:225]
	s_nop 0
	v_add_f32_e32 v231, v222, v223
	v_cvt_pk_f32_fp8_e32 v[214:215], v168
	v_cvt_pk_f32_fp8_sdwa v[216:217], v168 src0_sel:WORD_1
	v_cvt_pk_f32_fp8_e32 v[218:219], v169
	v_cvt_pk_f32_fp8_sdwa v[220:221], v169 src0_sel:WORD_1
	v_pk_mul_f32 v[222:223], v[64:65], v[214:215]
	v_pk_mul_f32 v[224:225], v[66:67], v[216:217]
	v_cvt_pk_f32_fp8_e32 v[214:215], v170
	v_cvt_pk_f32_fp8_sdwa v[216:217], v170 src0_sel:WORD_1
	v_pk_fma_f32 v[222:223], v[68:69], v[218:219], v[222:223]
	v_pk_fma_f32 v[224:225], v[70:71], v[220:221], v[224:225]
	v_cvt_pk_f32_fp8_e32 v[218:219], v171
	v_cvt_pk_f32_fp8_sdwa v[220:221], v171 src0_sel:WORD_1
	v_pk_fma_f32 v[222:223], v[72:73], v[214:215], v[222:223]
	v_pk_fma_f32 v[224:225], v[74:75], v[216:217], v[224:225]
	v_pk_fma_f32 v[222:223], v[76:77], v[218:219], v[222:223]
	v_pk_fma_f32 v[224:225], v[78:79], v[220:221], v[224:225]
	v_pk_add_f32 v[222:223], v[222:223], v[224:225]
	s_nop 0
	v_add_f32_e32 v232, v222, v223
	v_cvt_pk_f32_fp8_e32 v[214:215], v172
	v_cvt_pk_f32_fp8_sdwa v[216:217], v172 src0_sel:WORD_1
	v_cvt_pk_f32_fp8_e32 v[218:219], v173
	v_cvt_pk_f32_fp8_sdwa v[220:221], v173 src0_sel:WORD_1
	v_pk_mul_f32 v[222:223], v[64:65], v[214:215]
	v_pk_mul_f32 v[224:225], v[66:67], v[216:217]
	v_cvt_pk_f32_fp8_e32 v[214:215], v174
	v_cvt_pk_f32_fp8_sdwa v[216:217], v174 src0_sel:WORD_1
	v_pk_fma_f32 v[222:223], v[68:69], v[218:219], v[222:223]
	v_pk_fma_f32 v[224:225], v[70:71], v[220:221], v[224:225]
	v_cvt_pk_f32_fp8_e32 v[218:219], v175
	v_cvt_pk_f32_fp8_sdwa v[220:221], v175 src0_sel:WORD_1
	v_pk_fma_f32 v[222:223], v[72:73], v[214:215], v[222:223]
	v_pk_fma_f32 v[224:225], v[74:75], v[216:217], v[224:225]
	v_pk_fma_f32 v[222:223], v[76:77], v[218:219], v[222:223]
	v_pk_fma_f32 v[224:225], v[78:79], v[220:221], v[224:225]
	v_pk_add_f32 v[222:223], v[222:223], v[224:225]
	s_nop 0
	v_add_f32_e32 v233, v222, v223
	v_permlane32_swap_b32_e32 v226, v230
	v_permlane32_swap_b32_e32 v227, v231
	v_permlane32_swap_b32_e32 v228, v232
	v_permlane32_swap_b32_e32 v229, v233
	v_add_f32_e32 v226, v226, v230
	v_add_f32_e32 v228, v228, v232
	v_add_f32_e32 v227, v227, v231
	v_add_f32_e32 v229, v229, v233
	s_nop 1
	v_permlane16_swap_b32_e32 v226, v228
	v_permlane16_swap_b32_e32 v227, v229
	v_add_f32_e32 v226, v226, v228
	v_add_f32_e32 v227, v227, v229
	s_nop 0
	v_cndmask_b32_e64 v230, v226, v227, s[24:25]
	v_cndmask_b32_e64 v231, v227, v226, s[24:25]
	s_nop 1
	v_add_f32_dpp v232, v231, v230 row_ror:8 row_mask:0xf bank_mask:0xf
	s_nop 1
	v_add_f32_dpp v233, v232, v232 quad_perm:[1,0,3,2] row_mask:0xf bank_mask:0xf
	s_nop 1
	v_add_f32_dpp v232, v233, v233 quad_perm:[2,3,0,1] row_mask:0xf bank_mask:0xf
	s_nop 1
	v_add_f32_dpp v233, v232, v232 row_half_mirror row_mask:0xf bank_mask:0xf
	ds_write_b32 v235, v233 offset:34848
	v_readlane_b32 s48, v141, s72
	v_readlane_b32 s49, v141, s73
	v_readlane_b32 s50, v141, s74
	v_readlane_b32 s51, v141, s75
	v_readlane_b32 s52, v141, s76
	v_readlane_b32 s53, v141, s77
	v_readlane_b32 s54, v141, s78
	v_readlane_b32 s55, v141, s79
	s_add_u32 s32, s0, s48
	s_addc_u32 s33, s1, 0
	s_add_u32 s34, s0, s49
	s_addc_u32 s35, s1, 0
	s_add_u32 s36, s0, s50
	s_addc_u32 s37, s1, 0
	s_add_u32 s38, s0, s51
	s_addc_u32 s39, s1, 0
	s_add_u32 s40, s0, s52
	s_addc_u32 s41, s1, 0
	s_add_u32 s42, s0, s53
	s_addc_u32 s43, s1, 0
	s_add_u32 s44, s0, s54
	s_addc_u32 s45, s1, 0
	s_add_u32 s46, s0, s55
	s_addc_u32 s47, s1, 0
	global_load_dwordx4 v[144:147], v234, s[32:33]
	global_load_dwordx4 v[148:151], v234, s[34:35]
	global_load_dwordx4 v[152:155], v234, s[36:37]
	global_load_dwordx4 v[156:159], v234, s[38:39]
	global_load_dwordx4 v[160:163], v234, s[40:41]
	global_load_dwordx4 v[164:167], v234, s[42:43]
	global_load_dwordx4 v[168:171], v234, s[44:45]
	global_load_dwordx4 v[172:175], v234, s[46:47]
	s_waitcnt vmcnt(8)
; template <bool STORE>
; DI void peer_item(const Params& p, int item, char* smem) {
;     ...
; #pragma unroll
;       for (int u = 0; u < 8; ++u) {
;         float d = 0.f;
; #pragma unroll
;         for (int i = 0; i < 4; ++i) {
;           f32x2_t lo = __builtin_amdgcn_cvt_pk_f32_fp8((int)uq[u][i], false);
;           f32x2_t hi = __builtin_amdgcn_cvt_pk_f32_fp8((int)uq[u][i], true);
;           d += xf[4 * i] * lo.x + xf[4 * i + 1] * lo.y + xf[4 * i + 2] * hi.x + xf[4 * i + 3] * hi.y;
;         }
;         part[u] = d;
;       }
	v_cvt_pk_f32_fp8_e32 v[214:215], v176
	v_cvt_pk_f32_fp8_sdwa v[216:217], v176 src0_sel:WORD_1
	v_cvt_pk_f32_fp8_e32 v[218:219], v177
	v_cvt_pk_f32_fp8_sdwa v[220:221], v177 src0_sel:WORD_1
	v_pk_mul_f32 v[222:223], v[80:81], v[214:215]
	v_pk_mul_f32 v[224:225], v[82:83], v[216:217]
	v_cvt_pk_f32_fp8_e32 v[214:215], v178
	v_cvt_pk_f32_fp8_sdwa v[216:217], v178 src0_sel:WORD_1
	v_pk_fma_f32 v[222:223], v[84:85], v[218:219], v[222:223]
	v_pk_fma_f32 v[224:225], v[86:87], v[220:221], v[224:225]
	v_cvt_pk_f32_fp8_e32 v[218:219], v179
	v_cvt_pk_f32_fp8_sdwa v[220:221], v179 src0_sel:WORD_1
	v_pk_fma_f32 v[222:223], v[88:89], v[214:215], v[222:223]
	v_pk_fma_f32 v[224:225], v[90:91], v[216:217], v[224:225]
	v_pk_fma_f32 v[222:223], v[92:93], v[218:219], v[222:223]
	v_pk_fma_f32 v[224:225], v[94:95], v[220:221], v[224:225]
	v_pk_add_f32 v[222:223], v[222:223], v[224:225]
	s_nop 0
	v_add_f32_e32 v226, v222, v223
	v_cvt_pk_f32_fp8_e32 v[214:215], v180
	v_cvt_pk_f32_fp8_sdwa v[216:217], v180 src0_sel:WORD_1
	v_cvt_pk_f32_fp8_e32 v[218:219], v181
	v_cvt_pk_f32_fp8_sdwa v[220:221], v181 src0_sel:WORD_1
	v_pk_mul_f32 v[222:223], v[80:81], v[214:215]
	v_pk_mul_f32 v[224:225], v[82:83], v[216:217]
	v_cvt_pk_f32_fp8_e32 v[214:215], v182
	v_cvt_pk_f32_fp8_sdwa v[216:217], v182 src0_sel:WORD_1
	v_pk_fma_f32 v[222:223], v[84:85], v[218:219], v[222:223]
	v_pk_fma_f32 v[224:225], v[86:87], v[220:221], v[224:225]
	v_cvt_pk_f32_fp8_e32 v[218:219], v183
	v_cvt_pk_f32_fp8_sdwa v[220:221], v183 src0_sel:WORD_1
	v_pk_fma_f32 v[222:223], v[88:89], v[214:215], v[222:223]
	v_pk_fma_f32 v[224:225], v[90:91], v[216:217], v[224:225]
	v_pk_fma_f32 v[222:223], v[92:93], v[218:219], v[222:223]
	v_pk_fma_f32 v[224:225], v[94:95], v[220:221], v[224:225]
	v_pk_add_f32 v[222:223], v[222:223], v[224:225]
	s_nop 0
	v_add_f32_e32 v227, v222, v223
	v_cvt_pk_f32_fp8_e32 v[214:215], v184
	v_cvt_pk_f32_fp8_sdwa v[216:217], v184 src0_sel:WORD_1
	v_cvt_pk_f32_fp8_e32 v[218:219], v185
	v_cvt_pk_f32_fp8_sdwa v[220:221], v185 src0_sel:WORD_1
	v_pk_mul_f32 v[222:223], v[80:81], v[214:215]
	v_pk_mul_f32 v[224:225], v[82:83], v[216:217]
	v_cvt_pk_f32_fp8_e32 v[214:215], v186
	v_cvt_pk_f32_fp8_sdwa v[216:217], v186 src0_sel:WORD_1
	v_pk_fma_f32 v[222:223], v[84:85], v[218:219], v[222:223]
	v_pk_fma_f32 v[224:225], v[86:87], v[220:221], v[224:225]
	v_cvt_pk_f32_fp8_e32 v[218:219], v187
	v_cvt_pk_f32_fp8_sdwa v[220:221], v187 src0_sel:WORD_1
	v_pk_fma_f32 v[222:223], v[88:89], v[214:215], v[222:223]
	v_pk_fma_f32 v[224:225], v[90:91], v[216:217], v[224:225]
	v_pk_fma_f32 v[222:223], v[92:93], v[218:219], v[222:223]
	v_pk_fma_f32 v[224:225], v[94:95], v[220:221], v[224:225]
	v_pk_add_f32 v[222:223], v[222:223], v[224:225]
	s_nop 0
	v_add_f32_e32 v228, v222, v223
	v_cvt_pk_f32_fp8_e32 v[214:215], v188
	v_cvt_pk_f32_fp8_sdwa v[216:217], v188 src0_sel:WORD_1
	v_cvt_pk_f32_fp8_e32 v[218:219], v189
	v_cvt_pk_f32_fp8_sdwa v[220:221], v189 src0_sel:WORD_1
	v_pk_mul_f32 v[222:223], v[80:81], v[214:215]
	v_pk_mul_f32 v[224:225], v[82:83], v[216:217]
	v_cvt_pk_f32_fp8_e32 v[214:215], v190
	v_cvt_pk_f32_fp8_sdwa v[216:217], v190 src0_sel:WORD_1
	v_pk_fma_f32 v[222:223], v[84:85], v[218:219], v[222:223]
	v_pk_fma_f32 v[224:225], v[86:87], v[220:221], v[224:225]
	v_cvt_pk_f32_fp8_e32 v[218:219], v191
	v_cvt_pk_f32_fp8_sdwa v[220:221], v191 src0_sel:WORD_1
	v_pk_fma_f32 v[222:223], v[88:89], v[214:215], v[222:223]
	v_pk_fma_f32 v[224:225], v[90:91], v[216:217], v[224:225]
	v_pk_fma_f32 v[222:223], v[92:93], v[218:219], v[222:223]
	v_pk_fma_f32 v[224:225], v[94:95], v[220:221], v[224:225]
	v_pk_add_f32 v[222:223], v[222:223], v[224:225]
	s_nop 0
	v_add_f32_e32 v229, v222, v223
	v_cvt_pk_f32_fp8_e32 v[214:215], v192
	v_cvt_pk_f32_fp8_sdwa v[216:217], v192 src0_sel:WORD_1
	v_cvt_pk_f32_fp8_e32 v[218:219], v193
	v_cvt_pk_f32_fp8_sdwa v[220:221], v193 src0_sel:WORD_1
	v_pk_mul_f32 v[222:223], v[80:81], v[214:215]
	v_pk_mul_f32 v[224:225], v[82:83], v[216:217]
	v_cvt_pk_f32_fp8_e32 v[214:215], v194
	v_cvt_pk_f32_fp8_sdwa v[216:217], v194 src0_sel:WORD_1
	v_pk_fma_f32 v[222:223], v[84:85], v[218:219], v[222:223]
	v_pk_fma_f32 v[224:225], v[86:87], v[220:221], v[224:225]
	v_cvt_pk_f32_fp8_e32 v[218:219], v195
	v_cvt_pk_f32_fp8_sdwa v[220:221], v195 src0_sel:WORD_1
	v_pk_fma_f32 v[222:223], v[88:89], v[214:215], v[222:223]
	v_pk_fma_f32 v[224:225], v[90:91], v[216:217], v[224:225]
	v_pk_fma_f32 v[222:223], v[92:93], v[218:219], v[222:223]
	v_pk_fma_f32 v[224:225], v[94:95], v[220:221], v[224:225]
	v_pk_add_f32 v[222:223], v[222:223], v[224:225]
	s_nop 0
	v_add_f32_e32 v230, v222, v223
	v_cvt_pk_f32_fp8_e32 v[214:215], v196
	v_cvt_pk_f32_fp8_sdwa v[216:217], v196 src0_sel:WORD_1
	v_cvt_pk_f32_fp8_e32 v[218:219], v197
	v_cvt_pk_f32_fp8_sdwa v[220:221], v197 src0_sel:WORD_1
	v_pk_mul_f32 v[222:223], v[80:81], v[214:215]
	v_pk_mul_f32 v[224:225], v[82:83], v[216:217]
	v_cvt_pk_f32_fp8_e32 v[214:215], v198
	v_cvt_pk_f32_fp8_sdwa v[216:217], v198 src0_sel:WORD_1
	v_pk_fma_f32 v[222:223], v[84:85], v[218:219], v[222:223]
	v_pk_fma_f32 v[224:225], v[86:87], v[220:221], v[224:225]
	v_cvt_pk_f32_fp8_e32 v[218:219], v199
	v_cvt_pk_f32_fp8_sdwa v[220:221], v199 src0_sel:WORD_1
	v_pk_fma_f32 v[222:223], v[88:89], v[214:215], v[222:223]
	v_pk_fma_f32 v[224:225], v[90:91], v[216:217], v[224:225]
	v_pk_fma_f32 v[222:223], v[92:93], v[218:219], v[222:223]
	v_pk_fma_f32 v[224:225], v[94:95], v[220:221], v[224:225]
	v_pk_add_f32 v[222:223], v[222:223], v[224:225]
	s_nop 0
	v_add_f32_e32 v231, v222, v223
	v_cvt_pk_f32_fp8_e32 v[214:215], v200
	v_cvt_pk_f32_fp8_sdwa v[216:217], v200 src0_sel:WORD_1
	v_cvt_pk_f32_fp8_e32 v[218:219], v201
; template <bool STORE>
; DI void peer_item(const Params& p, int item, char* smem) {
;     ...
; #pragma unroll
;       for (int u = 0; u < 8; ++u) {
;         int e = e_s[tl * 128 + k + u];
;         uq[u] = *(const u32x4*)(U8 + (size_t)e * 1024 + lane * 16);
;       }
;       float part[8];
; #pragma unroll
;       for (int u = 0; u < 8; ++u) {
;         float d = 0.f;
; #pragma unroll
;         for (int i = 0; i < 4; ++i) {
;           f32x2_t lo = __builtin_amdgcn_cvt_pk_f32_fp8((int)uq[u][i], false);
;           f32x2_t hi = __builtin_amdgcn_cvt_pk_f32_fp8((int)uq[u][i], true);
;           d += xf[4 * i] * lo.x + xf[4 * i + 1] * lo.y + xf[4 * i + 2] * hi.x + xf[4 * i + 3] * hi.y;
;         }
;         part[u] = d;
;       }
;       float q4[4], r2[2], h;
; #pragma unroll
;       for (int j = 0; j < 4; ++j) {
;         float mine = b5 ? part[j + 4] : part[j];
;         float other = b5 ? part[j] : part[j + 4];
;         q4[j] = mine + __shfl_xor(other, 32);
;       }
; #pragma unroll
;       for (int j = 0; j < 2; ++j) {
;         float mine = b4 ? q4[j + 2] : q4[j];
;         float other = b4 ? q4[j] : q4[j + 2];
;         r2[j] = mine + __shfl_xor(other, 16);
;       }
;       {
;         float mine = b3 ? r2[1] : r2[0];
;         float other = b3 ? r2[0] : r2[1];
;         h = mine + __shfl_xor(other, 8);
;       }
;       h += __shfl_xor(h, 4);
;       h += __shfl_xor(h, 2);
;       h += __shfl_xor(h, 1);
	v_cvt_pk_f32_fp8_sdwa v[220:221], v201 src0_sel:WORD_1
	v_pk_mul_f32 v[222:223], v[80:81], v[214:215]
	v_pk_mul_f32 v[224:225], v[82:83], v[216:217]
	v_cvt_pk_f32_fp8_e32 v[214:215], v202
	v_cvt_pk_f32_fp8_sdwa v[216:217], v202 src0_sel:WORD_1
	v_pk_fma_f32 v[222:223], v[84:85], v[218:219], v[222:223]
	v_pk_fma_f32 v[224:225], v[86:87], v[220:221], v[224:225]
	v_cvt_pk_f32_fp8_e32 v[218:219], v203
	v_cvt_pk_f32_fp8_sdwa v[220:221], v203 src0_sel:WORD_1
	v_pk_fma_f32 v[222:223], v[88:89], v[214:215], v[222:223]
	v_pk_fma_f32 v[224:225], v[90:91], v[216:217], v[224:225]
	v_pk_fma_f32 v[222:223], v[92:93], v[218:219], v[222:223]
	v_pk_fma_f32 v[224:225], v[94:95], v[220:221], v[224:225]
	v_pk_add_f32 v[222:223], v[222:223], v[224:225]
	s_nop 0
	v_add_f32_e32 v232, v222, v223
	v_cvt_pk_f32_fp8_e32 v[214:215], v204
	v_cvt_pk_f32_fp8_sdwa v[216:217], v204 src0_sel:WORD_1
	v_cvt_pk_f32_fp8_e32 v[218:219], v205
	v_cvt_pk_f32_fp8_sdwa v[220:221], v205 src0_sel:WORD_1
	v_pk_mul_f32 v[222:223], v[80:81], v[214:215]
	v_pk_mul_f32 v[224:225], v[82:83], v[216:217]
	v_cvt_pk_f32_fp8_e32 v[214:215], v206
	v_cvt_pk_f32_fp8_sdwa v[216:217], v206 src0_sel:WORD_1
	v_pk_fma_f32 v[222:223], v[84:85], v[218:219], v[222:223]
	v_pk_fma_f32 v[224:225], v[86:87], v[220:221], v[224:225]
	v_cvt_pk_f32_fp8_e32 v[218:219], v207
	v_cvt_pk_f32_fp8_sdwa v[220:221], v207 src0_sel:WORD_1
	v_pk_fma_f32 v[222:223], v[88:89], v[214:215], v[222:223]
	v_pk_fma_f32 v[224:225], v[90:91], v[216:217], v[224:225]
	v_pk_fma_f32 v[222:223], v[92:93], v[218:219], v[222:223]
	v_pk_fma_f32 v[224:225], v[94:95], v[220:221], v[224:225]
	v_pk_add_f32 v[222:223], v[222:223], v[224:225]
	s_nop 0
	v_add_f32_e32 v233, v222, v223
	v_permlane32_swap_b32_e32 v226, v230
	v_permlane32_swap_b32_e32 v227, v231
	v_permlane32_swap_b32_e32 v228, v232
	v_permlane32_swap_b32_e32 v229, v233
	v_add_f32_e32 v226, v226, v230
	v_add_f32_e32 v228, v228, v232
	v_add_f32_e32 v227, v227, v231
	v_add_f32_e32 v229, v229, v233
	s_nop 1
	v_permlane16_swap_b32_e32 v226, v228
	v_permlane16_swap_b32_e32 v227, v229
	v_add_f32_e32 v226, v226, v228
	v_add_f32_e32 v227, v227, v229
	s_nop 0
	v_cndmask_b32_e64 v230, v226, v227, s[24:25]
	v_cndmask_b32_e64 v231, v227, v226, s[24:25]
	s_nop 1
	v_add_f32_dpp v232, v231, v230 row_ror:8 row_mask:0xf bank_mask:0xf
	s_nop 1
	v_add_f32_dpp v233, v232, v232 quad_perm:[1,0,3,2] row_mask:0xf bank_mask:0xf
	s_nop 1
	v_add_f32_dpp v232, v233, v233 quad_perm:[2,3,0,1] row_mask:0xf bank_mask:0xf
	s_nop 1
	v_add_f32_dpp v233, v232, v232 row_half_mirror row_mask:0xf bank_mask:0xf
	ds_write_b32 v235, v233 offset:35360
	v_readlane_b32 s48, v143, s72
	v_readlane_b32 s49, v143, s73
	v_readlane_b32 s50, v143, s74
	v_readlane_b32 s51, v143, s75
	v_readlane_b32 s52, v143, s76
	v_readlane_b32 s53, v143, s77
	v_readlane_b32 s54, v143, s78
	v_readlane_b32 s55, v143, s79
	s_add_u32 s32, s0, s48
	s_addc_u32 s33, s1, 0
	s_add_u32 s34, s0, s49
	s_addc_u32 s35, s1, 0
	s_add_u32 s36, s0, s50
	s_addc_u32 s37, s1, 0
	s_add_u32 s38, s0, s51
	s_addc_u32 s39, s1, 0
	s_add_u32 s40, s0, s52
	s_addc_u32 s41, s1, 0
	s_add_u32 s42, s0, s53
	s_addc_u32 s43, s1, 0
	s_add_u32 s44, s0, s54
	s_addc_u32 s45, s1, 0
	s_add_u32 s46, s0, s55
	s_addc_u32 s47, s1, 0
	global_load_dwordx4 v[176:179], v234, s[32:33]
	global_load_dwordx4 v[180:183], v234, s[34:35]
	global_load_dwordx4 v[184:187], v234, s[36:37]
	global_load_dwordx4 v[188:191], v234, s[38:39]
	global_load_dwordx4 v[192:195], v234, s[40:41]
	global_load_dwordx4 v[196:199], v234, s[42:43]
	global_load_dwordx4 v[200:203], v234, s[44:45]
	global_load_dwordx4 v[204:207], v234, s[46:47]
	s_waitcnt vmcnt(8)
	v_cvt_pk_f32_fp8_e32 v[214:215], v144
	v_cvt_pk_f32_fp8_sdwa v[216:217], v144 src0_sel:WORD_1
	v_cvt_pk_f32_fp8_e32 v[218:219], v145
	v_cvt_pk_f32_fp8_sdwa v[220:221], v145 src0_sel:WORD_1
	v_pk_mul_f32 v[222:223], v[96:97], v[214:215]
	v_pk_mul_f32 v[224:225], v[98:99], v[216:217]
	v_cvt_pk_f32_fp8_e32 v[214:215], v146
	v_cvt_pk_f32_fp8_sdwa v[216:217], v146 src0_sel:WORD_1
	v_pk_fma_f32 v[222:223], v[100:101], v[218:219], v[222:223]
	v_pk_fma_f32 v[224:225], v[102:103], v[220:221], v[224:225]
	v_cvt_pk_f32_fp8_e32 v[218:219], v147
	v_cvt_pk_f32_fp8_sdwa v[220:221], v147 src0_sel:WORD_1
	v_pk_fma_f32 v[222:223], v[104:105], v[214:215], v[222:223]
	v_pk_fma_f32 v[224:225], v[106:107], v[216:217], v[224:225]
	v_pk_fma_f32 v[222:223], v[108:109], v[218:219], v[222:223]
	v_pk_fma_f32 v[224:225], v[110:111], v[220:221], v[224:225]
	v_pk_add_f32 v[222:223], v[222:223], v[224:225]
	s_nop 0
	v_add_f32_e32 v226, v222, v223
	v_cvt_pk_f32_fp8_e32 v[214:215], v148
	v_cvt_pk_f32_fp8_sdwa v[216:217], v148 src0_sel:WORD_1
	v_cvt_pk_f32_fp8_e32 v[218:219], v149
	v_cvt_pk_f32_fp8_sdwa v[220:221], v149 src0_sel:WORD_1
	v_pk_mul_f32 v[222:223], v[96:97], v[214:215]
	v_pk_mul_f32 v[224:225], v[98:99], v[216:217]
	v_cvt_pk_f32_fp8_e32 v[214:215], v150
	v_cvt_pk_f32_fp8_sdwa v[216:217], v150 src0_sel:WORD_1
	v_pk_fma_f32 v[222:223], v[100:101], v[218:219], v[222:223]
	v_pk_fma_f32 v[224:225], v[102:103], v[220:221], v[224:225]
	v_cvt_pk_f32_fp8_e32 v[218:219], v151
	v_cvt_pk_f32_fp8_sdwa v[220:221], v151 src0_sel:WORD_1
	v_pk_fma_f32 v[222:223], v[104:105], v[214:215], v[222:223]
	v_pk_fma_f32 v[224:225], v[106:107], v[216:217], v[224:225]
	v_pk_fma_f32 v[222:223], v[108:109], v[218:219], v[222:223]
	v_pk_fma_f32 v[224:225], v[110:111], v[220:221], v[224:225]
	v_pk_add_f32 v[222:223], v[222:223], v[224:225]
	s_nop 0
	v_add_f32_e32 v227, v222, v223
	v_cvt_pk_f32_fp8_e32 v[214:215], v152
	v_cvt_pk_f32_fp8_sdwa v[216:217], v152 src0_sel:WORD_1
	v_cvt_pk_f32_fp8_e32 v[218:219], v153
; DI float gelu_exact(float x) { return 0.5f * x * (1.f + erff(x * 0.7071067811865476f)); }
; template <bool STORE>
; DI void peer_item(const Params& p, int item, char* smem) {
;     ...
; #pragma unroll
;       for (int u = 0; u < 8; ++u) {
;         float d = 0.f;
; #pragma unroll
;         for (int i = 0; i < 4; ++i) {
;           f32x2_t lo = __builtin_amdgcn_cvt_pk_f32_fp8((int)uq[u][i], false);
;           f32x2_t hi = __builtin_amdgcn_cvt_pk_f32_fp8((int)uq[u][i], true);
;           d += xf[4 * i] * lo.x + xf[4 * i + 1] * lo.y + xf[4 * i + 2] * hi.x + xf[4 * i + 3] * hi.y;
;         }
;         part[u] = d;
;       }
;       float q4[4], r2[2], h;
; #pragma unroll
;       for (int j = 0; j < 4; ++j) {
;         float mine = b5 ? part[j + 4] : part[j];
;         float other = b5 ? part[j] : part[j + 4];
;         q4[j] = mine + __shfl_xor(other, 32);
;       }
; #pragma unroll
;       for (int j = 0; j < 2; ++j) {
;         float mine = b4 ? q4[j + 2] : q4[j];
;         float other = b4 ? q4[j] : q4[j + 2];
;         r2[j] = mine + __shfl_xor(other, 16);
;       }
;       {
;         float mine = b3 ? r2[1] : r2[0];
;         float other = b3 ? r2[0] : r2[1];
;         h = mine + __shfl_xor(other, 8);
;       }
;       h += __shfl_xor(h, 4);
;       h += __shfl_xor(h, 2);
;       h += __shfl_xor(h, 1);
;       const float amine = gelu_exact(h * su) * gmine * sv;
;       if ((lane & 7) == 0) {
;         EG[tok * 128 + k + (lane >> 3)] = emine;
;         AG[tok * 128 + k + (lane >> 3)] = amine;
;       }
;     }
	v_cvt_pk_f32_fp8_sdwa v[220:221], v153 src0_sel:WORD_1
	v_pk_mul_f32 v[222:223], v[96:97], v[214:215]
	v_pk_mul_f32 v[224:225], v[98:99], v[216:217]
	v_cvt_pk_f32_fp8_e32 v[214:215], v154
	v_cvt_pk_f32_fp8_sdwa v[216:217], v154 src0_sel:WORD_1
	v_pk_fma_f32 v[222:223], v[100:101], v[218:219], v[222:223]
	v_pk_fma_f32 v[224:225], v[102:103], v[220:221], v[224:225]
	v_cvt_pk_f32_fp8_e32 v[218:219], v155
	v_cvt_pk_f32_fp8_sdwa v[220:221], v155 src0_sel:WORD_1
	v_pk_fma_f32 v[222:223], v[104:105], v[214:215], v[222:223]
	v_pk_fma_f32 v[224:225], v[106:107], v[216:217], v[224:225]
	v_pk_fma_f32 v[222:223], v[108:109], v[218:219], v[222:223]
	v_pk_fma_f32 v[224:225], v[110:111], v[220:221], v[224:225]
	v_pk_add_f32 v[222:223], v[222:223], v[224:225]
	s_nop 0
	v_add_f32_e32 v228, v222, v223
	v_cvt_pk_f32_fp8_e32 v[214:215], v156
	v_cvt_pk_f32_fp8_sdwa v[216:217], v156 src0_sel:WORD_1
	v_cvt_pk_f32_fp8_e32 v[218:219], v157
	v_cvt_pk_f32_fp8_sdwa v[220:221], v157 src0_sel:WORD_1
	v_pk_mul_f32 v[222:223], v[96:97], v[214:215]
	v_pk_mul_f32 v[224:225], v[98:99], v[216:217]
	v_cvt_pk_f32_fp8_e32 v[214:215], v158
	v_cvt_pk_f32_fp8_sdwa v[216:217], v158 src0_sel:WORD_1
	v_pk_fma_f32 v[222:223], v[100:101], v[218:219], v[222:223]
	v_pk_fma_f32 v[224:225], v[102:103], v[220:221], v[224:225]
	v_cvt_pk_f32_fp8_e32 v[218:219], v159
	v_cvt_pk_f32_fp8_sdwa v[220:221], v159 src0_sel:WORD_1
	v_pk_fma_f32 v[222:223], v[104:105], v[214:215], v[222:223]
	v_pk_fma_f32 v[224:225], v[106:107], v[216:217], v[224:225]
	v_pk_fma_f32 v[222:223], v[108:109], v[218:219], v[222:223]
	v_pk_fma_f32 v[224:225], v[110:111], v[220:221], v[224:225]
	v_pk_add_f32 v[222:223], v[222:223], v[224:225]
	s_nop 0
	v_add_f32_e32 v229, v222, v223
	v_cvt_pk_f32_fp8_e32 v[214:215], v160
	v_cvt_pk_f32_fp8_sdwa v[216:217], v160 src0_sel:WORD_1
	v_cvt_pk_f32_fp8_e32 v[218:219], v161
	v_cvt_pk_f32_fp8_sdwa v[220:221], v161 src0_sel:WORD_1
	v_pk_mul_f32 v[222:223], v[96:97], v[214:215]
	v_pk_mul_f32 v[224:225], v[98:99], v[216:217]
	v_cvt_pk_f32_fp8_e32 v[214:215], v162
	v_cvt_pk_f32_fp8_sdwa v[216:217], v162 src0_sel:WORD_1
	v_pk_fma_f32 v[222:223], v[100:101], v[218:219], v[222:223]
	v_pk_fma_f32 v[224:225], v[102:103], v[220:221], v[224:225]
	v_cvt_pk_f32_fp8_e32 v[218:219], v163
	v_cvt_pk_f32_fp8_sdwa v[220:221], v163 src0_sel:WORD_1
	v_pk_fma_f32 v[222:223], v[104:105], v[214:215], v[222:223]
	v_pk_fma_f32 v[224:225], v[106:107], v[216:217], v[224:225]
	v_pk_fma_f32 v[222:223], v[108:109], v[218:219], v[222:223]
	v_pk_fma_f32 v[224:225], v[110:111], v[220:221], v[224:225]
	v_pk_add_f32 v[222:223], v[222:223], v[224:225]
	s_nop 0
	v_add_f32_e32 v230, v222, v223
	v_cvt_pk_f32_fp8_e32 v[214:215], v164
	v_cvt_pk_f32_fp8_sdwa v[216:217], v164 src0_sel:WORD_1
	v_cvt_pk_f32_fp8_e32 v[218:219], v165
	v_cvt_pk_f32_fp8_sdwa v[220:221], v165 src0_sel:WORD_1
	v_pk_mul_f32 v[222:223], v[96:97], v[214:215]
	v_pk_mul_f32 v[224:225], v[98:99], v[216:217]
	v_cvt_pk_f32_fp8_e32 v[214:215], v166
	v_cvt_pk_f32_fp8_sdwa v[216:217], v166 src0_sel:WORD_1
	v_pk_fma_f32 v[222:223], v[100:101], v[218:219], v[222:223]
	v_pk_fma_f32 v[224:225], v[102:103], v[220:221], v[224:225]
	v_cvt_pk_f32_fp8_e32 v[218:219], v167
	v_cvt_pk_f32_fp8_sdwa v[220:221], v167 src0_sel:WORD_1
	v_pk_fma_f32 v[222:223], v[104:105], v[214:215], v[222:223]
	v_pk_fma_f32 v[224:225], v[106:107], v[216:217], v[224:225]
	v_pk_fma_f32 v[222:223], v[108:109], v[218:219], v[222:223]
	v_pk_fma_f32 v[224:225], v[110:111], v[220:221], v[224:225]
	v_pk_add_f32 v[222:223], v[222:223], v[224:225]
	s_nop 0
	v_add_f32_e32 v231, v222, v223
	v_cvt_pk_f32_fp8_e32 v[214:215], v168
	v_cvt_pk_f32_fp8_sdwa v[216:217], v168 src0_sel:WORD_1
	v_cvt_pk_f32_fp8_e32 v[218:219], v169
	v_cvt_pk_f32_fp8_sdwa v[220:221], v169 src0_sel:WORD_1
	v_pk_mul_f32 v[222:223], v[96:97], v[214:215]
	v_pk_mul_f32 v[224:225], v[98:99], v[216:217]
	v_cvt_pk_f32_fp8_e32 v[214:215], v170
	v_cvt_pk_f32_fp8_sdwa v[216:217], v170 src0_sel:WORD_1
	v_pk_fma_f32 v[222:223], v[100:101], v[218:219], v[222:223]
	v_pk_fma_f32 v[224:225], v[102:103], v[220:221], v[224:225]
	v_cvt_pk_f32_fp8_e32 v[218:219], v171
	v_cvt_pk_f32_fp8_sdwa v[220:221], v171 src0_sel:WORD_1
	v_pk_fma_f32 v[222:223], v[104:105], v[214:215], v[222:223]
	v_pk_fma_f32 v[224:225], v[106:107], v[216:217], v[224:225]
	v_pk_fma_f32 v[222:223], v[108:109], v[218:219], v[222:223]
	v_pk_fma_f32 v[224:225], v[110:111], v[220:221], v[224:225]
	v_pk_add_f32 v[222:223], v[222:223], v[224:225]
	s_nop 0
	v_add_f32_e32 v232, v222, v223
	v_cvt_pk_f32_fp8_e32 v[214:215], v172
	v_cvt_pk_f32_fp8_sdwa v[216:217], v172 src0_sel:WORD_1
	v_cvt_pk_f32_fp8_e32 v[218:219], v173
	v_cvt_pk_f32_fp8_sdwa v[220:221], v173 src0_sel:WORD_1
	v_pk_mul_f32 v[222:223], v[96:97], v[214:215]
	v_pk_mul_f32 v[224:225], v[98:99], v[216:217]
	v_cvt_pk_f32_fp8_e32 v[214:215], v174
	v_cvt_pk_f32_fp8_sdwa v[216:217], v174 src0_sel:WORD_1
	v_pk_fma_f32 v[222:223], v[100:101], v[218:219], v[222:223]
	v_pk_fma_f32 v[224:225], v[102:103], v[220:221], v[224:225]
	v_cvt_pk_f32_fp8_e32 v[218:219], v175
	v_cvt_pk_f32_fp8_sdwa v[220:221], v175 src0_sel:WORD_1
	v_pk_fma_f32 v[222:223], v[104:105], v[214:215], v[222:223]
	v_pk_fma_f32 v[224:225], v[106:107], v[216:217], v[224:225]
	v_pk_fma_f32 v[222:223], v[108:109], v[218:219], v[222:223]
	v_pk_fma_f32 v[224:225], v[110:111], v[220:221], v[224:225]
	v_pk_add_f32 v[222:223], v[222:223], v[224:225]
	s_nop 0
	v_add_f32_e32 v233, v222, v223
	v_permlane32_swap_b32_e32 v226, v230
	v_permlane32_swap_b32_e32 v227, v231
	v_permlane32_swap_b32_e32 v228, v232
	v_permlane32_swap_b32_e32 v229, v233
	v_add_f32_e32 v226, v226, v230
	v_add_f32_e32 v228, v228, v232
	v_add_f32_e32 v227, v227, v231
	v_add_f32_e32 v229, v229, v233
	s_nop 1
	v_permlane16_swap_b32_e32 v226, v228
	v_permlane16_swap_b32_e32 v227, v229
	v_add_f32_e32 v226, v226, v228
	v_add_f32_e32 v227, v227, v229
	s_nop 0
	v_cndmask_b32_e64 v230, v226, v227, s[24:25]
	v_cndmask_b32_e64 v231, v227, v226, s[24:25]
	s_nop 1
	v_add_f32_dpp v232, v231, v230 row_ror:8 row_mask:0xf bank_mask:0xf
	s_nop 1
	v_add_f32_dpp v233, v232, v232 quad_perm:[1,0,3,2] row_mask:0xf bank_mask:0xf
	s_nop 1
	v_add_f32_dpp v232, v233, v233 quad_perm:[2,3,0,1] row_mask:0xf bank_mask:0xf
	s_nop 1
	v_add_f32_dpp v233, v232, v232 row_half_mirror row_mask:0xf bank_mask:0xf
	ds_write_b32 v235, v233 offset:35872
	s_add_u32 s72, s72, 8
	s_add_u32 s73, s73, 8
	s_add_u32 s74, s74, 8
	s_add_u32 s75, s75, 8
	s_add_u32 s76, s76, 8
	s_add_u32 s77, s77, 8
	s_add_u32 s78, s78, 8
	s_add_u32 s79, s79, 8
	s_and_b32 s72, s72, 63
	s_and_b32 s73, s73, 63
	s_and_b32 s74, s74, 63
	s_and_b32 s75, s75, 63
	s_and_b32 s76, s76, 63
	s_and_b32 s77, s77, 63
	s_and_b32 s78, s78, 63
	s_and_b32 s79, s79, 63
	s_cmp_eq_u32 s12, 7
	s_cbranch_scc1 .Lup_last
; template <bool STORE>
; DI void peer_item(const Params& p, int item, char* smem) {
;     ...
;       const int emine = e_s[tl * 128 + k + (lane >> 3)];
;       const float gmine = g_s[tl * 128 + k + (lane >> 3)];
;       const float su = SU[emine], sv = SV[emine];
; #pragma unroll
;       for (int u = 0; u < 8; ++u) {
;         int e = e_s[tl * 128 + k + u];
;         uq[u] = *(const u32x4*)(U8 + (size_t)e * 1024 + lane * 16);
;       }
;       float part[8];
; #pragma unroll
;       for (int u = 0; u < 8; ++u) {
;         float d = 0.f;
; #pragma unroll
;         for (int i = 0; i < 4; ++i) {
;           f32x2_t lo = __builtin_amdgcn_cvt_pk_f32_fp8((int)uq[u][i], false);
;           f32x2_t hi = __builtin_amdgcn_cvt_pk_f32_fp8((int)uq[u][i], true);
;           d += xf[4 * i] * lo.x + xf[4 * i + 1] * lo.y + xf[4 * i + 2] * hi.x + xf[4 * i + 3] * hi.y;
;         }
;         part[u] = d;
;       }
	v_readlane_b32 s48, v128, s72
	v_readlane_b32 s49, v128, s73
	v_readlane_b32 s50, v128, s74
	v_readlane_b32 s51, v128, s75
	v_readlane_b32 s52, v128, s76
	v_readlane_b32 s53, v128, s77
	v_readlane_b32 s54, v128, s78
	v_readlane_b32 s55, v128, s79
	s_add_u32 s32, s0, s48
	s_addc_u32 s33, s1, 0
	s_add_u32 s34, s0, s49
	s_addc_u32 s35, s1, 0
	s_add_u32 s36, s0, s50
	s_addc_u32 s37, s1, 0
	s_add_u32 s38, s0, s51
	s_addc_u32 s39, s1, 0
	s_add_u32 s40, s0, s52
	s_addc_u32 s41, s1, 0
	s_add_u32 s42, s0, s53
	s_addc_u32 s43, s1, 0
	s_add_u32 s44, s0, s54
	s_addc_u32 s45, s1, 0
	s_add_u32 s46, s0, s55
	s_addc_u32 s47, s1, 0
	global_load_dwordx4 v[144:147], v234, s[32:33]
	global_load_dwordx4 v[148:151], v234, s[34:35]
	global_load_dwordx4 v[152:155], v234, s[36:37]
	global_load_dwordx4 v[156:159], v234, s[38:39]
	global_load_dwordx4 v[160:163], v234, s[40:41]
	global_load_dwordx4 v[164:167], v234, s[42:43]
	global_load_dwordx4 v[168:171], v234, s[44:45]
	global_load_dwordx4 v[172:175], v234, s[46:47]
	s_waitcnt vmcnt(8)
	s_branch .Lup_cons
.Lup_last:
	ds_read_b32 v144, v237 offset:0
	ds_read_b32 v146, v237 offset:256
	ds_read_b32 v148, v237 offset:512
	ds_read_b32 v150, v237 offset:768
	ds_read_b32 v152, v237 offset:1024
	ds_read_b32 v154, v237 offset:1280
	ds_read_b32 v156, v237 offset:1536
	ds_read_b32 v158, v237 offset:1792
	ds_read_b32 v160, v237 offset:2048
	ds_read_b32 v162, v237 offset:2304
	ds_read_b32 v164, v237 offset:2560
	ds_read_b32 v166, v237 offset:2816
	ds_read_b32 v168, v237 offset:3072
	ds_read_b32 v170, v237 offset:3328
	ds_read_b32 v172, v237 offset:3584
	ds_read_b32 v174, v237 offset:3840
	s_waitcnt lgkmcnt(0)
	v_lshlrev_b32_e32 v144, 3, v144
	v_lshlrev_b32_e32 v146, 3, v146
	v_lshlrev_b32_e32 v148, 3, v148
	v_lshlrev_b32_e32 v150, 3, v150
	v_lshlrev_b32_e32 v152, 3, v152
	v_lshlrev_b32_e32 v154, 3, v154
	v_lshlrev_b32_e32 v156, 3, v156
	v_lshlrev_b32_e32 v158, 3, v158
	v_lshlrev_b32_e32 v160, 3, v160
	v_lshlrev_b32_e32 v162, 3, v162
	v_lshlrev_b32_e32 v164, 3, v164
	v_lshlrev_b32_e32 v166, 3, v166
	v_lshlrev_b32_e32 v168, 3, v168
	v_lshlrev_b32_e32 v170, 3, v170
	v_lshlrev_b32_e32 v172, 3, v172
	v_lshlrev_b32_e32 v174, 3, v174
	global_load_dwordx2 v[144:145], v144, s[8:9]
	global_load_dwordx2 v[146:147], v146, s[8:9]
	global_load_dwordx2 v[148:149], v148, s[8:9]
	global_load_dwordx2 v[150:151], v150, s[8:9]
	global_load_dwordx2 v[152:153], v152, s[8:9]
	global_load_dwordx2 v[154:155], v154, s[8:9]
	global_load_dwordx2 v[156:157], v156, s[8:9]
	global_load_dwordx2 v[158:159], v158, s[8:9]
	global_load_dwordx2 v[160:161], v160, s[8:9]
	global_load_dwordx2 v[162:163], v162, s[8:9]
	global_load_dwordx2 v[164:165], v164, s[8:9]
	global_load_dwordx2 v[166:167], v166, s[8:9]
	global_load_dwordx2 v[168:169], v168, s[8:9]
	global_load_dwordx2 v[170:171], v170, s[8:9]
	global_load_dwordx2 v[172:173], v172, s[8:9]
	global_load_dwordx2 v[174:175], v174, s[8:9]
	s_waitcnt vmcnt(16)
.Lup_cons:
	v_cvt_pk_f32_fp8_e32 v[214:215], v176
	v_cvt_pk_f32_fp8_sdwa v[216:217], v176 src0_sel:WORD_1
	v_cvt_pk_f32_fp8_e32 v[218:219], v177
	v_cvt_pk_f32_fp8_sdwa v[220:221], v177 src0_sel:WORD_1
	v_pk_mul_f32 v[222:223], v[112:113], v[214:215]
	v_pk_mul_f32 v[224:225], v[114:115], v[216:217]
	v_cvt_pk_f32_fp8_e32 v[214:215], v178
	v_cvt_pk_f32_fp8_sdwa v[216:217], v178 src0_sel:WORD_1
	v_pk_fma_f32 v[222:223], v[116:117], v[218:219], v[222:223]
	v_pk_fma_f32 v[224:225], v[118:119], v[220:221], v[224:225]
	v_cvt_pk_f32_fp8_e32 v[218:219], v179
	v_cvt_pk_f32_fp8_sdwa v[220:221], v179 src0_sel:WORD_1
	v_pk_fma_f32 v[222:223], v[120:121], v[214:215], v[222:223]
	v_pk_fma_f32 v[224:225], v[122:123], v[216:217], v[224:225]
	v_pk_fma_f32 v[222:223], v[124:125], v[218:219], v[222:223]
	v_pk_fma_f32 v[224:225], v[126:127], v[220:221], v[224:225]
	v_pk_add_f32 v[222:223], v[222:223], v[224:225]
	s_nop 0
	v_add_f32_e32 v226, v222, v223
	v_cvt_pk_f32_fp8_e32 v[214:215], v180
	v_cvt_pk_f32_fp8_sdwa v[216:217], v180 src0_sel:WORD_1
	v_cvt_pk_f32_fp8_e32 v[218:219], v181
	v_cvt_pk_f32_fp8_sdwa v[220:221], v181 src0_sel:WORD_1
	v_pk_mul_f32 v[222:223], v[112:113], v[214:215]
	v_pk_mul_f32 v[224:225], v[114:115], v[216:217]
	v_cvt_pk_f32_fp8_e32 v[214:215], v182
	v_cvt_pk_f32_fp8_sdwa v[216:217], v182 src0_sel:WORD_1
	v_pk_fma_f32 v[222:223], v[116:117], v[218:219], v[222:223]
	v_pk_fma_f32 v[224:225], v[118:119], v[220:221], v[224:225]
	v_cvt_pk_f32_fp8_e32 v[218:219], v183
	v_cvt_pk_f32_fp8_sdwa v[220:221], v183 src0_sel:WORD_1
	v_pk_fma_f32 v[222:223], v[120:121], v[214:215], v[222:223]
	v_pk_fma_f32 v[224:225], v[122:123], v[216:217], v[224:225]
	v_pk_fma_f32 v[222:223], v[124:125], v[218:219], v[222:223]
	v_pk_fma_f32 v[224:225], v[126:127], v[220:221], v[224:225]
	v_pk_add_f32 v[222:223], v[222:223], v[224:225]
	s_nop 0
	v_add_f32_e32 v227, v222, v223
	v_cvt_pk_f32_fp8_e32 v[214:215], v184
	v_cvt_pk_f32_fp8_sdwa v[216:217], v184 src0_sel:WORD_1
	v_cvt_pk_f32_fp8_e32 v[218:219], v185
	v_cvt_pk_f32_fp8_sdwa v[220:221], v185 src0_sel:WORD_1
	v_pk_mul_f32 v[222:223], v[112:113], v[214:215]
	v_pk_mul_f32 v[224:225], v[114:115], v[216:217]
	v_cvt_pk_f32_fp8_e32 v[214:215], v186
	v_cvt_pk_f32_fp8_sdwa v[216:217], v186 src0_sel:WORD_1
	v_pk_fma_f32 v[222:223], v[116:117], v[218:219], v[222:223]
	v_pk_fma_f32 v[224:225], v[118:119], v[220:221], v[224:225]
	v_cvt_pk_f32_fp8_e32 v[218:219], v187
	v_cvt_pk_f32_fp8_sdwa v[220:221], v187 src0_sel:WORD_1
	v_pk_fma_f32 v[222:223], v[120:121], v[214:215], v[222:223]
	v_pk_fma_f32 v[224:225], v[122:123], v[216:217], v[224:225]
	v_pk_fma_f32 v[222:223], v[124:125], v[218:219], v[222:223]
	v_pk_fma_f32 v[224:225], v[126:127], v[220:221], v[224:225]
; DI float gelu_exact(float x) { return 0.5f * x * (1.f + erff(x * 0.7071067811865476f)); }
; template <bool STORE>
; DI void peer_item(const Params& p, int item, char* smem) {
;     ...
; #pragma unroll
;       for (int u = 0; u < 8; ++u) {
;         float d = 0.f;
; #pragma unroll
;         for (int i = 0; i < 4; ++i) {
;           f32x2_t lo = __builtin_amdgcn_cvt_pk_f32_fp8((int)uq[u][i], false);
;           f32x2_t hi = __builtin_amdgcn_cvt_pk_f32_fp8((int)uq[u][i], true);
;           d += xf[4 * i] * lo.x + xf[4 * i + 1] * lo.y + xf[4 * i + 2] * hi.x + xf[4 * i + 3] * hi.y;
;         }
;         part[u] = d;
;       }
;       float q4[4], r2[2], h;
; #pragma unroll
;       for (int j = 0; j < 4; ++j) {
;         float mine = b5 ? part[j + 4] : part[j];
;         float other = b5 ? part[j] : part[j + 4];
;         q4[j] = mine + __shfl_xor(other, 32);
;       }
; #pragma unroll
;       for (int j = 0; j < 2; ++j) {
;         float mine = b4 ? q4[j + 2] : q4[j];
;         float other = b4 ? q4[j] : q4[j + 2];
;         r2[j] = mine + __shfl_xor(other, 16);
;       }
;       {
;         float mine = b3 ? r2[1] : r2[0];
;         float other = b3 ? r2[0] : r2[1];
;         h = mine + __shfl_xor(other, 8);
;       }
;       h += __shfl_xor(h, 4);
;       h += __shfl_xor(h, 2);
;       h += __shfl_xor(h, 1);
;       const float amine = gelu_exact(h * su) * gmine * sv;
;       if ((lane & 7) == 0) {
;         EG[tok * 128 + k + (lane >> 3)] = emine;
;         AG[tok * 128 + k + (lane >> 3)] = amine;
;       }
;     }
	v_pk_add_f32 v[222:223], v[222:223], v[224:225]
	s_nop 0
	v_add_f32_e32 v228, v222, v223
	v_cvt_pk_f32_fp8_e32 v[214:215], v188
	v_cvt_pk_f32_fp8_sdwa v[216:217], v188 src0_sel:WORD_1
	v_cvt_pk_f32_fp8_e32 v[218:219], v189
	v_cvt_pk_f32_fp8_sdwa v[220:221], v189 src0_sel:WORD_1
	v_pk_mul_f32 v[222:223], v[112:113], v[214:215]
	v_pk_mul_f32 v[224:225], v[114:115], v[216:217]
	v_cvt_pk_f32_fp8_e32 v[214:215], v190
	v_cvt_pk_f32_fp8_sdwa v[216:217], v190 src0_sel:WORD_1
	v_pk_fma_f32 v[222:223], v[116:117], v[218:219], v[222:223]
	v_pk_fma_f32 v[224:225], v[118:119], v[220:221], v[224:225]
	v_cvt_pk_f32_fp8_e32 v[218:219], v191
	v_cvt_pk_f32_fp8_sdwa v[220:221], v191 src0_sel:WORD_1
	v_pk_fma_f32 v[222:223], v[120:121], v[214:215], v[222:223]
	v_pk_fma_f32 v[224:225], v[122:123], v[216:217], v[224:225]
	v_pk_fma_f32 v[222:223], v[124:125], v[218:219], v[222:223]
	v_pk_fma_f32 v[224:225], v[126:127], v[220:221], v[224:225]
	v_pk_add_f32 v[222:223], v[222:223], v[224:225]
	s_nop 0
	v_add_f32_e32 v229, v222, v223
	v_cvt_pk_f32_fp8_e32 v[214:215], v192
	v_cvt_pk_f32_fp8_sdwa v[216:217], v192 src0_sel:WORD_1
	v_cvt_pk_f32_fp8_e32 v[218:219], v193
	v_cvt_pk_f32_fp8_sdwa v[220:221], v193 src0_sel:WORD_1
	v_pk_mul_f32 v[222:223], v[112:113], v[214:215]
	v_pk_mul_f32 v[224:225], v[114:115], v[216:217]
	v_cvt_pk_f32_fp8_e32 v[214:215], v194
	v_cvt_pk_f32_fp8_sdwa v[216:217], v194 src0_sel:WORD_1
	v_pk_fma_f32 v[222:223], v[116:117], v[218:219], v[222:223]
	v_pk_fma_f32 v[224:225], v[118:119], v[220:221], v[224:225]
	v_cvt_pk_f32_fp8_e32 v[218:219], v195
	v_cvt_pk_f32_fp8_sdwa v[220:221], v195 src0_sel:WORD_1
	v_pk_fma_f32 v[222:223], v[120:121], v[214:215], v[222:223]
	v_pk_fma_f32 v[224:225], v[122:123], v[216:217], v[224:225]
	v_pk_fma_f32 v[222:223], v[124:125], v[218:219], v[222:223]
	v_pk_fma_f32 v[224:225], v[126:127], v[220:221], v[224:225]
	v_pk_add_f32 v[222:223], v[222:223], v[224:225]
	s_nop 0
	v_add_f32_e32 v230, v222, v223
	v_cvt_pk_f32_fp8_e32 v[214:215], v196
	v_cvt_pk_f32_fp8_sdwa v[216:217], v196 src0_sel:WORD_1
	v_cvt_pk_f32_fp8_e32 v[218:219], v197
	v_cvt_pk_f32_fp8_sdwa v[220:221], v197 src0_sel:WORD_1
	v_pk_mul_f32 v[222:223], v[112:113], v[214:215]
	v_pk_mul_f32 v[224:225], v[114:115], v[216:217]
	v_cvt_pk_f32_fp8_e32 v[214:215], v198
	v_cvt_pk_f32_fp8_sdwa v[216:217], v198 src0_sel:WORD_1
	v_pk_fma_f32 v[222:223], v[116:117], v[218:219], v[222:223]
	v_pk_fma_f32 v[224:225], v[118:119], v[220:221], v[224:225]
	v_cvt_pk_f32_fp8_e32 v[218:219], v199
	v_cvt_pk_f32_fp8_sdwa v[220:221], v199 src0_sel:WORD_1
	v_pk_fma_f32 v[222:223], v[120:121], v[214:215], v[222:223]
	v_pk_fma_f32 v[224:225], v[122:123], v[216:217], v[224:225]
	v_pk_fma_f32 v[222:223], v[124:125], v[218:219], v[222:223]
	v_pk_fma_f32 v[224:225], v[126:127], v[220:221], v[224:225]
	v_pk_add_f32 v[222:223], v[222:223], v[224:225]
	s_nop 0
	v_add_f32_e32 v231, v222, v223
	v_cvt_pk_f32_fp8_e32 v[214:215], v200
	v_cvt_pk_f32_fp8_sdwa v[216:217], v200 src0_sel:WORD_1
	v_cvt_pk_f32_fp8_e32 v[218:219], v201
	v_cvt_pk_f32_fp8_sdwa v[220:221], v201 src0_sel:WORD_1
	v_pk_mul_f32 v[222:223], v[112:113], v[214:215]
	v_pk_mul_f32 v[224:225], v[114:115], v[216:217]
	v_cvt_pk_f32_fp8_e32 v[214:215], v202
	v_cvt_pk_f32_fp8_sdwa v[216:217], v202 src0_sel:WORD_1
	v_pk_fma_f32 v[222:223], v[116:117], v[218:219], v[222:223]
	v_pk_fma_f32 v[224:225], v[118:119], v[220:221], v[224:225]
	v_cvt_pk_f32_fp8_e32 v[218:219], v203
	v_cvt_pk_f32_fp8_sdwa v[220:221], v203 src0_sel:WORD_1
	v_pk_fma_f32 v[222:223], v[120:121], v[214:215], v[222:223]
	v_pk_fma_f32 v[224:225], v[122:123], v[216:217], v[224:225]
	v_pk_fma_f32 v[222:223], v[124:125], v[218:219], v[222:223]
	v_pk_fma_f32 v[224:225], v[126:127], v[220:221], v[224:225]
	v_pk_add_f32 v[222:223], v[222:223], v[224:225]
	s_nop 0
	v_add_f32_e32 v232, v222, v223
	v_cvt_pk_f32_fp8_e32 v[214:215], v204
	v_cvt_pk_f32_fp8_sdwa v[216:217], v204 src0_sel:WORD_1
	v_cvt_pk_f32_fp8_e32 v[218:219], v205
	v_cvt_pk_f32_fp8_sdwa v[220:221], v205 src0_sel:WORD_1
	v_pk_mul_f32 v[222:223], v[112:113], v[214:215]
	v_pk_mul_f32 v[224:225], v[114:115], v[216:217]
	v_cvt_pk_f32_fp8_e32 v[214:215], v206
	v_cvt_pk_f32_fp8_sdwa v[216:217], v206 src0_sel:WORD_1
	v_pk_fma_f32 v[222:223], v[116:117], v[218:219], v[222:223]
	v_pk_fma_f32 v[224:225], v[118:119], v[220:221], v[224:225]
	v_cvt_pk_f32_fp8_e32 v[218:219], v207
	v_cvt_pk_f32_fp8_sdwa v[220:221], v207 src0_sel:WORD_1
	v_pk_fma_f32 v[222:223], v[120:121], v[214:215], v[222:223]
	v_pk_fma_f32 v[224:225], v[122:123], v[216:217], v[224:225]
	v_pk_fma_f32 v[222:223], v[124:125], v[218:219], v[222:223]
	v_pk_fma_f32 v[224:225], v[126:127], v[220:221], v[224:225]
	v_pk_add_f32 v[222:223], v[222:223], v[224:225]
	s_nop 0
	v_add_f32_e32 v233, v222, v223
	v_permlane32_swap_b32_e32 v226, v230
	v_permlane32_swap_b32_e32 v227, v231
	v_permlane32_swap_b32_e32 v228, v232
	v_permlane32_swap_b32_e32 v229, v233
	v_add_f32_e32 v226, v226, v230
	v_add_f32_e32 v228, v228, v232
	v_add_f32_e32 v227, v227, v231
	v_add_f32_e32 v229, v229, v233
	s_nop 1
	v_permlane16_swap_b32_e32 v226, v228
	v_permlane16_swap_b32_e32 v227, v229
	v_add_f32_e32 v226, v226, v228
	v_add_f32_e32 v227, v227, v229
	s_nop 0
	v_cndmask_b32_e64 v230, v226, v227, s[24:25]
	v_cndmask_b32_e64 v231, v227, v226, s[24:25]
	s_nop 1
	v_add_f32_dpp v232, v231, v230 row_ror:8 row_mask:0xf bank_mask:0xf
	s_nop 1
	v_add_f32_dpp v233, v232, v232 quad_perm:[1,0,3,2] row_mask:0xf bank_mask:0xf
	s_nop 1
	v_add_f32_dpp v232, v233, v233 quad_perm:[2,3,0,1] row_mask:0xf bank_mask:0xf
	s_nop 1
	v_add_f32_dpp v233, v232, v232 row_half_mirror row_mask:0xf bank_mask:0xf
	ds_write_b32 v235, v233 offset:36384
	v_add_u32_e32 v235, 64, v235
	s_add_u32 s12, s12, 1
	s_cmp_lt_u32 s12, 8
	s_cbranch_scc1 .Lup_k
; DI float gelu_exact(float x) { return 0.5f * x * (1.f + erff(x * 0.7071067811865476f)); }
; template <bool STORE>
; DI void peer_item(const Params& p, int item, char* smem) {
;     ...
;       const int emine = e_s[tl * 128 + k + (lane >> 3)];
;       const float gmine = g_s[tl * 128 + k + (lane >> 3)];
;       const float su = SU[emine], sv = SV[emine];
;     ...
;       const float amine = gelu_exact(h * su) * gmine * sv;
;       if ((lane & 7) == 0) {
;         EG[tok * 128 + k + (lane >> 3)] = emine;
;         AG[tok * 128 + k + (lane >> 3)] = amine;
;       }
	s_waitcnt lgkmcnt(0)
	s_lshl_b32 s13, s14, 9
	s_add_u32 s26, s4, s13
	s_addc_u32 s27, s5, 0
	s_add_u32 s28, s6, s13
	s_addc_u32 s29, s7, 0
	ds_read_b32 v0, v237 offset:32768
	ds_read_b32 v1, v237 offset:33024
	ds_read_b32 v2, v237 offset:0
	ds_read_b32 v3, v237 offset:256
	ds_read_b32 v4, v237 offset:16384
	ds_read_b32 v5, v237 offset:16640
	ds_read_b32 v16, v237 offset:33280
	ds_read_b32 v17, v237 offset:33536
	ds_read_b32 v18, v237 offset:512
	ds_read_b32 v19, v237 offset:768
	ds_read_b32 v20, v237 offset:16896
	ds_read_b32 v21, v237 offset:17152
	ds_read_b32 v32, v237 offset:33792
	ds_read_b32 v33, v237 offset:34048
	ds_read_b32 v34, v237 offset:1024
	ds_read_b32 v35, v237 offset:1280
	ds_read_b32 v36, v237 offset:17408
	ds_read_b32 v37, v237 offset:17664
	ds_read_b32 v48, v237 offset:34304
	ds_read_b32 v49, v237 offset:34560
	ds_read_b32 v50, v237 offset:1536
	ds_read_b32 v51, v237 offset:1792
	ds_read_b32 v52, v237 offset:17920
	ds_read_b32 v53, v237 offset:18176
	ds_read_b32 v64, v237 offset:34816
	ds_read_b32 v65, v237 offset:35072
	ds_read_b32 v66, v237 offset:2048
	ds_read_b32 v67, v237 offset:2304
	ds_read_b32 v68, v237 offset:18432
	ds_read_b32 v69, v237 offset:18688
	ds_read_b32 v80, v237 offset:35328
	ds_read_b32 v81, v237 offset:35584
	ds_read_b32 v82, v237 offset:2560
	ds_read_b32 v83, v237 offset:2816
	ds_read_b32 v84, v237 offset:18944
	ds_read_b32 v85, v237 offset:19200
	ds_read_b32 v96, v237 offset:35840
	ds_read_b32 v97, v237 offset:36096
	ds_read_b32 v98, v237 offset:3072
	ds_read_b32 v99, v237 offset:3328
	ds_read_b32 v100, v237 offset:19456
	ds_read_b32 v101, v237 offset:19712
	ds_read_b32 v112, v237 offset:36352
	ds_read_b32 v113, v237 offset:36608
	ds_read_b32 v114, v237 offset:3584
	ds_read_b32 v115, v237 offset:3840
	ds_read_b32 v116, v237 offset:19968
	ds_read_b32 v117, v237 offset:20224
	s_lshl_b32 s13, s14, 5
	s_add_u32 s32, s56, 0x9a80200
	s_addc_u32 s33, s57, 0
	s_add_u32 s32, s32, s13
	s_addc_u32 s33, s33, 0
	v_mov_b32_e32 v208, 0
	global_load_dwordx4 v[12:15], v208, s[32:33] offset:0
	global_load_dwordx4 v[6:9], v208, s[32:33] offset:16
	global_load_dwordx4 v[28:31], v208, s[32:33] offset:32
	global_load_dwordx4 v[22:25], v208, s[32:33] offset:48
	global_load_dwordx4 v[44:47], v208, s[32:33] offset:64
	global_load_dwordx4 v[38:41], v208, s[32:33] offset:80
	global_load_dwordx4 v[60:63], v208, s[32:33] offset:96
	global_load_dwordx4 v[54:57], v208, s[32:33] offset:112
	global_load_dwordx4 v[76:79], v208, s[32:33] offset:128
	global_load_dwordx4 v[70:73], v208, s[32:33] offset:144
	global_load_dwordx4 v[92:95], v208, s[32:33] offset:160
	global_load_dwordx4 v[86:89], v208, s[32:33] offset:176
	global_load_dwordx4 v[108:111], v208, s[32:33] offset:192
	global_load_dwordx4 v[102:105], v208, s[32:33] offset:208
	global_load_dwordx4 v[124:127], v208, s[32:33] offset:224
	global_load_dwordx4 v[118:121], v208, s[32:33] offset:240
	s_waitcnt lgkmcnt(15)
	s_waitcnt lgkmcnt(15)
	s_waitcnt lgkmcnt(15)
	s_waitcnt lgkmcnt(15)
	s_waitcnt lgkmcnt(15)
	s_waitcnt lgkmcnt(12)
	s_waitcnt lgkmcnt(6)
	s_waitcnt lgkmcnt(0)
	s_waitcnt vmcnt(0)
	v_pk_add_f32 v[12:13], v[12:13], v[14:15]
	v_pk_add_f32 v[6:7], v[6:7], v[8:9]
	v_mov_b32_e32 v14, 0x358637bd
	v_pk_add_f32 v[12:13], v[12:13], v[6:7]
	s_nop 0
	v_add_f32_e32 v12, v12, v13
	s_nop 0
	v_fmamk_f32 v12, v12, 0x3a800000, v14
	s_nop 0
	v_rsq_f32_e32 v12, v12
	s_nop 1
	v_mul_f32_e32 v144, v144, v12
	v_mul_f32_e32 v146, v146, v12
	v_mul_f32_e32 v176, v144, v0
	v_mul_f32_e32 v177, 0x3f3504f3, v176
	v_mov_b32_e32 v178, 0xb9c68948
	v_fma_f32 v178, |v177|, s80, v178
	v_fma_f32 v178, |v177|, v178, s81
	v_fma_f32 v178, |v177|, v178, s82
	v_fma_f32 v178, |v177|, v178, s83
	v_fma_f32 v178, |v177|, v178, s84
	v_fma_f32 v178, |v177|, v178, s85
	v_fma_f32 v178, |v177|, v178, |v177|
	v_mul_f32_e32 v179, 0xbfb8aa3b, v178
	v_fma_f32 v180, v178, s86, -v179
	v_rndne_f32_e32 v181, v179
	v_fmac_f32_e32 v180, 0xb2a5705f, v178
	v_sub_f32_e32 v179, v179, v181
	v_add_f32_e32 v179, v179, v180
	v_cvt_i32_f32_e32 v180, v181
	v_exp_f32_e32 v179, v179
	v_cmp_nlt_f32_e32 vcc, s87, v178
	v_ldexp_f32 v179, v179, v180
	s_nop 0
	v_cndmask_b32_e32 v179, 0, v179, vcc
	v_cmp_ngt_f32_e32 vcc, s88, v178
	v_mov_b32_e32 v180, 0x7f800000
	s_nop 0
	v_cndmask_b32_e32 v179, v180, v179, vcc
	v_sub_f32_e32 v179, 1.0, v179
	v_mul_f32_e32 v180, v177, v177
	v_mov_b32_e32 v181, 0x3ba10414
	v_fmamk_f32 v181, v180, 0xba1345e1, v181
	v_fmaak_f32 v181, v180, v181, 0xbcdac9b8
	v_fmaak_f32 v181, v180, v181, 0x3de703be
	v_fmaak_f32 v181, v180, v181, 0xbec09330
	v_fmaak_f32 v181, v180, v181, 0x3e0375d0
	v_fma_f32 v181, |v177|, v181, |v177|
	v_cmp_nlt_f32_e64 vcc, |v177|, 1.0
	s_nop 1
	v_cndmask_b32_e32 v179, v181, v179, vcc
	v_bfi_b32 v179, s89, v179, v177
	v_mul_f32_e32 v176, 0.5, v176
	v_add_f32_e32 v179, 1.0, v179
	v_mul_f32_e32 v176, v176, v179
	v_mul_f32_e32 v176, v4, v176
	v_mul_f32_e32 v0, v145, v176
	v_mul_f32_e32 v176, v146, v1
	v_mul_f32_e32 v177, 0x3f3504f3, v176
	v_mov_b32_e32 v178, 0xb9c68948
	v_fma_f32 v178, |v177|, s80, v178
	v_fma_f32 v178, |v177|, v178, s81
	v_fma_f32 v178, |v177|, v178, s82
	v_fma_f32 v178, |v177|, v178, s83
	v_fma_f32 v178, |v177|, v178, s84
	v_fma_f32 v178, |v177|, v178, s85
	v_fma_f32 v178, |v177|, v178, |v177|
	v_mul_f32_e32 v179, 0xbfb8aa3b, v178
	v_fma_f32 v180, v178, s86, -v179
	v_rndne_f32_e32 v181, v179
	v_fmac_f32_e32 v180, 0xb2a5705f, v178
	v_sub_f32_e32 v179, v179, v181
	v_add_f32_e32 v179, v179, v180
	v_cvt_i32_f32_e32 v180, v181
	v_exp_f32_e32 v179, v179
	v_cmp_nlt_f32_e32 vcc, s87, v178
	v_ldexp_f32 v179, v179, v180
	s_nop 0
	v_cndmask_b32_e32 v179, 0, v179, vcc
	v_cmp_ngt_f32_e32 vcc, s88, v178
; DI float gelu_exact(float x) { return 0.5f * x * (1.f + erff(x * 0.7071067811865476f)); }
; template <bool STORE>
; DI void peer_item(const Params& p, int item, char* smem) {
;     ...
;       const float amine = gelu_exact(h * su) * gmine * sv;
;       if ((lane & 7) == 0) {
;         EG[tok * 128 + k + (lane >> 3)] = emine;
;         AG[tok * 128 + k + (lane >> 3)] = amine;
;       }
	v_mov_b32_e32 v180, 0x7f800000
	s_nop 0
	v_cndmask_b32_e32 v179, v180, v179, vcc
	v_sub_f32_e32 v179, 1.0, v179
	v_mul_f32_e32 v180, v177, v177
	v_mov_b32_e32 v181, 0x3ba10414
	v_fmamk_f32 v181, v180, 0xba1345e1, v181
	v_fmaak_f32 v181, v180, v181, 0xbcdac9b8
	v_fmaak_f32 v181, v180, v181, 0x3de703be
	v_fmaak_f32 v181, v180, v181, 0xbec09330
	v_fmaak_f32 v181, v180, v181, 0x3e0375d0
	v_fma_f32 v181, |v177|, v181, |v177|
	v_cmp_nlt_f32_e64 vcc, |v177|, 1.0
	s_nop 1
	v_cndmask_b32_e32 v179, v181, v179, vcc
	v_bfi_b32 v179, s89, v179, v177
	v_mul_f32_e32 v176, 0.5, v176
	v_add_f32_e32 v179, 1.0, v179
	v_mul_f32_e32 v176, v176, v179
	v_mul_f32_e32 v176, v5, v176
	v_mul_f32_e32 v1, v147, v176
	ds_write_b32 v237, v0 offset:32768
	ds_write_b32 v237, v1 offset:33024
	v_pk_add_f32 v[28:29], v[28:29], v[30:31]
	v_pk_add_f32 v[22:23], v[22:23], v[24:25]
	v_mov_b32_e32 v30, 0x358637bd
	v_pk_add_f32 v[28:29], v[28:29], v[22:23]
	s_nop 0
	v_add_f32_e32 v28, v28, v29
	s_nop 0
	v_fmamk_f32 v28, v28, 0x3a800000, v30
	s_nop 0
	v_rsq_f32_e32 v28, v28
	s_nop 1
	v_mul_f32_e32 v148, v148, v28
	v_mul_f32_e32 v150, v150, v28
	v_mul_f32_e32 v176, v148, v16
	v_mul_f32_e32 v177, 0x3f3504f3, v176
	v_mov_b32_e32 v178, 0xb9c68948
	v_fma_f32 v178, |v177|, s80, v178
	v_fma_f32 v178, |v177|, v178, s81
	v_fma_f32 v178, |v177|, v178, s82
	v_fma_f32 v178, |v177|, v178, s83
	v_fma_f32 v178, |v177|, v178, s84
	v_fma_f32 v178, |v177|, v178, s85
	v_fma_f32 v178, |v177|, v178, |v177|
	v_mul_f32_e32 v179, 0xbfb8aa3b, v178
	v_fma_f32 v180, v178, s86, -v179
	v_rndne_f32_e32 v181, v179
	v_fmac_f32_e32 v180, 0xb2a5705f, v178
	v_sub_f32_e32 v179, v179, v181
	v_add_f32_e32 v179, v179, v180
	v_cvt_i32_f32_e32 v180, v181
	v_exp_f32_e32 v179, v179
	v_cmp_nlt_f32_e32 vcc, s87, v178
	v_ldexp_f32 v179, v179, v180
	s_nop 0
	v_cndmask_b32_e32 v179, 0, v179, vcc
	v_cmp_ngt_f32_e32 vcc, s88, v178
	v_mov_b32_e32 v180, 0x7f800000
	s_nop 0
	v_cndmask_b32_e32 v179, v180, v179, vcc
	v_sub_f32_e32 v179, 1.0, v179
	v_mul_f32_e32 v180, v177, v177
	v_mov_b32_e32 v181, 0x3ba10414
	v_fmamk_f32 v181, v180, 0xba1345e1, v181
	v_fmaak_f32 v181, v180, v181, 0xbcdac9b8
	v_fmaak_f32 v181, v180, v181, 0x3de703be
	v_fmaak_f32 v181, v180, v181, 0xbec09330
	v_fmaak_f32 v181, v180, v181, 0x3e0375d0
	v_fma_f32 v181, |v177|, v181, |v177|
	v_cmp_nlt_f32_e64 vcc, |v177|, 1.0
	s_nop 1
	v_cndmask_b32_e32 v179, v181, v179, vcc
	v_bfi_b32 v179, s89, v179, v177
	v_mul_f32_e32 v176, 0.5, v176
	v_add_f32_e32 v179, 1.0, v179
	v_mul_f32_e32 v176, v176, v179
	v_mul_f32_e32 v176, v20, v176
	v_mul_f32_e32 v16, v149, v176
	v_mul_f32_e32 v176, v150, v17
	v_mul_f32_e32 v177, 0x3f3504f3, v176
	v_mov_b32_e32 v178, 0xb9c68948
	v_fma_f32 v178, |v177|, s80, v178
	v_fma_f32 v178, |v177|, v178, s81
	v_fma_f32 v178, |v177|, v178, s82
	v_fma_f32 v178, |v177|, v178, s83
	v_fma_f32 v178, |v177|, v178, s84
	v_fma_f32 v178, |v177|, v178, s85
	v_fma_f32 v178, |v177|, v178, |v177|
	v_mul_f32_e32 v179, 0xbfb8aa3b, v178
	v_fma_f32 v180, v178, s86, -v179
	v_rndne_f32_e32 v181, v179
	v_fmac_f32_e32 v180, 0xb2a5705f, v178
	v_sub_f32_e32 v179, v179, v181
	v_add_f32_e32 v179, v179, v180
	v_cvt_i32_f32_e32 v180, v181
	v_exp_f32_e32 v179, v179
	v_cmp_nlt_f32_e32 vcc, s87, v178
	v_ldexp_f32 v179, v179, v180
	s_nop 0
	v_cndmask_b32_e32 v179, 0, v179, vcc
	v_cmp_ngt_f32_e32 vcc, s88, v178
	v_mov_b32_e32 v180, 0x7f800000
	s_nop 0
	v_cndmask_b32_e32 v179, v180, v179, vcc
	v_sub_f32_e32 v179, 1.0, v179
	v_mul_f32_e32 v180, v177, v177
	v_mov_b32_e32 v181, 0x3ba10414
	v_fmamk_f32 v181, v180, 0xba1345e1, v181
	v_fmaak_f32 v181, v180, v181, 0xbcdac9b8
	v_fmaak_f32 v181, v180, v181, 0x3de703be
	v_fmaak_f32 v181, v180, v181, 0xbec09330
	v_fmaak_f32 v181, v180, v181, 0x3e0375d0
	v_fma_f32 v181, |v177|, v181, |v177|
	v_cmp_nlt_f32_e64 vcc, |v177|, 1.0
	s_nop 1
	v_cndmask_b32_e32 v179, v181, v179, vcc
	v_bfi_b32 v179, s89, v179, v177
	v_mul_f32_e32 v176, 0.5, v176
	v_add_f32_e32 v179, 1.0, v179
	v_mul_f32_e32 v176, v176, v179
	v_mul_f32_e32 v176, v21, v176
	v_mul_f32_e32 v17, v151, v176
	ds_write_b32 v237, v16 offset:33280
	ds_write_b32 v237, v17 offset:33536
	v_pk_add_f32 v[44:45], v[44:45], v[46:47]
	v_pk_add_f32 v[38:39], v[38:39], v[40:41]
	v_mov_b32_e32 v46, 0x358637bd
	v_pk_add_f32 v[44:45], v[44:45], v[38:39]
	s_nop 0
	v_add_f32_e32 v44, v44, v45
	s_nop 0
	v_fmamk_f32 v44, v44, 0x3a800000, v46
	s_nop 0
	v_rsq_f32_e32 v44, v44
	s_nop 1
	v_mul_f32_e32 v152, v152, v44
	v_mul_f32_e32 v154, v154, v44
	v_mul_f32_e32 v176, v152, v32
	v_mul_f32_e32 v177, 0x3f3504f3, v176
	v_mov_b32_e32 v178, 0xb9c68948
	v_fma_f32 v178, |v177|, s80, v178
	v_fma_f32 v178, |v177|, v178, s81
	v_fma_f32 v178, |v177|, v178, s82
	v_fma_f32 v178, |v177|, v178, s83
	v_fma_f32 v178, |v177|, v178, s84
	v_fma_f32 v178, |v177|, v178, s85
	v_fma_f32 v178, |v177|, v178, |v177|
	v_mul_f32_e32 v179, 0xbfb8aa3b, v178
	v_fma_f32 v180, v178, s86, -v179
	v_rndne_f32_e32 v181, v179
	v_fmac_f32_e32 v180, 0xb2a5705f, v178
	v_sub_f32_e32 v179, v179, v181
	v_add_f32_e32 v179, v179, v180
	v_cvt_i32_f32_e32 v180, v181
	v_exp_f32_e32 v179, v179
	v_cmp_nlt_f32_e32 vcc, s87, v178
	v_ldexp_f32 v179, v179, v180
	s_nop 0
	v_cndmask_b32_e32 v179, 0, v179, vcc
	v_cmp_ngt_f32_e32 vcc, s88, v178
	v_mov_b32_e32 v180, 0x7f800000
	s_nop 0
	v_cndmask_b32_e32 v179, v180, v179, vcc
	v_sub_f32_e32 v179, 1.0, v179
	v_mul_f32_e32 v180, v177, v177
	v_mov_b32_e32 v181, 0x3ba10414
	v_fmamk_f32 v181, v180, 0xba1345e1, v181
	v_fmaak_f32 v181, v180, v181, 0xbcdac9b8
	v_fmaak_f32 v181, v180, v181, 0x3de703be
	v_fmaak_f32 v181, v180, v181, 0xbec09330
	v_fmaak_f32 v181, v180, v181, 0x3e0375d0
	v_fma_f32 v181, |v177|, v181, |v177|
; DI float gelu_exact(float x) { return 0.5f * x * (1.f + erff(x * 0.7071067811865476f)); }
; template <bool STORE>
; DI void peer_item(const Params& p, int item, char* smem) {
;     ...
;       const float amine = gelu_exact(h * su) * gmine * sv;
;       if ((lane & 7) == 0) {
;         EG[tok * 128 + k + (lane >> 3)] = emine;
;         AG[tok * 128 + k + (lane >> 3)] = amine;
;       }
	v_cmp_nlt_f32_e64 vcc, |v177|, 1.0
	s_nop 1
	v_cndmask_b32_e32 v179, v181, v179, vcc
	v_bfi_b32 v179, s89, v179, v177
	v_mul_f32_e32 v176, 0.5, v176
	v_add_f32_e32 v179, 1.0, v179
	v_mul_f32_e32 v176, v176, v179
	v_mul_f32_e32 v176, v36, v176
	v_mul_f32_e32 v32, v153, v176
	v_mul_f32_e32 v176, v154, v33
	v_mul_f32_e32 v177, 0x3f3504f3, v176
	v_mov_b32_e32 v178, 0xb9c68948
	v_fma_f32 v178, |v177|, s80, v178
	v_fma_f32 v178, |v177|, v178, s81
	v_fma_f32 v178, |v177|, v178, s82
	v_fma_f32 v178, |v177|, v178, s83
	v_fma_f32 v178, |v177|, v178, s84
	v_fma_f32 v178, |v177|, v178, s85
	v_fma_f32 v178, |v177|, v178, |v177|
	v_mul_f32_e32 v179, 0xbfb8aa3b, v178
	v_fma_f32 v180, v178, s86, -v179
	v_rndne_f32_e32 v181, v179
	v_fmac_f32_e32 v180, 0xb2a5705f, v178
	v_sub_f32_e32 v179, v179, v181
	v_add_f32_e32 v179, v179, v180
	v_cvt_i32_f32_e32 v180, v181
	v_exp_f32_e32 v179, v179
	v_cmp_nlt_f32_e32 vcc, s87, v178
	v_ldexp_f32 v179, v179, v180
	s_nop 0
	v_cndmask_b32_e32 v179, 0, v179, vcc
	v_cmp_ngt_f32_e32 vcc, s88, v178
	v_mov_b32_e32 v180, 0x7f800000
	s_nop 0
	v_cndmask_b32_e32 v179, v180, v179, vcc
	v_sub_f32_e32 v179, 1.0, v179
	v_mul_f32_e32 v180, v177, v177
	v_mov_b32_e32 v181, 0x3ba10414
	v_fmamk_f32 v181, v180, 0xba1345e1, v181
	v_fmaak_f32 v181, v180, v181, 0xbcdac9b8
	v_fmaak_f32 v181, v180, v181, 0x3de703be
	v_fmaak_f32 v181, v180, v181, 0xbec09330
	v_fmaak_f32 v181, v180, v181, 0x3e0375d0
	v_fma_f32 v181, |v177|, v181, |v177|
	v_cmp_nlt_f32_e64 vcc, |v177|, 1.0
	s_nop 1
	v_cndmask_b32_e32 v179, v181, v179, vcc
	v_bfi_b32 v179, s89, v179, v177
	v_mul_f32_e32 v176, 0.5, v176
	v_add_f32_e32 v179, 1.0, v179
	v_mul_f32_e32 v176, v176, v179
	v_mul_f32_e32 v176, v37, v176
	v_mul_f32_e32 v33, v155, v176
	ds_write_b32 v237, v32 offset:33792
	ds_write_b32 v237, v33 offset:34048
	v_pk_add_f32 v[60:61], v[60:61], v[62:63]
	v_pk_add_f32 v[54:55], v[54:55], v[56:57]
	v_mov_b32_e32 v62, 0x358637bd
	v_pk_add_f32 v[60:61], v[60:61], v[54:55]
	s_nop 0
	v_add_f32_e32 v60, v60, v61
	s_nop 0
	v_fmamk_f32 v60, v60, 0x3a800000, v62
	s_nop 0
	v_rsq_f32_e32 v60, v60
	s_nop 1
	v_mul_f32_e32 v156, v156, v60
	v_mul_f32_e32 v158, v158, v60
	v_mul_f32_e32 v176, v156, v48
	v_mul_f32_e32 v177, 0x3f3504f3, v176
	v_mov_b32_e32 v178, 0xb9c68948
	v_fma_f32 v178, |v177|, s80, v178
	v_fma_f32 v178, |v177|, v178, s81
	v_fma_f32 v178, |v177|, v178, s82
	v_fma_f32 v178, |v177|, v178, s83
	v_fma_f32 v178, |v177|, v178, s84
	v_fma_f32 v178, |v177|, v178, s85
	v_fma_f32 v178, |v177|, v178, |v177|
	v_mul_f32_e32 v179, 0xbfb8aa3b, v178
	v_fma_f32 v180, v178, s86, -v179
	v_rndne_f32_e32 v181, v179
	v_fmac_f32_e32 v180, 0xb2a5705f, v178
	v_sub_f32_e32 v179, v179, v181
	v_add_f32_e32 v179, v179, v180
	v_cvt_i32_f32_e32 v180, v181
	v_exp_f32_e32 v179, v179
	v_cmp_nlt_f32_e32 vcc, s87, v178
	v_ldexp_f32 v179, v179, v180
	s_nop 0
	v_cndmask_b32_e32 v179, 0, v179, vcc
	v_cmp_ngt_f32_e32 vcc, s88, v178
	v_mov_b32_e32 v180, 0x7f800000
	s_nop 0
	v_cndmask_b32_e32 v179, v180, v179, vcc
	v_sub_f32_e32 v179, 1.0, v179
	v_mul_f32_e32 v180, v177, v177
	v_mov_b32_e32 v181, 0x3ba10414
	v_fmamk_f32 v181, v180, 0xba1345e1, v181
	v_fmaak_f32 v181, v180, v181, 0xbcdac9b8
	v_fmaak_f32 v181, v180, v181, 0x3de703be
	v_fmaak_f32 v181, v180, v181, 0xbec09330
	v_fmaak_f32 v181, v180, v181, 0x3e0375d0
	v_fma_f32 v181, |v177|, v181, |v177|
	v_cmp_nlt_f32_e64 vcc, |v177|, 1.0
	s_nop 1
	v_cndmask_b32_e32 v179, v181, v179, vcc
	v_bfi_b32 v179, s89, v179, v177
	v_mul_f32_e32 v176, 0.5, v176
	v_add_f32_e32 v179, 1.0, v179
	v_mul_f32_e32 v176, v176, v179
	v_mul_f32_e32 v176, v52, v176
	v_mul_f32_e32 v48, v157, v176
	v_mul_f32_e32 v176, v158, v49
	v_mul_f32_e32 v177, 0x3f3504f3, v176
	v_mov_b32_e32 v178, 0xb9c68948
	v_fma_f32 v178, |v177|, s80, v178
	v_fma_f32 v178, |v177|, v178, s81
	v_fma_f32 v178, |v177|, v178, s82
	v_fma_f32 v178, |v177|, v178, s83
	v_fma_f32 v178, |v177|, v178, s84
	v_fma_f32 v178, |v177|, v178, s85
	v_fma_f32 v178, |v177|, v178, |v177|
	v_mul_f32_e32 v179, 0xbfb8aa3b, v178
	v_fma_f32 v180, v178, s86, -v179
	v_rndne_f32_e32 v181, v179
	v_fmac_f32_e32 v180, 0xb2a5705f, v178
	v_sub_f32_e32 v179, v179, v181
	v_add_f32_e32 v179, v179, v180
	v_cvt_i32_f32_e32 v180, v181
	v_exp_f32_e32 v179, v179
	v_cmp_nlt_f32_e32 vcc, s87, v178
	v_ldexp_f32 v179, v179, v180
	s_nop 0
	v_cndmask_b32_e32 v179, 0, v179, vcc
	v_cmp_ngt_f32_e32 vcc, s88, v178
	v_mov_b32_e32 v180, 0x7f800000
	s_nop 0
	v_cndmask_b32_e32 v179, v180, v179, vcc
	v_sub_f32_e32 v179, 1.0, v179
	v_mul_f32_e32 v180, v177, v177
	v_mov_b32_e32 v181, 0x3ba10414
	v_fmamk_f32 v181, v180, 0xba1345e1, v181
	v_fmaak_f32 v181, v180, v181, 0xbcdac9b8
	v_fmaak_f32 v181, v180, v181, 0x3de703be
	v_fmaak_f32 v181, v180, v181, 0xbec09330
	v_fmaak_f32 v181, v180, v181, 0x3e0375d0
	v_fma_f32 v181, |v177|, v181, |v177|
	v_cmp_nlt_f32_e64 vcc, |v177|, 1.0
	s_nop 1
	v_cndmask_b32_e32 v179, v181, v179, vcc
	v_bfi_b32 v179, s89, v179, v177
	v_mul_f32_e32 v176, 0.5, v176
	v_add_f32_e32 v179, 1.0, v179
	v_mul_f32_e32 v176, v176, v179
	v_mul_f32_e32 v176, v53, v176
	v_mul_f32_e32 v49, v159, v176
	ds_write_b32 v237, v48 offset:34304
	ds_write_b32 v237, v49 offset:34560
	v_pk_add_f32 v[76:77], v[76:77], v[78:79]
	v_pk_add_f32 v[70:71], v[70:71], v[72:73]
	v_mov_b32_e32 v78, 0x358637bd
	v_pk_add_f32 v[76:77], v[76:77], v[70:71]
	s_nop 0
	v_add_f32_e32 v76, v76, v77
	s_nop 0
	v_fmamk_f32 v76, v76, 0x3a800000, v78
	s_nop 0
	v_rsq_f32_e32 v76, v76
	s_nop 1
	v_mul_f32_e32 v160, v160, v76
	v_mul_f32_e32 v162, v162, v76
	v_mul_f32_e32 v176, v160, v64
	v_mul_f32_e32 v177, 0x3f3504f3, v176
	v_mov_b32_e32 v178, 0xb9c68948
	v_fma_f32 v178, |v177|, s80, v178
	v_fma_f32 v178, |v177|, v178, s81
; DI float gelu_exact(float x) { return 0.5f * x * (1.f + erff(x * 0.7071067811865476f)); }
; template <bool STORE>
; DI void peer_item(const Params& p, int item, char* smem) {
;     ...
;       const float amine = gelu_exact(h * su) * gmine * sv;
;       if ((lane & 7) == 0) {
;         EG[tok * 128 + k + (lane >> 3)] = emine;
;         AG[tok * 128 + k + (lane >> 3)] = amine;
;       }
	v_fma_f32 v178, |v177|, v178, s82
	v_fma_f32 v178, |v177|, v178, s83
	v_fma_f32 v178, |v177|, v178, s84
	v_fma_f32 v178, |v177|, v178, s85
	v_fma_f32 v178, |v177|, v178, |v177|
	v_mul_f32_e32 v179, 0xbfb8aa3b, v178
	v_fma_f32 v180, v178, s86, -v179
	v_rndne_f32_e32 v181, v179
	v_fmac_f32_e32 v180, 0xb2a5705f, v178
	v_sub_f32_e32 v179, v179, v181
	v_add_f32_e32 v179, v179, v180
	v_cvt_i32_f32_e32 v180, v181
	v_exp_f32_e32 v179, v179
	v_cmp_nlt_f32_e32 vcc, s87, v178
	v_ldexp_f32 v179, v179, v180
	s_nop 0
	v_cndmask_b32_e32 v179, 0, v179, vcc
	v_cmp_ngt_f32_e32 vcc, s88, v178
	v_mov_b32_e32 v180, 0x7f800000
	s_nop 0
	v_cndmask_b32_e32 v179, v180, v179, vcc
	v_sub_f32_e32 v179, 1.0, v179
	v_mul_f32_e32 v180, v177, v177
	v_mov_b32_e32 v181, 0x3ba10414
	v_fmamk_f32 v181, v180, 0xba1345e1, v181
	v_fmaak_f32 v181, v180, v181, 0xbcdac9b8
	v_fmaak_f32 v181, v180, v181, 0x3de703be
	v_fmaak_f32 v181, v180, v181, 0xbec09330
	v_fmaak_f32 v181, v180, v181, 0x3e0375d0
	v_fma_f32 v181, |v177|, v181, |v177|
	v_cmp_nlt_f32_e64 vcc, |v177|, 1.0
	s_nop 1
	v_cndmask_b32_e32 v179, v181, v179, vcc
	v_bfi_b32 v179, s89, v179, v177
	v_mul_f32_e32 v176, 0.5, v176
	v_add_f32_e32 v179, 1.0, v179
	v_mul_f32_e32 v176, v176, v179
	v_mul_f32_e32 v176, v68, v176
	v_mul_f32_e32 v64, v161, v176
	v_mul_f32_e32 v176, v162, v65
	v_mul_f32_e32 v177, 0x3f3504f3, v176
	v_mov_b32_e32 v178, 0xb9c68948
	v_fma_f32 v178, |v177|, s80, v178
	v_fma_f32 v178, |v177|, v178, s81
	v_fma_f32 v178, |v177|, v178, s82
	v_fma_f32 v178, |v177|, v178, s83
	v_fma_f32 v178, |v177|, v178, s84
	v_fma_f32 v178, |v177|, v178, s85
	v_fma_f32 v178, |v177|, v178, |v177|
	v_mul_f32_e32 v179, 0xbfb8aa3b, v178
	v_fma_f32 v180, v178, s86, -v179
	v_rndne_f32_e32 v181, v179
	v_fmac_f32_e32 v180, 0xb2a5705f, v178
	v_sub_f32_e32 v179, v179, v181
	v_add_f32_e32 v179, v179, v180
	v_cvt_i32_f32_e32 v180, v181
	v_exp_f32_e32 v179, v179
	v_cmp_nlt_f32_e32 vcc, s87, v178
	v_ldexp_f32 v179, v179, v180
	s_nop 0
	v_cndmask_b32_e32 v179, 0, v179, vcc
	v_cmp_ngt_f32_e32 vcc, s88, v178
	v_mov_b32_e32 v180, 0x7f800000
	s_nop 0
	v_cndmask_b32_e32 v179, v180, v179, vcc
	v_sub_f32_e32 v179, 1.0, v179
	v_mul_f32_e32 v180, v177, v177
	v_mov_b32_e32 v181, 0x3ba10414
	v_fmamk_f32 v181, v180, 0xba1345e1, v181
	v_fmaak_f32 v181, v180, v181, 0xbcdac9b8
	v_fmaak_f32 v181, v180, v181, 0x3de703be
	v_fmaak_f32 v181, v180, v181, 0xbec09330
	v_fmaak_f32 v181, v180, v181, 0x3e0375d0
	v_fma_f32 v181, |v177|, v181, |v177|
	v_cmp_nlt_f32_e64 vcc, |v177|, 1.0
	s_nop 1
	v_cndmask_b32_e32 v179, v181, v179, vcc
	v_bfi_b32 v179, s89, v179, v177
	v_mul_f32_e32 v176, 0.5, v176
	v_add_f32_e32 v179, 1.0, v179
	v_mul_f32_e32 v176, v176, v179
	v_mul_f32_e32 v176, v69, v176
	v_mul_f32_e32 v65, v163, v176
	ds_write_b32 v237, v64 offset:34816
	ds_write_b32 v237, v65 offset:35072
	v_pk_add_f32 v[92:93], v[92:93], v[94:95]
	v_pk_add_f32 v[86:87], v[86:87], v[88:89]
	v_mov_b32_e32 v94, 0x358637bd
	v_pk_add_f32 v[92:93], v[92:93], v[86:87]
	s_nop 0
	v_add_f32_e32 v92, v92, v93
	s_nop 0
	v_fmamk_f32 v92, v92, 0x3a800000, v94
	s_nop 0
	v_rsq_f32_e32 v92, v92
	s_nop 1
	v_mul_f32_e32 v164, v164, v92
	v_mul_f32_e32 v166, v166, v92
	v_mul_f32_e32 v176, v164, v80
	v_mul_f32_e32 v177, 0x3f3504f3, v176
	v_mov_b32_e32 v178, 0xb9c68948
	v_fma_f32 v178, |v177|, s80, v178
	v_fma_f32 v178, |v177|, v178, s81
	v_fma_f32 v178, |v177|, v178, s82
	v_fma_f32 v178, |v177|, v178, s83
	v_fma_f32 v178, |v177|, v178, s84
	v_fma_f32 v178, |v177|, v178, s85
	v_fma_f32 v178, |v177|, v178, |v177|
	v_mul_f32_e32 v179, 0xbfb8aa3b, v178
	v_fma_f32 v180, v178, s86, -v179
	v_rndne_f32_e32 v181, v179
	v_fmac_f32_e32 v180, 0xb2a5705f, v178
	v_sub_f32_e32 v179, v179, v181
	v_add_f32_e32 v179, v179, v180
	v_cvt_i32_f32_e32 v180, v181
	v_exp_f32_e32 v179, v179
	v_cmp_nlt_f32_e32 vcc, s87, v178
	v_ldexp_f32 v179, v179, v180
	s_nop 0
	v_cndmask_b32_e32 v179, 0, v179, vcc
	v_cmp_ngt_f32_e32 vcc, s88, v178
	v_mov_b32_e32 v180, 0x7f800000
	s_nop 0
	v_cndmask_b32_e32 v179, v180, v179, vcc
	v_sub_f32_e32 v179, 1.0, v179
	v_mul_f32_e32 v180, v177, v177
	v_mov_b32_e32 v181, 0x3ba10414
	v_fmamk_f32 v181, v180, 0xba1345e1, v181
	v_fmaak_f32 v181, v180, v181, 0xbcdac9b8
	v_fmaak_f32 v181, v180, v181, 0x3de703be
	v_fmaak_f32 v181, v180, v181, 0xbec09330
	v_fmaak_f32 v181, v180, v181, 0x3e0375d0
	v_fma_f32 v181, |v177|, v181, |v177|
	v_cmp_nlt_f32_e64 vcc, |v177|, 1.0
	s_nop 1
	v_cndmask_b32_e32 v179, v181, v179, vcc
	v_bfi_b32 v179, s89, v179, v177
	v_mul_f32_e32 v176, 0.5, v176
	v_add_f32_e32 v179, 1.0, v179
	v_mul_f32_e32 v176, v176, v179
	v_mul_f32_e32 v176, v84, v176
	v_mul_f32_e32 v80, v165, v176
	v_mul_f32_e32 v176, v166, v81
	v_mul_f32_e32 v177, 0x3f3504f3, v176
	v_mov_b32_e32 v178, 0xb9c68948
	v_fma_f32 v178, |v177|, s80, v178
	v_fma_f32 v178, |v177|, v178, s81
	v_fma_f32 v178, |v177|, v178, s82
	v_fma_f32 v178, |v177|, v178, s83
	v_fma_f32 v178, |v177|, v178, s84
	v_fma_f32 v178, |v177|, v178, s85
	v_fma_f32 v178, |v177|, v178, |v177|
	v_mul_f32_e32 v179, 0xbfb8aa3b, v178
	v_fma_f32 v180, v178, s86, -v179
	v_rndne_f32_e32 v181, v179
	v_fmac_f32_e32 v180, 0xb2a5705f, v178
	v_sub_f32_e32 v179, v179, v181
	v_add_f32_e32 v179, v179, v180
	v_cvt_i32_f32_e32 v180, v181
	v_exp_f32_e32 v179, v179
	v_cmp_nlt_f32_e32 vcc, s87, v178
	v_ldexp_f32 v179, v179, v180
	s_nop 0
	v_cndmask_b32_e32 v179, 0, v179, vcc
	v_cmp_ngt_f32_e32 vcc, s88, v178
	v_mov_b32_e32 v180, 0x7f800000
	s_nop 0
	v_cndmask_b32_e32 v179, v180, v179, vcc
	v_sub_f32_e32 v179, 1.0, v179
	v_mul_f32_e32 v180, v177, v177
	v_mov_b32_e32 v181, 0x3ba10414
	v_fmamk_f32 v181, v180, 0xba1345e1, v181
	v_fmaak_f32 v181, v180, v181, 0xbcdac9b8
; DI float gelu_exact(float x) { return 0.5f * x * (1.f + erff(x * 0.7071067811865476f)); }
; template <bool STORE>
; DI void peer_item(const Params& p, int item, char* smem) {
;     ...
;       const float amine = gelu_exact(h * su) * gmine * sv;
;       if ((lane & 7) == 0) {
;         EG[tok * 128 + k + (lane >> 3)] = emine;
;         AG[tok * 128 + k + (lane >> 3)] = amine;
;       }
	v_fmaak_f32 v181, v180, v181, 0x3de703be
	v_fmaak_f32 v181, v180, v181, 0xbec09330
	v_fmaak_f32 v181, v180, v181, 0x3e0375d0
	v_fma_f32 v181, |v177|, v181, |v177|
	v_cmp_nlt_f32_e64 vcc, |v177|, 1.0
	s_nop 1
	v_cndmask_b32_e32 v179, v181, v179, vcc
	v_bfi_b32 v179, s89, v179, v177
	v_mul_f32_e32 v176, 0.5, v176
	v_add_f32_e32 v179, 1.0, v179
	v_mul_f32_e32 v176, v176, v179
	v_mul_f32_e32 v176, v85, v176
	v_mul_f32_e32 v81, v167, v176
	ds_write_b32 v237, v80 offset:35328
	ds_write_b32 v237, v81 offset:35584
	v_pk_add_f32 v[108:109], v[108:109], v[110:111]
	v_pk_add_f32 v[102:103], v[102:103], v[104:105]
	v_mov_b32_e32 v110, 0x358637bd
	v_pk_add_f32 v[108:109], v[108:109], v[102:103]
	s_nop 0
	v_add_f32_e32 v108, v108, v109
	s_nop 0
	v_fmamk_f32 v108, v108, 0x3a800000, v110
	s_nop 0
	v_rsq_f32_e32 v108, v108
	s_nop 1
	v_mul_f32_e32 v168, v168, v108
	v_mul_f32_e32 v170, v170, v108
	v_mul_f32_e32 v176, v168, v96
	v_mul_f32_e32 v177, 0x3f3504f3, v176
	v_mov_b32_e32 v178, 0xb9c68948
	v_fma_f32 v178, |v177|, s80, v178
	v_fma_f32 v178, |v177|, v178, s81
	v_fma_f32 v178, |v177|, v178, s82
	v_fma_f32 v178, |v177|, v178, s83
	v_fma_f32 v178, |v177|, v178, s84
	v_fma_f32 v178, |v177|, v178, s85
	v_fma_f32 v178, |v177|, v178, |v177|
	v_mul_f32_e32 v179, 0xbfb8aa3b, v178
	v_fma_f32 v180, v178, s86, -v179
	v_rndne_f32_e32 v181, v179
	v_fmac_f32_e32 v180, 0xb2a5705f, v178
	v_sub_f32_e32 v179, v179, v181
	v_add_f32_e32 v179, v179, v180
	v_cvt_i32_f32_e32 v180, v181
	v_exp_f32_e32 v179, v179
	v_cmp_nlt_f32_e32 vcc, s87, v178
	v_ldexp_f32 v179, v179, v180
	s_nop 0
	v_cndmask_b32_e32 v179, 0, v179, vcc
	v_cmp_ngt_f32_e32 vcc, s88, v178
	v_mov_b32_e32 v180, 0x7f800000
	s_nop 0
	v_cndmask_b32_e32 v179, v180, v179, vcc
	v_sub_f32_e32 v179, 1.0, v179
	v_mul_f32_e32 v180, v177, v177
	v_mov_b32_e32 v181, 0x3ba10414
	v_fmamk_f32 v181, v180, 0xba1345e1, v181
	v_fmaak_f32 v181, v180, v181, 0xbcdac9b8
	v_fmaak_f32 v181, v180, v181, 0x3de703be
	v_fmaak_f32 v181, v180, v181, 0xbec09330
	v_fmaak_f32 v181, v180, v181, 0x3e0375d0
	v_fma_f32 v181, |v177|, v181, |v177|
	v_cmp_nlt_f32_e64 vcc, |v177|, 1.0
	s_nop 1
	v_cndmask_b32_e32 v179, v181, v179, vcc
	v_bfi_b32 v179, s89, v179, v177
	v_mul_f32_e32 v176, 0.5, v176
	v_add_f32_e32 v179, 1.0, v179
	v_mul_f32_e32 v176, v176, v179
	v_mul_f32_e32 v176, v100, v176
	v_mul_f32_e32 v96, v169, v176
	v_mul_f32_e32 v176, v170, v97
	v_mul_f32_e32 v177, 0x3f3504f3, v176
	v_mov_b32_e32 v178, 0xb9c68948
	v_fma_f32 v178, |v177|, s80, v178
	v_fma_f32 v178, |v177|, v178, s81
	v_fma_f32 v178, |v177|, v178, s82
	v_fma_f32 v178, |v177|, v178, s83
	v_fma_f32 v178, |v177|, v178, s84
	v_fma_f32 v178, |v177|, v178, s85
	v_fma_f32 v178, |v177|, v178, |v177|
	v_mul_f32_e32 v179, 0xbfb8aa3b, v178
	v_fma_f32 v180, v178, s86, -v179
	v_rndne_f32_e32 v181, v179
	v_fmac_f32_e32 v180, 0xb2a5705f, v178
	v_sub_f32_e32 v179, v179, v181
	v_add_f32_e32 v179, v179, v180
	v_cvt_i32_f32_e32 v180, v181
	v_exp_f32_e32 v179, v179
	v_cmp_nlt_f32_e32 vcc, s87, v178
	v_ldexp_f32 v179, v179, v180
	s_nop 0
	v_cndmask_b32_e32 v179, 0, v179, vcc
	v_cmp_ngt_f32_e32 vcc, s88, v178
	v_mov_b32_e32 v180, 0x7f800000
	s_nop 0
	v_cndmask_b32_e32 v179, v180, v179, vcc
	v_sub_f32_e32 v179, 1.0, v179
	v_mul_f32_e32 v180, v177, v177
	v_mov_b32_e32 v181, 0x3ba10414
	v_fmamk_f32 v181, v180, 0xba1345e1, v181
	v_fmaak_f32 v181, v180, v181, 0xbcdac9b8
	v_fmaak_f32 v181, v180, v181, 0x3de703be
	v_fmaak_f32 v181, v180, v181, 0xbec09330
	v_fmaak_f32 v181, v180, v181, 0x3e0375d0
	v_fma_f32 v181, |v177|, v181, |v177|
	v_cmp_nlt_f32_e64 vcc, |v177|, 1.0
	s_nop 1
	v_cndmask_b32_e32 v179, v181, v179, vcc
	v_bfi_b32 v179, s89, v179, v177
	v_mul_f32_e32 v176, 0.5, v176
	v_add_f32_e32 v179, 1.0, v179
	v_mul_f32_e32 v176, v176, v179
	v_mul_f32_e32 v176, v101, v176
	v_mul_f32_e32 v97, v171, v176
	ds_write_b32 v237, v96 offset:35840
	ds_write_b32 v237, v97 offset:36096
	v_pk_add_f32 v[124:125], v[124:125], v[126:127]
	v_pk_add_f32 v[118:119], v[118:119], v[120:121]
	v_mov_b32_e32 v126, 0x358637bd
	v_pk_add_f32 v[124:125], v[124:125], v[118:119]
	s_nop 0
	v_add_f32_e32 v124, v124, v125
	s_nop 0
	v_fmamk_f32 v124, v124, 0x3a800000, v126
	s_nop 0
	v_rsq_f32_e32 v124, v124
	s_nop 1
	v_mul_f32_e32 v172, v172, v124
	v_mul_f32_e32 v174, v174, v124
	v_mul_f32_e32 v176, v172, v112
	v_mul_f32_e32 v177, 0x3f3504f3, v176
	v_mov_b32_e32 v178, 0xb9c68948
	v_fma_f32 v178, |v177|, s80, v178
	v_fma_f32 v178, |v177|, v178, s81
	v_fma_f32 v178, |v177|, v178, s82
	v_fma_f32 v178, |v177|, v178, s83
	v_fma_f32 v178, |v177|, v178, s84
	v_fma_f32 v178, |v177|, v178, s85
	v_fma_f32 v178, |v177|, v178, |v177|
	v_mul_f32_e32 v179, 0xbfb8aa3b, v178
	v_fma_f32 v180, v178, s86, -v179
	v_rndne_f32_e32 v181, v179
	v_fmac_f32_e32 v180, 0xb2a5705f, v178
	v_sub_f32_e32 v179, v179, v181
	v_add_f32_e32 v179, v179, v180
	v_cvt_i32_f32_e32 v180, v181
	v_exp_f32_e32 v179, v179
	v_cmp_nlt_f32_e32 vcc, s87, v178
	v_ldexp_f32 v179, v179, v180
; DI float gelu_exact(float x) { return 0.5f * x * (1.f + erff(x * 0.7071067811865476f)); }
; template <bool STORE>
; DI void peer_item(const Params& p, int item, char* smem) {
;     ...
;       const float amine = gelu_exact(h * su) * gmine * sv;
;       if ((lane & 7) == 0) {
;         EG[tok * 128 + k + (lane >> 3)] = emine;
;         AG[tok * 128 + k + (lane >> 3)] = amine;
;       }
	s_nop 0
	v_cndmask_b32_e32 v179, 0, v179, vcc
	v_cmp_ngt_f32_e32 vcc, s88, v178
	v_mov_b32_e32 v180, 0x7f800000
	s_nop 0
	v_cndmask_b32_e32 v179, v180, v179, vcc
	v_sub_f32_e32 v179, 1.0, v179
	v_mul_f32_e32 v180, v177, v177
	v_mov_b32_e32 v181, 0x3ba10414
	v_fmamk_f32 v181, v180, 0xba1345e1, v181
	v_fmaak_f32 v181, v180, v181, 0xbcdac9b8
	v_fmaak_f32 v181, v180, v181, 0x3de703be
	v_fmaak_f32 v181, v180, v181, 0xbec09330
	v_fmaak_f32 v181, v180, v181, 0x3e0375d0
	v_fma_f32 v181, |v177|, v181, |v177|
	v_cmp_nlt_f32_e64 vcc, |v177|, 1.0
	s_nop 1
	v_cndmask_b32_e32 v179, v181, v179, vcc
	v_bfi_b32 v179, s89, v179, v177
	v_mul_f32_e32 v176, 0.5, v176
	v_add_f32_e32 v179, 1.0, v179
	v_mul_f32_e32 v176, v176, v179
	v_mul_f32_e32 v176, v116, v176
	v_mul_f32_e32 v112, v173, v176
	v_mul_f32_e32 v176, v174, v113
	v_mul_f32_e32 v177, 0x3f3504f3, v176
	v_mov_b32_e32 v178, 0xb9c68948
	v_fma_f32 v178, |v177|, s80, v178
	v_fma_f32 v178, |v177|, v178, s81
	v_fma_f32 v178, |v177|, v178, s82
	v_fma_f32 v178, |v177|, v178, s83
	v_fma_f32 v178, |v177|, v178, s84
	v_fma_f32 v178, |v177|, v178, s85
	v_fma_f32 v178, |v177|, v178, |v177|
	v_mul_f32_e32 v179, 0xbfb8aa3b, v178
	v_fma_f32 v180, v178, s86, -v179
	v_rndne_f32_e32 v181, v179
	v_fmac_f32_e32 v180, 0xb2a5705f, v178
	v_sub_f32_e32 v179, v179, v181
	v_add_f32_e32 v179, v179, v180
	v_cvt_i32_f32_e32 v180, v181
	v_exp_f32_e32 v179, v179
	v_cmp_nlt_f32_e32 vcc, s87, v178
	v_ldexp_f32 v179, v179, v180
	s_nop 0
	v_cndmask_b32_e32 v179, 0, v179, vcc
	v_cmp_ngt_f32_e32 vcc, s88, v178
	v_mov_b32_e32 v180, 0x7f800000
	s_nop 0
	v_cndmask_b32_e32 v179, v180, v179, vcc
	v_sub_f32_e32 v179, 1.0, v179
	v_mul_f32_e32 v180, v177, v177
	v_mov_b32_e32 v181, 0x3ba10414
	v_fmamk_f32 v181, v180, 0xba1345e1, v181
	v_fmaak_f32 v181, v180, v181, 0xbcdac9b8
	v_fmaak_f32 v181, v180, v181, 0x3de703be
	v_fmaak_f32 v181, v180, v181, 0xbec09330
	v_fmaak_f32 v181, v180, v181, 0x3e0375d0
	v_fma_f32 v181, |v177|, v181, |v177|
	v_cmp_nlt_f32_e64 vcc, |v177|, 1.0
	s_nop 1
	v_cndmask_b32_e32 v179, v181, v179, vcc
	v_bfi_b32 v179, s89, v179, v177
	v_mul_f32_e32 v176, 0.5, v176
	v_add_f32_e32 v179, 1.0, v179
	v_mul_f32_e32 v176, v176, v179
	v_mul_f32_e32 v176, v117, v176
	v_mul_f32_e32 v113, v175, v176
	ds_write_b32 v237, v112 offset:36352
	ds_write_b32 v237, v113 offset:36608
	ds_read_b32 v3, v236 offset:512
	ds_read_b32 v53, v236 offset:768
	ds_read_b32 v64, v236 offset:1024
	ds_read_b32 v65, v236 offset:1280
	ds_read_b32 v66, v236 offset:1536
	ds_read_b32 v67, v236 offset:1792
	ds_read_b32 v68, v236 offset:2048
	ds_read_b32 v69, v236 offset:2304
	ds_read_b32 v70, v236 offset:2560
	ds_read_b32 v71, v236 offset:2816
	ds_read_b32 v72, v236 offset:3072
	ds_read_b32 v73, v236 offset:3328
	ds_read_b32 v74, v236 offset:3584
	ds_read_b32 v75, v236 offset:3840
	ds_read_b32 v76, v236 offset:4096
	ds_read_b32 v77, v236 offset:4352
	ds_read_b32 v78, v236 offset:4608
	ds_read_b32 v79, v236 offset:4864
	ds_read_b32 v80, v236 offset:5120
	ds_read_b32 v81, v236 offset:5376
	ds_read_b32 v82, v236 offset:5632
	ds_read_b32 v83, v236 offset:5888
	ds_read_b32 v96, v236 offset:6144
	ds_read_b32 v210, v236 offset:6400
	ds_read_b32 v211, v236 offset:6656
	ds_read_b32 v212, v236 offset:6912
	v_readlane_b32 s6, v254, 0
	v_readlane_b32 s7, v254, 1
	v_readlane_b32 s12, v254, 2
	v_readlane_b32 s13, v254, 3
	v_readlane_b32 s14, v254, 4
	v_readlane_b32 s15, v254, 5
	v_readlane_b32 s16, v254, 6
	v_readlane_b32 s17, v254, 7
	v_readlane_b32 s18, v254, 8
	v_readlane_b32 s19, v254, 9
	v_readlane_b32 s20, v254, 10
	v_readlane_b32 s21, v254, 11
	v_readlane_b32 s22, v254, 12
	v_readlane_b32 s23, v254, 13
	v_readlane_b32 s24, v254, 14
	v_readlane_b32 s25, v254, 15
	v_readlane_b32 s26, v254, 16
	v_readlane_b32 s27, v254, 17
	v_readlane_b32 s28, v254, 18
	v_readlane_b32 s29, v254, 19
	v_readlane_b32 s30, v254, 20
	v_readlane_b32 s31, v254, 21
	v_readlane_b32 s33, v254, 22
	v_readlane_b32 s34, v254, 23
	v_readlane_b32 s35, v254, 24
	v_readlane_b32 s36, v254, 25
	v_readlane_b32 s37, v254, 26
	v_readlane_b32 s38, v254, 27
	v_readlane_b32 s39, v254, 28
	v_readlane_b32 s40, v254, 29
	v_readlane_b32 s41, v254, 30
	v_readlane_b32 s42, v254, 31
	v_readlane_b32 s44, v254, 32
	v_readlane_b32 s45, v254, 33
	v_readlane_b32 s48, v254, 34
	v_readlane_b32 s49, v254, 35
	v_readlane_b32 s50, v254, 36
	v_readlane_b32 s51, v254, 37
	v_readlane_b32 s52, v254, 38
	v_readlane_b32 s53, v254, 39
	v_readlane_b32 s55, v254, 40
	v_readlane_b32 s60, v254, 41
	v_readlane_b32 s61, v254, 42
	v_readlane_b32 s62, v254, 43
	v_readlane_b32 s63, v254, 44
	v_readlane_b32 s66, v254, 45
	v_readlane_b32 s67, v254, 46
	v_readlane_b32 s68, v254, 47
	v_readlane_b32 s69, v254, 48
	v_readlane_b32 s74, v254, 49
	v_readlane_b32 s75, v254, 50
	v_readlane_b32 s76, v254, 51
	v_readlane_b32 s77, v254, 52
	v_readlane_b32 s78, v254, 53
	v_readlane_b32 s79, v254, 54
	v_readlane_b32 s88, v254, 55
	s_waitcnt lgkmcnt(0)
	s_nop 3

; DI void peer_item_v(const Params& p, int item) {
;     ...
;   for (int ti = 0; ti < 8; ++ti) {
;     const size_t tok = (size_t)item * 32 + wave * 8 + ti;
;     const int e_lo = EG[tok * 128 + lane], e_hi = EG[tok * 128 + 64 + lane];
;     const int a_lo = __float_as_int(AG[tok * 128 + lane]), a_hi = __float_as_int(AG[tok * 128 + 64 + lane]);
;     float out[16];
; #pragma unroll
;     for (int i = 0; i < 16; ++i) out[i] = 0.f;
;     u32x4 vqa[8], vqb[8];
.Lvq_item:
	s_lshl_b32 s14, s10, 5
	s_add_u32 s14, s14, s56
	s_lshl_b32 s13, s14, 9
	s_add_u32 s58, s2, s13
	s_addc_u32 s59, s3, 0
	s_add_u32 s60, s4, s13
	s_addc_u32 s61, s5, 0
	v_lshrrev_b32_e32 v250, 3, v249
	v_and_b32_e32 v251, 7, v249
	v_lshlrev_b32_e32 v250, 6, v250
	v_lshl_add_u32 v250, v251, 2, v250
	s_lshr_b32 s13, s68, 8
	s_mul_i32 s13, s13, 0x13f00
	s_lshl_b32 s15, s56, 9
	s_add_u32 s13, s13, s15
	s_add_u32 s13, s13, 32
	v_add_u32_e32 v250, s13, v250
	ds_read_b32 v128, v250 offset:0
	ds_read_b32 v129, v250 offset:32
	ds_read_b32 v130, v250 offset:32768
	ds_read_b32 v131, v250 offset:32800
	ds_read_b32 v132, v250 offset:512
	ds_read_b32 v133, v250 offset:544
	ds_read_b32 v134, v250 offset:33280
	ds_read_b32 v135, v250 offset:33312
	ds_read_b32 v136, v250 offset:1024
	ds_read_b32 v137, v250 offset:1056
	ds_read_b32 v138, v250 offset:33792
	ds_read_b32 v139, v250 offset:33824
	ds_read_b32 v140, v250 offset:1536
	ds_read_b32 v141, v250 offset:1568
	ds_read_b32 v142, v250 offset:34304
	ds_read_b32 v143, v250 offset:34336
	ds_read_b32 v144, v250 offset:2048
	ds_read_b32 v145, v250 offset:2080
	ds_read_b32 v146, v250 offset:34816
	ds_read_b32 v147, v250 offset:34848
	ds_read_b32 v148, v250 offset:2560
	ds_read_b32 v149, v250 offset:2592
	ds_read_b32 v150, v250 offset:35328
	ds_read_b32 v151, v250 offset:35360
	ds_read_b32 v152, v250 offset:3072
	ds_read_b32 v153, v250 offset:3104
	ds_read_b32 v154, v250 offset:35840
	ds_read_b32 v155, v250 offset:35872
	ds_read_b32 v156, v250 offset:3584
	ds_read_b32 v157, v250 offset:3616
	ds_read_b32 v158, v250 offset:36352
	ds_read_b32 v159, v250 offset:36384
	v_add_u32_e32 v160, s57, v241
	v_mov_b32_e32 v161, 0
	v_mov_b32_e32 v162, 1
	v_lshrrev_b32_e32 v163, 3, v249
	v_and_b32_e32 v164, 7, v249
	v_lshlrev_b32_e32 v163, 6, v163
	v_lshl_add_u32 v163, v164, 2, v163
	v_add_u32_e32 v163, s57, v163
	v_add_u32_e32 v164, 32, v163
	v_subrev_u32_e32 v165, 1, v249
	v_subrev_u32_e32 v166, 2, v249
	v_subrev_u32_e32 v167, 4, v249
	v_subrev_u32_e32 v168, 8, v249
	v_subrev_u32_e32 v169, 16, v249
	v_subrev_u32_e32 v170, 32, v249
	v_lshlrev_b32_e32 v165, 2, v165
	v_lshlrev_b32_e32 v166, 2, v166
	v_lshlrev_b32_e32 v167, 2, v167
	v_lshlrev_b32_e32 v168, 2, v168
	v_lshlrev_b32_e32 v169, 2, v169
	v_lshlrev_b32_e32 v170, 2, v170
	v_mov_b32_e32 v0, 0
	v_mov_b32_e32 v1, 0
	v_mov_b32_e32 v2, 0
	v_mov_b32_e32 v3, 0
	v_mov_b32_e32 v4, 0
	v_mov_b32_e32 v5, 0
	v_mov_b32_e32 v6, 0
	v_mov_b32_e32 v7, 0
	v_mov_b32_e32 v8, 0
	v_mov_b32_e32 v9, 0
	v_mov_b32_e32 v10, 0
	v_mov_b32_e32 v11, 0
	v_mov_b32_e32 v12, 0
	v_mov_b32_e32 v13, 0
	v_mov_b32_e32 v14, 0
	v_mov_b32_e32 v15, 0
	v_mov_b32_e32 v16, 0
	v_mov_b32_e32 v17, 0
	v_mov_b32_e32 v18, 0
	v_mov_b32_e32 v19, 0
	v_mov_b32_e32 v20, 0
	v_mov_b32_e32 v21, 0
	v_mov_b32_e32 v22, 0
	v_mov_b32_e32 v23, 0
	v_mov_b32_e32 v24, 0
	v_mov_b32_e32 v25, 0
	v_mov_b32_e32 v26, 0
	v_mov_b32_e32 v27, 0
	v_mov_b32_e32 v28, 0
	v_mov_b32_e32 v29, 0
	v_mov_b32_e32 v30, 0
	v_mov_b32_e32 v31, 0
	v_mov_b32_e32 v32, 0
	v_mov_b32_e32 v33, 0
	v_mov_b32_e32 v34, 0
	v_mov_b32_e32 v35, 0
	v_mov_b32_e32 v36, 0
	v_mov_b32_e32 v37, 0
	v_mov_b32_e32 v38, 0
	v_mov_b32_e32 v39, 0
	v_mov_b32_e32 v40, 0
	v_mov_b32_e32 v41, 0
	v_mov_b32_e32 v42, 0
	v_mov_b32_e32 v43, 0
	v_mov_b32_e32 v44, 0
	v_mov_b32_e32 v45, 0
	v_mov_b32_e32 v46, 0
	v_mov_b32_e32 v47, 0
	v_mov_b32_e32 v48, 0
	v_mov_b32_e32 v49, 0
	v_mov_b32_e32 v50, 0
	v_mov_b32_e32 v51, 0
	v_mov_b32_e32 v52, 0
	v_mov_b32_e32 v53, 0
	v_mov_b32_e32 v54, 0
	v_mov_b32_e32 v55, 0
	v_mov_b32_e32 v56, 0
	v_mov_b32_e32 v57, 0
	v_mov_b32_e32 v58, 0
	v_mov_b32_e32 v59, 0
	v_mov_b32_e32 v60, 0
	v_mov_b32_e32 v61, 0
	v_mov_b32_e32 v62, 0
	v_mov_b32_e32 v63, 0
	s_waitcnt vmcnt(0) lgkmcnt(0)
	v_lshlrev_b32_e32 v128, 10, v128
	v_lshlrev_b32_e32 v129, 10, v129
	v_lshlrev_b32_e32 v132, 10, v132
	v_lshlrev_b32_e32 v133, 10, v133
	v_lshlrev_b32_e32 v136, 10, v136
	v_lshlrev_b32_e32 v137, 10, v137
	v_lshlrev_b32_e32 v140, 10, v140
	v_lshlrev_b32_e32 v141, 10, v141
	v_lshlrev_b32_e32 v144, 10, v144
	v_lshlrev_b32_e32 v145, 10, v145
	v_lshlrev_b32_e32 v148, 10, v148
	v_lshlrev_b32_e32 v149, 10, v149
	v_lshlrev_b32_e32 v152, 10, v152
	v_lshlrev_b32_e32 v153, 10, v153
	v_lshlrev_b32_e32 v156, 10, v156
	v_lshlrev_b32_e32 v157, 10, v157
	s_lshl_b32 s15, s14, 12
	s_add_u32 s62, s6, s15
	s_addc_u32 s63, s7, 0
	s_add_u32 s32, s62, 0
	s_addc_u32 s33, s63, 0
	s_add_u32 s34, s62, 4096
	s_addc_u32 s35, s63, 0
	s_add_u32 s36, s62, 8192
	s_addc_u32 s37, s63, 0
	s_add_u32 s38, s62, 12288
	s_addc_u32 s39, s63, 0
	global_load_dwordx4 v[64:67], v240, s[32:33]
	global_load_dwordx4 v[68:71], v240, s[32:33] offset:1024
	global_load_dwordx4 v[72:75], v240, s[32:33] offset:2048
	global_load_dwordx4 v[76:79], v240, s[32:33] offset:3072
	global_load_dwordx4 v[80:83], v240, s[34:35]
	global_load_dwordx4 v[84:87], v240, s[34:35] offset:1024
	global_load_dwordx4 v[88:91], v240, s[34:35] offset:2048
	global_load_dwordx4 v[92:95], v240, s[34:35] offset:3072
	global_load_dwordx4 v[96:99], v240, s[36:37]
	global_load_dwordx4 v[100:103], v240, s[36:37] offset:1024
	global_load_dwordx4 v[104:107], v240, s[36:37] offset:2048
	global_load_dwordx4 v[108:111], v240, s[36:37] offset:3072
	global_load_dwordx4 v[112:115], v240, s[38:39]
	global_load_dwordx4 v[116:119], v240, s[38:39] offset:1024
	global_load_dwordx4 v[120:123], v240, s[38:39] offset:2048
	global_load_dwordx4 v[124:127], v240, s[38:39] offset:3072
	s_mov_b32 s72, 0
	s_mov_b32 s73, 1
	s_mov_b32 s74, 2
	s_mov_b32 s75, 3
	s_mov_b32 s76, 4
	s_mov_b32 s77, 5
	s_mov_b32 s78, 6
	s_mov_b32 s79, 7
	s_nop 0
	v_readlane_b32 s48, v128, s72
	v_readlane_b32 s49, v128, s73
	v_readlane_b32 s50, v128, s74
	v_readlane_b32 s51, v128, s75
	v_readlane_b32 s52, v128, s76
	v_readlane_b32 s53, v128, s77
	v_readlane_b32 s54, v128, s78
	v_readlane_b32 s55, v128, s79
	s_add_u32 s32, s0, s48
	s_addc_u32 s33, s1, 0
	s_add_u32 s34, s0, s49
	s_addc_u32 s35, s1, 0
	s_add_u32 s36, s0, s50
	s_addc_u32 s37, s1, 0
	s_add_u32 s38, s0, s51
	s_addc_u32 s39, s1, 0
	s_add_u32 s40, s0, s52
	s_addc_u32 s41, s1, 0
	s_add_u32 s42, s0, s53
	s_addc_u32 s43, s1, 0
	s_add_u32 s44, s0, s54
	s_addc_u32 s45, s1, 0
	s_add_u32 s46, s0, s55
	s_addc_u32 s47, s1, 0
	global_load_dwordx4 v[160:163], v240, s[32:33]
	global_load_dwordx4 v[164:167], v240, s[34:35]
	global_load_dwordx4 v[168:171], v240, s[36:37]
	global_load_dwordx4 v[172:175], v240, s[38:39]
	global_load_dwordx4 v[176:179], v240, s[40:41]
	global_load_dwordx4 v[180:183], v240, s[42:43]
	global_load_dwordx4 v[184:187], v240, s[44:45]
	global_load_dwordx4 v[188:191], v240, s[46:47]
	s_mov_b32 s12, 0
